# GEMM K-loops: merged the three back-to-back waitcnts before each phase barrier into one; m0 write moved ahead of the address add so the s_nop before each LDS-DMA goes
# speedup vs baseline: 1.0095x; 1.0095x over previous
; #define PG8_STAGE(bufoff, gbase, voff) do { _Pragma("unroll") for (int _i = 0; _i < 2; ++_i) \
;         __builtin_amdgcn_global_load_lds((const unsigned*)((const char*)(gbase) + (voff)[_i]), (PG8_LAS unsigned*)(lds + (bufoff) + ldsw + _i * 8192), 16, 0, 0); } while (0)
; #define PG8_LDA(dst, b, h) do { _Pragma("unroll") for (int m = 0; m < 4; ++m) _Pragma("unroll") for (int k = 0; k < 2; ++k) dst[m][k] = *(const PG8_LAS bf16x8*)(lds + PG8_SA(b, h) + aoff + m * 2048 + k * 1024); } while (0)
; #define PG8_LDB(dst, b, h) do { _Pragma("unroll") for (int n = 0; n < 2; ++n) _Pragma("unroll") for (int k = 0; k < 2; ++k) dst[n][k] = *(const PG8_LAS bf16x8*)(lds + PG8_SB(b, h) + boff + n * 2048 + k * 1024); } while (0)
; #define PG8_MMA(ai, bj, At, Bt) do { __builtin_amdgcn_s_setprio(1); _Pragma("unroll") for (int m = 0; m < 4; ++m) _Pragma("unroll") for (int n = 0; n < 2; ++n) _Pragma("unroll") for (int k = 0; k < 2; ++k) \
;         acc[ai][bj][m][n] = __builtin_amdgcn_mfma_f32_16x16x32_bf16(Bt[n][k], At[m][k], acc[ai][bj][m][n], 0, 0, 0); __builtin_amdgcn_s_setprio(0); } while (0)
; #define PG8_WAIT_V(n) asm volatile("s_waitcnt vmcnt(" #n ")" ::: "memory")
; #define PG8_WAIT_L(n) do { asm volatile("s_waitcnt lgkmcnt(" #n ")" ::: "memory"); __builtin_amdgcn_s_waitcnt(0xC07F); } while (0)
; #define PG8_BAR __builtin_amdgcn_s_barrier()
; #define PG8_SCHED __builtin_amdgcn_sched_barrier(0)
; template <class Epi, class Sched, bool SEG3 = false>
; __device__ __forceinline__ void gemm_phase(PG8_LAS unsigned char* lds, const Gemm g, const Sched& S, const Epi& E) {
;     ...
;             const char* a1 = cA + (size_t)(t + 1) * kstep;
;             const char* a2 = last ? nA : cA + (size_t)(t + 2) * kstep; const char* b2 = last ? nB : cB + (size_t)(t + 2) * kstep;
;             const char* a3 = a2 + kstep; const char* b3 = b2 + kstep;
;             PG8_LDB(B0, 0, 0); PG8_LDB(B1, 0, 1); PG8_SCHED; PG8_LDA(At, 0, 0); PG8_STAGE(PG8_SA(1, 1), a1 + hsA, voffA);
;             PG8_WAIT_V(8); PG8_WAIT_L(0); PG8_BAR; if (cur.half != 1) { PG8_MMA(0, 0, At, B0); PG8_MMA(0, 1, At, B1); } PG8_BAR; PG8_SCHED;
;             PG8_LDA(At, 0, 1); PG8_STAGE(PG8_SB(0, 0), b2, voffB); PG8_STAGE(PG8_SB(0, 1), b2 + hsB, voffB); PG8_STAGE(PG8_SA(0, 0), a2, voffA);
;             PG8_WAIT_V(8); PG8_WAIT_L(0); PG8_BAR; if (cur.half != 0) { PG8_MMA(1, 0, At, B0); PG8_MMA(1, 1, At, B1); } PG8_BAR; PG8_SCHED;
.LBB0_225:
	v_add_u32_e32 v142, s54, v146
	ds_read_b128 v[152:155], v142
	ds_read_b128 v[156:159], v142 offset:1024
	ds_read_b128 v[160:163], v142 offset:2048
	ds_read_b128 v[164:167], v142 offset:3072
	v_add_u32_e32 v142, s55, v146
	ds_read_b128 v[168:171], v142
	ds_read_b128 v[172:175], v142 offset:1024
	ds_read_b128 v[176:179], v142 offset:2048
	ds_read_b128 v[180:183], v142 offset:3072
	s_add_i32 s95, s40, 2
	s_add_u32 s0, s38, 0xfffc0080
	s_addc_u32 s1, s39, -1
	s_cmp_eq_u32 s89, s40
	s_cselect_b32 s40, s92, s93
	s_cselect_b32 s43, s17, s1
	s_cselect_b32 s42, s29, s0
	s_cselect_b32 s41, s31, s94
	v_lshl_add_u64 v[142:143], s[38:39], 0, v[138:139]
	s_add_i32 m0, s78, 0xc000
	ds_read_b128 v[184:187], v151
	ds_read_b128 v[188:191], v151 offset:1024
	ds_read_b128 v[192:195], v151 offset:2048
	ds_read_b128 v[196:199], v151 offset:3072
	ds_read_b128 v[200:203], v151 offset:4096
	ds_read_b128 v[204:207], v151 offset:5120
	ds_read_b128 v[208:211], v151 offset:6144
	ds_read_b128 v[212:215], v151 offset:7168
	global_load_lds_dwordx4 v[142:143], off
	s_add_i32 m0, s78, 0xe000
	v_lshl_add_u64 v[142:143], s[38:39], 0, v[140:141]
	global_load_lds_dwordx4 v[142:143], off
	s_waitcnt vmcnt(8) lgkmcnt(0)
	s_barrier
	s_setprio 1
	v_mfma_f32_16x16x32_bf16 v[126:129], v[152:155], v[184:187], v[126:129]
	v_mfma_f32_16x16x32_bf16 v[122:125], v[160:163], v[184:187], v[122:125]
	v_mfma_f32_16x16x32_bf16 v[110:113], v[152:155], v[192:195], v[110:113]
	v_mfma_f32_16x16x32_bf16 v[106:109], v[160:163], v[192:195], v[106:109]
	v_mfma_f32_16x16x32_bf16 v[94:97], v[152:155], v[200:203], v[94:97]
	v_mfma_f32_16x16x32_bf16 v[90:93], v[160:163], v[200:203], v[90:93]
	v_mfma_f32_16x16x32_bf16 v[78:81], v[152:155], v[208:211], v[78:81]
	v_mfma_f32_16x16x32_bf16 v[74:77], v[160:163], v[208:211], v[74:77]
	v_mfma_f32_16x16x32_bf16 v[126:129], v[156:159], v[188:191], v[126:129]
	v_mfma_f32_16x16x32_bf16 v[122:125], v[164:167], v[188:191], v[122:125]
	v_mfma_f32_16x16x32_bf16 v[110:113], v[156:159], v[196:199], v[110:113]
	v_mfma_f32_16x16x32_bf16 v[106:109], v[164:167], v[196:199], v[106:109]
	v_mfma_f32_16x16x32_bf16 v[94:97], v[156:159], v[204:207], v[94:97]
	v_mfma_f32_16x16x32_bf16 v[90:93], v[164:167], v[204:207], v[90:93]
	v_mfma_f32_16x16x32_bf16 v[78:81], v[156:159], v[212:215], v[78:81]
	v_mfma_f32_16x16x32_bf16 v[74:77], v[164:167], v[212:215], v[74:77]
	s_setprio 0
	s_setprio 1
	v_mfma_f32_16x16x32_bf16 v[118:121], v[168:171], v[184:187], v[118:121]
	v_mfma_f32_16x16x32_bf16 v[114:117], v[176:179], v[184:187], v[114:117]
	v_mfma_f32_16x16x32_bf16 v[102:105], v[168:171], v[192:195], v[102:105]
	v_mfma_f32_16x16x32_bf16 v[98:101], v[176:179], v[192:195], v[98:101]
	v_mfma_f32_16x16x32_bf16 v[86:89], v[168:171], v[200:203], v[86:89]
	v_mfma_f32_16x16x32_bf16 v[82:85], v[176:179], v[200:203], v[82:85]
	v_mfma_f32_16x16x32_bf16 v[70:73], v[168:171], v[208:211], v[70:73]
	v_mfma_f32_16x16x32_bf16 v[66:69], v[176:179], v[208:211], v[66:69]
	v_mfma_f32_16x16x32_bf16 v[118:121], v[172:175], v[188:191], v[118:121]
	v_mfma_f32_16x16x32_bf16 v[114:117], v[180:183], v[188:191], v[114:117]
	v_mfma_f32_16x16x32_bf16 v[102:105], v[172:175], v[196:199], v[102:105]
	v_mfma_f32_16x16x32_bf16 v[98:101], v[180:183], v[196:199], v[98:101]
	v_mfma_f32_16x16x32_bf16 v[86:89], v[172:175], v[204:207], v[86:89]
	v_mfma_f32_16x16x32_bf16 v[82:85], v[180:183], v[204:207], v[82:85]
	v_mfma_f32_16x16x32_bf16 v[70:73], v[172:175], v[212:215], v[70:73]
	v_mfma_f32_16x16x32_bf16 v[66:69], v[180:183], v[212:215], v[66:69]
	s_setprio 0
	s_barrier
	s_mov_b32 m0, s19
	v_lshl_add_u64 v[142:143], s[40:41], 0, v[130:131]
	s_add_u32 s96, s40, 0x40000
	ds_read_b128 v[184:187], v151 offset:16384
	ds_read_b128 v[188:191], v151 offset:17408
	ds_read_b128 v[192:195], v151 offset:18432
	ds_read_b128 v[196:199], v151 offset:19456
	ds_read_b128 v[200:203], v151 offset:20480
	ds_read_b128 v[204:207], v151 offset:21504
	ds_read_b128 v[208:211], v151 offset:22528
	ds_read_b128 v[212:215], v151 offset:23552
	global_load_lds_dwordx4 v[142:143], off
	v_lshl_add_u64 v[216:217], s[40:41], 0, v[136:137]
	s_mov_b32 m0, s75
	s_addc_u32 s97, s41, 0
	global_load_lds_dwordx4 v[216:217], off
	v_lshl_add_u64 v[218:219], s[96:97], 0, v[130:131]
	s_mov_b32 m0, s76
	v_lshl_add_u64 v[220:221], s[42:43], 0, v[134:135]
	global_load_lds_dwordx4 v[218:219], off
	s_mov_b32 m0, s77
	v_lshl_add_u64 v[218:219], s[96:97], 0, v[136:137]
	global_load_lds_dwordx4 v[218:219], off
	s_mov_b32 m0, s78
	v_lshl_add_u64 v[218:219], s[42:43], 0, v[132:133]
	global_load_lds_dwordx4 v[218:219], off
	s_mov_b32 m0, s79
	s_nop 0
	global_load_lds_dwordx4 v[220:221], off
	s_waitcnt vmcnt(8) lgkmcnt(0)
	s_barrier
; #define PG8_STAGE(bufoff, gbase, voff) do { _Pragma("unroll") for (int _i = 0; _i < 2; ++_i) \
;         __builtin_amdgcn_global_load_lds((const unsigned*)((const char*)(gbase) + (voff)[_i]), (PG8_LAS unsigned*)(lds + (bufoff) + ldsw + _i * 8192), 16, 0, 0); } while (0)
; #define PG8_LDA(dst, b, h) do { _Pragma("unroll") for (int m = 0; m < 4; ++m) _Pragma("unroll") for (int k = 0; k < 2; ++k) dst[m][k] = *(const PG8_LAS bf16x8*)(lds + PG8_SA(b, h) + aoff + m * 2048 + k * 1024); } while (0)
; #define PG8_LDB(dst, b, h) do { _Pragma("unroll") for (int n = 0; n < 2; ++n) _Pragma("unroll") for (int k = 0; k < 2; ++k) dst[n][k] = *(const PG8_LAS bf16x8*)(lds + PG8_SB(b, h) + boff + n * 2048 + k * 1024); } while (0)
; #define PG8_MMA(ai, bj, At, Bt) do { __builtin_amdgcn_s_setprio(1); _Pragma("unroll") for (int m = 0; m < 4; ++m) _Pragma("unroll") for (int n = 0; n < 2; ++n) _Pragma("unroll") for (int k = 0; k < 2; ++k) \
;         acc[ai][bj][m][n] = __builtin_amdgcn_mfma_f32_16x16x32_bf16(Bt[n][k], At[m][k], acc[ai][bj][m][n], 0, 0, 0); __builtin_amdgcn_s_setprio(0); } while (0)
; #define PG8_WAIT_V(n) asm volatile("s_waitcnt vmcnt(" #n ")" ::: "memory")
; #define PG8_WAIT_L(n) do { asm volatile("s_waitcnt lgkmcnt(" #n ")" ::: "memory"); __builtin_amdgcn_s_waitcnt(0xC07F); } while (0)
; #define PG8_BAR __builtin_amdgcn_s_barrier()
; #define PG8_SCHED __builtin_amdgcn_sched_barrier(0)
; template <class Epi, class Sched, bool SEG3 = false>
; __device__ __forceinline__ void gemm_phase(PG8_LAS unsigned char* lds, const Gemm g, const Sched& S, const Epi& E) {
;     ...
;             PG8_WAIT_V(8); PG8_WAIT_L(0); PG8_BAR; if (cur.half != 0) { PG8_MMA(1, 0, At, B0); PG8_MMA(1, 1, At, B1); } PG8_BAR; PG8_SCHED;
;             PG8_LDB(B0, 1, 0); PG8_LDB(B1, 1, 1); PG8_SCHED; PG8_LDA(At, 1, 0); PG8_STAGE(PG8_SA(0, 1), a2 + hsA, voffA);
;             PG8_WAIT_V(8); PG8_WAIT_L(0); PG8_BAR; if (cur.half != 1) { PG8_MMA(0, 0, At, B0); PG8_MMA(0, 1, At, B1); } PG8_BAR; PG8_SCHED;
	s_setprio 1
	v_mfma_f32_16x16x32_bf16 v[62:65], v[152:155], v[184:187], v[62:65]
	v_mfma_f32_16x16x32_bf16 v[58:61], v[160:163], v[184:187], v[58:61]
	v_mfma_f32_16x16x32_bf16 v[46:49], v[152:155], v[192:195], v[46:49]
	v_mfma_f32_16x16x32_bf16 v[42:45], v[160:163], v[192:195], v[42:45]
	v_mfma_f32_16x16x32_bf16 v[30:33], v[152:155], v[200:203], v[30:33]
	v_mfma_f32_16x16x32_bf16 v[26:29], v[160:163], v[200:203], v[26:29]
	v_mfma_f32_16x16x32_bf16 v[14:17], v[152:155], v[208:211], v[14:17]
	v_mfma_f32_16x16x32_bf16 v[10:13], v[160:163], v[208:211], v[10:13]
	v_mfma_f32_16x16x32_bf16 v[62:65], v[156:159], v[188:191], v[62:65]
	v_mfma_f32_16x16x32_bf16 v[58:61], v[164:167], v[188:191], v[58:61]
	v_mfma_f32_16x16x32_bf16 v[46:49], v[156:159], v[196:199], v[46:49]
	v_mfma_f32_16x16x32_bf16 v[42:45], v[164:167], v[196:199], v[42:45]
	v_mfma_f32_16x16x32_bf16 v[30:33], v[156:159], v[204:207], v[30:33]
	v_mfma_f32_16x16x32_bf16 v[26:29], v[164:167], v[204:207], v[26:29]
	v_mfma_f32_16x16x32_bf16 v[14:17], v[156:159], v[212:215], v[14:17]
	v_mfma_f32_16x16x32_bf16 v[10:13], v[164:167], v[212:215], v[10:13]
	s_setprio 0
	s_setprio 1
	v_mfma_f32_16x16x32_bf16 v[54:57], v[168:171], v[184:187], v[54:57]
	v_mfma_f32_16x16x32_bf16 v[50:53], v[176:179], v[184:187], v[50:53]
	v_mfma_f32_16x16x32_bf16 v[38:41], v[168:171], v[192:195], v[38:41]
	v_mfma_f32_16x16x32_bf16 v[34:37], v[176:179], v[192:195], v[34:37]
	v_mfma_f32_16x16x32_bf16 v[22:25], v[168:171], v[200:203], v[22:25]
	v_mfma_f32_16x16x32_bf16 v[18:21], v[176:179], v[200:203], v[18:21]
	v_mfma_f32_16x16x32_bf16 v[6:9], v[168:171], v[208:211], v[6:9]
	v_mfma_f32_16x16x32_bf16 v[2:5], v[176:179], v[208:211], v[2:5]
	v_mfma_f32_16x16x32_bf16 v[54:57], v[172:175], v[188:191], v[54:57]
	v_mfma_f32_16x16x32_bf16 v[50:53], v[180:183], v[188:191], v[50:53]
	v_mfma_f32_16x16x32_bf16 v[38:41], v[172:175], v[196:199], v[38:41]
	v_mfma_f32_16x16x32_bf16 v[34:37], v[180:183], v[196:199], v[34:37]
	v_mfma_f32_16x16x32_bf16 v[22:25], v[172:175], v[204:207], v[22:25]
	v_mfma_f32_16x16x32_bf16 v[18:21], v[180:183], v[204:207], v[18:21]
	v_mfma_f32_16x16x32_bf16 v[6:9], v[172:175], v[212:215], v[6:9]
	v_mfma_f32_16x16x32_bf16 v[2:5], v[180:183], v[212:215], v[2:5]
	s_setprio 0
	s_barrier
	v_add_u32_e32 v164, s56, v146
	v_add_u32_e32 v180, s57, v146
	ds_read_b128 v[152:155], v164
	ds_read_b128 v[156:159], v164 offset:1024
	ds_read_b128 v[160:163], v164 offset:2048
	ds_read_b128 v[164:167], v164 offset:3072
	ds_read_b128 v[168:171], v180
	ds_read_b128 v[172:175], v180 offset:1024
	ds_read_b128 v[176:179], v180 offset:2048
	ds_read_b128 v[180:183], v180 offset:3072
	s_add_u32 s42, s42, 0x40000
	s_addc_u32 s43, s43, 0
	s_mov_b32 m0, s80
	v_lshl_add_u64 v[222:223], s[42:43], 0, v[132:133]
	ds_read_b128 v[184:187], v151 offset:32768
	ds_read_b128 v[188:191], v151 offset:33792
	ds_read_b128 v[192:195], v151 offset:34816
	ds_read_b128 v[196:199], v151 offset:35840
	ds_read_b128 v[200:203], v151 offset:36864
	ds_read_b128 v[204:207], v151 offset:37888
	ds_read_b128 v[208:211], v151 offset:38912
	ds_read_b128 v[212:215], v151 offset:39936
	global_load_lds_dwordx4 v[222:223], off
	s_mov_b32 m0, s81
	v_lshl_add_u64 v[222:223], s[42:43], 0, v[134:135]
	global_load_lds_dwordx4 v[222:223], off
	s_waitcnt vmcnt(8) lgkmcnt(0)
	s_barrier
	s_setprio 1
	v_mfma_f32_16x16x32_bf16 v[126:129], v[152:155], v[184:187], v[126:129]
	v_mfma_f32_16x16x32_bf16 v[122:125], v[160:163], v[184:187], v[122:125]
	v_mfma_f32_16x16x32_bf16 v[110:113], v[152:155], v[192:195], v[110:113]
	v_mfma_f32_16x16x32_bf16 v[106:109], v[160:163], v[192:195], v[106:109]
	v_mfma_f32_16x16x32_bf16 v[94:97], v[152:155], v[200:203], v[94:97]
	v_mfma_f32_16x16x32_bf16 v[90:93], v[160:163], v[200:203], v[90:93]
	v_mfma_f32_16x16x32_bf16 v[78:81], v[152:155], v[208:211], v[78:81]
	v_mfma_f32_16x16x32_bf16 v[74:77], v[160:163], v[208:211], v[74:77]
	v_mfma_f32_16x16x32_bf16 v[126:129], v[156:159], v[188:191], v[126:129]
	v_mfma_f32_16x16x32_bf16 v[122:125], v[164:167], v[188:191], v[122:125]
	v_mfma_f32_16x16x32_bf16 v[110:113], v[156:159], v[196:199], v[110:113]
	v_mfma_f32_16x16x32_bf16 v[106:109], v[164:167], v[196:199], v[106:109]
	v_mfma_f32_16x16x32_bf16 v[94:97], v[156:159], v[204:207], v[94:97]
	v_mfma_f32_16x16x32_bf16 v[90:93], v[164:167], v[204:207], v[90:93]
	v_mfma_f32_16x16x32_bf16 v[78:81], v[156:159], v[212:215], v[78:81]
	v_mfma_f32_16x16x32_bf16 v[74:77], v[164:167], v[212:215], v[74:77]
	s_setprio 0
	s_setprio 1
	v_mfma_f32_16x16x32_bf16 v[118:121], v[168:171], v[184:187], v[118:121]
	v_mfma_f32_16x16x32_bf16 v[114:117], v[176:179], v[184:187], v[114:117]
	v_mfma_f32_16x16x32_bf16 v[102:105], v[168:171], v[192:195], v[102:105]
	v_mfma_f32_16x16x32_bf16 v[98:101], v[176:179], v[192:195], v[98:101]
	v_mfma_f32_16x16x32_bf16 v[86:89], v[168:171], v[200:203], v[86:89]
	v_mfma_f32_16x16x32_bf16 v[82:85], v[176:179], v[200:203], v[82:85]
	v_mfma_f32_16x16x32_bf16 v[70:73], v[168:171], v[208:211], v[70:73]
	v_mfma_f32_16x16x32_bf16 v[66:69], v[176:179], v[208:211], v[66:69]
	v_mfma_f32_16x16x32_bf16 v[118:121], v[172:175], v[188:191], v[118:121]
	v_mfma_f32_16x16x32_bf16 v[114:117], v[180:183], v[188:191], v[114:117]
	v_mfma_f32_16x16x32_bf16 v[102:105], v[172:175], v[196:199], v[102:105]
	v_mfma_f32_16x16x32_bf16 v[98:101], v[180:183], v[196:199], v[98:101]
	v_mfma_f32_16x16x32_bf16 v[86:89], v[172:175], v[204:207], v[86:89]
	v_mfma_f32_16x16x32_bf16 v[82:85], v[180:183], v[204:207], v[82:85]
	v_mfma_f32_16x16x32_bf16 v[70:73], v[172:175], v[212:215], v[70:73]
	v_mfma_f32_16x16x32_bf16 v[66:69], v[180:183], v[212:215], v[66:69]
	s_setprio 0
	s_barrier
; #define PG8_STAGE(bufoff, gbase, voff) do { _Pragma("unroll") for (int _i = 0; _i < 2; ++_i) \
;         __builtin_amdgcn_global_load_lds((const unsigned*)((const char*)(gbase) + (voff)[_i]), (PG8_LAS unsigned*)(lds + (bufoff) + ldsw + _i * 8192), 16, 0, 0); } while (0)
; #define PG8_LDA(dst, b, h) do { _Pragma("unroll") for (int m = 0; m < 4; ++m) _Pragma("unroll") for (int k = 0; k < 2; ++k) dst[m][k] = *(const PG8_LAS bf16x8*)(lds + PG8_SA(b, h) + aoff + m * 2048 + k * 1024); } while (0)
; #define PG8_MMA(ai, bj, At, Bt) do { __builtin_amdgcn_s_setprio(1); _Pragma("unroll") for (int m = 0; m < 4; ++m) _Pragma("unroll") for (int n = 0; n < 2; ++n) _Pragma("unroll") for (int k = 0; k < 2; ++k) \
;         acc[ai][bj][m][n] = __builtin_amdgcn_mfma_f32_16x16x32_bf16(Bt[n][k], At[m][k], acc[ai][bj][m][n], 0, 0, 0); __builtin_amdgcn_s_setprio(0); } while (0)
; #define PG8_WAIT_V(n) asm volatile("s_waitcnt vmcnt(" #n ")" ::: "memory")
; #define PG8_WAIT_L(n) do { asm volatile("s_waitcnt lgkmcnt(" #n ")" ::: "memory"); __builtin_amdgcn_s_waitcnt(0xC07F); } while (0)
; #define PG8_BAR __builtin_amdgcn_s_barrier()
; #define PG8_SCHED __builtin_amdgcn_sched_barrier(0)
; template <class Epi, class Sched, bool SEG3 = false>
; __device__ __forceinline__ void gemm_phase(PG8_LAS unsigned char* lds, const Gemm g, const Sched& S, const Epi& E) {
;     ...
;             PG8_LDA(At, 1, 1); PG8_STAGE(PG8_SB(1, 0), b3, voffB); PG8_STAGE(PG8_SB(1, 1), b3 + hsB, voffB); PG8_STAGE(PG8_SA(1, 0), a3, voffA);
;             PG8_WAIT_V(8); PG8_WAIT_L(0); PG8_BAR; if (cur.half != 0) { PG8_MMA(1, 0, At, B0); PG8_MMA(1, 1, At, B1); } PG8_BAR; PG8_SCHED;
;         }
	s_mov_b32 m0, s83
	v_lshl_add_u64 v[142:143], v[142:143], 0, s[6:7]
	s_add_u32 s40, s40, 0x40080
	ds_read_b128 v[184:187], v151 offset:49152
	ds_read_b128 v[188:191], v151 offset:50176
	ds_read_b128 v[192:195], v151 offset:51200
	ds_read_b128 v[196:199], v151 offset:52224
	ds_read_b128 v[200:203], v151 offset:53248
	ds_read_b128 v[204:207], v151 offset:54272
	ds_read_b128 v[208:211], v151 offset:55296
	ds_read_b128 v[212:215], v151 offset:56320
	global_load_lds_dwordx4 v[142:143], off
	v_lshl_add_u64 v[142:143], v[216:217], 0, s[6:7]
	s_mov_b32 m0, s84
	s_addc_u32 s41, s41, 0
	global_load_lds_dwordx4 v[142:143], off
	s_mov_b32 m0, s87
	v_lshl_add_u64 v[142:143], s[40:41], 0, v[130:131]
	global_load_lds_dwordx4 v[142:143], off
	s_mov_b32 m0, s88
	v_lshl_add_u64 v[142:143], s[40:41], 0, v[136:137]
	global_load_lds_dwordx4 v[142:143], off
	s_mov_b32 m0, s85
	v_lshl_add_u64 v[142:143], v[218:219], 0, s[6:7]
	global_load_lds_dwordx4 v[142:143], off
	s_mov_b32 m0, s86
	v_lshl_add_u64 v[142:143], v[220:221], 0, s[6:7]
	global_load_lds_dwordx4 v[142:143], off
	s_waitcnt vmcnt(8) lgkmcnt(0)
	s_barrier
	s_setprio 1
	v_mfma_f32_16x16x32_bf16 v[62:65], v[152:155], v[184:187], v[62:65]
	v_mfma_f32_16x16x32_bf16 v[58:61], v[160:163], v[184:187], v[58:61]
	v_mfma_f32_16x16x32_bf16 v[46:49], v[152:155], v[192:195], v[46:49]
	v_mfma_f32_16x16x32_bf16 v[42:45], v[160:163], v[192:195], v[42:45]
	v_mfma_f32_16x16x32_bf16 v[30:33], v[152:155], v[200:203], v[30:33]
	v_mfma_f32_16x16x32_bf16 v[26:29], v[160:163], v[200:203], v[26:29]
	v_mfma_f32_16x16x32_bf16 v[14:17], v[152:155], v[208:211], v[14:17]
	v_mfma_f32_16x16x32_bf16 v[10:13], v[160:163], v[208:211], v[10:13]
	v_mfma_f32_16x16x32_bf16 v[62:65], v[156:159], v[188:191], v[62:65]
	v_mfma_f32_16x16x32_bf16 v[58:61], v[164:167], v[188:191], v[58:61]
	v_mfma_f32_16x16x32_bf16 v[46:49], v[156:159], v[196:199], v[46:49]
	v_mfma_f32_16x16x32_bf16 v[42:45], v[164:167], v[196:199], v[42:45]
	v_mfma_f32_16x16x32_bf16 v[30:33], v[156:159], v[204:207], v[30:33]
	v_mfma_f32_16x16x32_bf16 v[26:29], v[164:167], v[204:207], v[26:29]
	v_mfma_f32_16x16x32_bf16 v[14:17], v[156:159], v[212:215], v[14:17]
	v_mfma_f32_16x16x32_bf16 v[10:13], v[164:167], v[212:215], v[10:13]
	s_setprio 0
	s_setprio 1
	v_mfma_f32_16x16x32_bf16 v[54:57], v[168:171], v[184:187], v[54:57]
	v_mfma_f32_16x16x32_bf16 v[50:53], v[176:179], v[184:187], v[50:53]
	v_mfma_f32_16x16x32_bf16 v[38:41], v[168:171], v[192:195], v[38:41]
	v_mfma_f32_16x16x32_bf16 v[34:37], v[176:179], v[192:195], v[34:37]
	v_mfma_f32_16x16x32_bf16 v[22:25], v[168:171], v[200:203], v[22:25]
	v_mfma_f32_16x16x32_bf16 v[18:21], v[176:179], v[200:203], v[18:21]
	v_mfma_f32_16x16x32_bf16 v[6:9], v[168:171], v[208:211], v[6:9]
	v_mfma_f32_16x16x32_bf16 v[2:5], v[176:179], v[208:211], v[2:5]
	v_mfma_f32_16x16x32_bf16 v[54:57], v[172:175], v[188:191], v[54:57]
	v_mfma_f32_16x16x32_bf16 v[50:53], v[180:183], v[188:191], v[50:53]
	v_mfma_f32_16x16x32_bf16 v[38:41], v[172:175], v[196:199], v[38:41]
	v_mfma_f32_16x16x32_bf16 v[34:37], v[180:183], v[196:199], v[34:37]
	v_mfma_f32_16x16x32_bf16 v[22:25], v[172:175], v[204:207], v[22:25]
	v_mfma_f32_16x16x32_bf16 v[18:21], v[180:183], v[204:207], v[18:21]
	v_mfma_f32_16x16x32_bf16 v[6:9], v[172:175], v[212:215], v[6:9]
	v_mfma_f32_16x16x32_bf16 v[2:5], v[180:183], v[212:215], v[2:5]
	s_setprio 0
	s_barrier
	s_add_u32 s38, s38, 0x100
	s_addc_u32 s39, s39, 0
	s_add_u32 s93, s93, 0x100
	s_addc_u32 s94, s94, 0
	s_cmp_ge_i32 s95, s82
	s_mov_b32 s40, s95
	s_cbranch_scc0 .LBB0_225
	s_and_b64 vcc, exec, s[24:25]
	s_cbranch_vccz .LBB0_228

; #define PG8_STAGE(bufoff, gbase, voff) do { _Pragma("unroll") for (int _i = 0; _i < 2; ++_i) \
;         __builtin_amdgcn_global_load_lds((const unsigned*)((const char*)(gbase) + (voff)[_i]), (PG8_LAS unsigned*)(lds + (bufoff) + ldsw + _i * 8192), 16, 0, 0); } while (0)
; #define PG8_LDA(dst, b, h) do { _Pragma("unroll") for (int m = 0; m < 4; ++m) _Pragma("unroll") for (int k = 0; k < 2; ++k) dst[m][k] = *(const PG8_LAS bf16x8*)(lds + PG8_SA(b, h) + aoff + m * 2048 + k * 1024); } while (0)
; #define PG8_LDB(dst, b, h) do { _Pragma("unroll") for (int n = 0; n < 2; ++n) _Pragma("unroll") for (int k = 0; k < 2; ++k) dst[n][k] = *(const PG8_LAS bf16x8*)(lds + PG8_SB(b, h) + boff + n * 2048 + k * 1024); } while (0)
; #define PG8_MMA(ai, bj, At, Bt) do { __builtin_amdgcn_s_setprio(1); _Pragma("unroll") for (int m = 0; m < 4; ++m) _Pragma("unroll") for (int n = 0; n < 2; ++n) _Pragma("unroll") for (int k = 0; k < 2; ++k) \
;         acc[ai][bj][m][n] = __builtin_amdgcn_mfma_f32_16x16x32_bf16(Bt[n][k], At[m][k], acc[ai][bj][m][n], 0, 0, 0); __builtin_amdgcn_s_setprio(0); } while (0)
; #define PG8_WAIT_V(n) asm volatile("s_waitcnt vmcnt(" #n ")" ::: "memory")
; #define PG8_WAIT_L(n) do { asm volatile("s_waitcnt lgkmcnt(" #n ")" ::: "memory"); __builtin_amdgcn_s_waitcnt(0xC07F); } while (0)
; #define PG8_BAR __builtin_amdgcn_s_barrier()
; #define PG8_SCHED __builtin_amdgcn_sched_barrier(0)
; template <class Epi, class Sched, bool SEG3 = false>
; __device__ __forceinline__ void gemm_phase(PG8_LAS unsigned char* lds, const Gemm g, const Sched& S, const Epi& E) {
;     ...
;             const char* a1 = cA + (size_t)(t + 1) * kstep;
;             const char* a2 = last ? nA : cA + (size_t)(t + 2) * kstep; const char* b2 = last ? nB : cB + (size_t)(t + 2) * kstep;
;             const char* a3 = a2 + kstep; const char* b3 = b2 + kstep;
;             PG8_LDB(B0, 0, 0); PG8_LDB(B1, 0, 1); PG8_SCHED; PG8_LDA(At, 0, 0); PG8_STAGE(PG8_SA(1, 1), a1 + hsA, voffA);
;             PG8_WAIT_V(8); PG8_WAIT_L(0); PG8_BAR; if (cur.half != 1) { PG8_MMA(0, 0, At, B0); PG8_MMA(0, 1, At, B1); } PG8_BAR; PG8_SCHED;
;             PG8_LDA(At, 0, 1); PG8_STAGE(PG8_SB(0, 0), b2, voffB); PG8_STAGE(PG8_SB(0, 1), b2 + hsB, voffB); PG8_STAGE(PG8_SA(0, 0), a2, voffA);
;             PG8_WAIT_V(8); PG8_WAIT_L(0); PG8_BAR; if (cur.half != 0) { PG8_MMA(1, 0, At, B0); PG8_MMA(1, 1, At, B1); } PG8_BAR; PG8_SCHED;
.LBB0_269:
	v_add_u32_e32 v142, s54, v146
	ds_read_b128 v[152:155], v142
	ds_read_b128 v[156:159], v142 offset:1024
	ds_read_b128 v[160:163], v142 offset:2048
	ds_read_b128 v[164:167], v142 offset:3072
	v_add_u32_e32 v142, s55, v146
	ds_read_b128 v[168:171], v142
	ds_read_b128 v[172:175], v142 offset:1024
	ds_read_b128 v[176:179], v142 offset:2048
	ds_read_b128 v[180:183], v142 offset:3072
	s_add_i32 vcc_lo, s40, 2
	s_add_u32 s0, s38, 0xfffc0080
	s_addc_u32 s1, s39, -1
	s_cmp_eq_u32 s92, s40
	s_cselect_b32 s40, s95, s96
	s_cselect_b32 s43, s17, s1
	s_cselect_b32 s42, s29, s0
	s_cselect_b32 s41, s31, s97
	v_lshl_add_u64 v[142:143], s[38:39], 0, v[138:139]
	s_add_i32 m0, s82, 0xc000
	ds_read_b128 v[184:187], v151
	ds_read_b128 v[188:191], v151 offset:1024
	ds_read_b128 v[192:195], v151 offset:2048
	ds_read_b128 v[196:199], v151 offset:3072
	ds_read_b128 v[200:203], v151 offset:4096
	ds_read_b128 v[204:207], v151 offset:5120
	ds_read_b128 v[208:211], v151 offset:6144
	ds_read_b128 v[212:215], v151 offset:7168
	global_load_lds_dwordx4 v[142:143], off
	s_add_i32 m0, s82, 0xe000
	v_lshl_add_u64 v[142:143], s[38:39], 0, v[140:141]
	global_load_lds_dwordx4 v[142:143], off
	s_waitcnt vmcnt(8) lgkmcnt(0)
	s_barrier
	s_setprio 1
	v_mfma_f32_16x16x32_bf16 v[126:129], v[152:155], v[184:187], v[126:129]
	v_mfma_f32_16x16x32_bf16 v[122:125], v[160:163], v[184:187], v[122:125]
	v_mfma_f32_16x16x32_bf16 v[110:113], v[152:155], v[192:195], v[110:113]
	v_mfma_f32_16x16x32_bf16 v[106:109], v[160:163], v[192:195], v[106:109]
	v_mfma_f32_16x16x32_bf16 v[94:97], v[152:155], v[200:203], v[94:97]
	v_mfma_f32_16x16x32_bf16 v[90:93], v[160:163], v[200:203], v[90:93]
	v_mfma_f32_16x16x32_bf16 v[78:81], v[152:155], v[208:211], v[78:81]
	v_mfma_f32_16x16x32_bf16 v[74:77], v[160:163], v[208:211], v[74:77]
	v_mfma_f32_16x16x32_bf16 v[126:129], v[156:159], v[188:191], v[126:129]
	v_mfma_f32_16x16x32_bf16 v[122:125], v[164:167], v[188:191], v[122:125]
	v_mfma_f32_16x16x32_bf16 v[110:113], v[156:159], v[196:199], v[110:113]
	v_mfma_f32_16x16x32_bf16 v[106:109], v[164:167], v[196:199], v[106:109]
	v_mfma_f32_16x16x32_bf16 v[94:97], v[156:159], v[204:207], v[94:97]
	v_mfma_f32_16x16x32_bf16 v[90:93], v[164:167], v[204:207], v[90:93]
	v_mfma_f32_16x16x32_bf16 v[78:81], v[156:159], v[212:215], v[78:81]
	v_mfma_f32_16x16x32_bf16 v[74:77], v[164:167], v[212:215], v[74:77]
	s_setprio 0
	s_setprio 1
	v_mfma_f32_16x16x32_bf16 v[118:121], v[168:171], v[184:187], v[118:121]
	v_mfma_f32_16x16x32_bf16 v[114:117], v[176:179], v[184:187], v[114:117]
	v_mfma_f32_16x16x32_bf16 v[102:105], v[168:171], v[192:195], v[102:105]
	v_mfma_f32_16x16x32_bf16 v[98:101], v[176:179], v[192:195], v[98:101]
	v_mfma_f32_16x16x32_bf16 v[86:89], v[168:171], v[200:203], v[86:89]
	v_mfma_f32_16x16x32_bf16 v[82:85], v[176:179], v[200:203], v[82:85]
	v_mfma_f32_16x16x32_bf16 v[70:73], v[168:171], v[208:211], v[70:73]
	v_mfma_f32_16x16x32_bf16 v[66:69], v[176:179], v[208:211], v[66:69]
	v_mfma_f32_16x16x32_bf16 v[118:121], v[172:175], v[188:191], v[118:121]
	v_mfma_f32_16x16x32_bf16 v[114:117], v[180:183], v[188:191], v[114:117]
	v_mfma_f32_16x16x32_bf16 v[102:105], v[172:175], v[196:199], v[102:105]
	v_mfma_f32_16x16x32_bf16 v[98:101], v[180:183], v[196:199], v[98:101]
	v_mfma_f32_16x16x32_bf16 v[86:89], v[172:175], v[204:207], v[86:89]
	v_mfma_f32_16x16x32_bf16 v[82:85], v[180:183], v[204:207], v[82:85]
	v_mfma_f32_16x16x32_bf16 v[70:73], v[172:175], v[212:215], v[70:73]
	v_mfma_f32_16x16x32_bf16 v[66:69], v[180:183], v[212:215], v[66:69]
	s_setprio 0
	s_barrier
	s_mov_b32 m0, s19
	v_lshl_add_u64 v[142:143], s[40:41], 0, v[130:131]
	s_add_u32 s0, s40, 0x40000
	ds_read_b128 v[184:187], v151 offset:16384
	ds_read_b128 v[188:191], v151 offset:17408
	ds_read_b128 v[192:195], v151 offset:18432
	ds_read_b128 v[196:199], v151 offset:19456
	ds_read_b128 v[200:203], v151 offset:20480
	ds_read_b128 v[204:207], v151 offset:21504
	ds_read_b128 v[208:211], v151 offset:22528
	ds_read_b128 v[212:215], v151 offset:23552
	global_load_lds_dwordx4 v[142:143], off
	v_lshl_add_u64 v[216:217], s[40:41], 0, v[136:137]
	s_mov_b32 m0, s79
	s_addc_u32 s1, s41, 0
	global_load_lds_dwordx4 v[216:217], off
	v_lshl_add_u64 v[218:219], s[0:1], 0, v[130:131]
	s_mov_b32 m0, s80
	v_lshl_add_u64 v[220:221], s[42:43], 0, v[134:135]
	global_load_lds_dwordx4 v[218:219], off
	s_mov_b32 m0, s81
	v_lshl_add_u64 v[218:219], s[0:1], 0, v[136:137]
	global_load_lds_dwordx4 v[218:219], off
	s_mov_b32 m0, s82
	v_lshl_add_u64 v[218:219], s[42:43], 0, v[132:133]
	global_load_lds_dwordx4 v[218:219], off
	s_mov_b32 m0, s83
	s_nop 0
	global_load_lds_dwordx4 v[220:221], off
	s_waitcnt vmcnt(8) lgkmcnt(0)
	s_barrier
; #define PG8_STAGE(bufoff, gbase, voff) do { _Pragma("unroll") for (int _i = 0; _i < 2; ++_i) \
;         __builtin_amdgcn_global_load_lds((const unsigned*)((const char*)(gbase) + (voff)[_i]), (PG8_LAS unsigned*)(lds + (bufoff) + ldsw + _i * 8192), 16, 0, 0); } while (0)
; #define PG8_LDA(dst, b, h) do { _Pragma("unroll") for (int m = 0; m < 4; ++m) _Pragma("unroll") for (int k = 0; k < 2; ++k) dst[m][k] = *(const PG8_LAS bf16x8*)(lds + PG8_SA(b, h) + aoff + m * 2048 + k * 1024); } while (0)
; #define PG8_LDB(dst, b, h) do { _Pragma("unroll") for (int n = 0; n < 2; ++n) _Pragma("unroll") for (int k = 0; k < 2; ++k) dst[n][k] = *(const PG8_LAS bf16x8*)(lds + PG8_SB(b, h) + boff + n * 2048 + k * 1024); } while (0)
; #define PG8_MMA(ai, bj, At, Bt) do { __builtin_amdgcn_s_setprio(1); _Pragma("unroll") for (int m = 0; m < 4; ++m) _Pragma("unroll") for (int n = 0; n < 2; ++n) _Pragma("unroll") for (int k = 0; k < 2; ++k) \
;         acc[ai][bj][m][n] = __builtin_amdgcn_mfma_f32_16x16x32_bf16(Bt[n][k], At[m][k], acc[ai][bj][m][n], 0, 0, 0); __builtin_amdgcn_s_setprio(0); } while (0)
; #define PG8_WAIT_V(n) asm volatile("s_waitcnt vmcnt(" #n ")" ::: "memory")
; #define PG8_WAIT_L(n) do { asm volatile("s_waitcnt lgkmcnt(" #n ")" ::: "memory"); __builtin_amdgcn_s_waitcnt(0xC07F); } while (0)
; #define PG8_BAR __builtin_amdgcn_s_barrier()
; #define PG8_SCHED __builtin_amdgcn_sched_barrier(0)
; template <class Epi, class Sched, bool SEG3 = false>
; __device__ __forceinline__ void gemm_phase(PG8_LAS unsigned char* lds, const Gemm g, const Sched& S, const Epi& E) {
;     ...
;             PG8_WAIT_V(8); PG8_WAIT_L(0); PG8_BAR; if (cur.half != 0) { PG8_MMA(1, 0, At, B0); PG8_MMA(1, 1, At, B1); } PG8_BAR; PG8_SCHED;
;             PG8_LDB(B0, 1, 0); PG8_LDB(B1, 1, 1); PG8_SCHED; PG8_LDA(At, 1, 0); PG8_STAGE(PG8_SA(0, 1), a2 + hsA, voffA);
;             PG8_WAIT_V(8); PG8_WAIT_L(0); PG8_BAR; if (cur.half != 1) { PG8_MMA(0, 0, At, B0); PG8_MMA(0, 1, At, B1); } PG8_BAR; PG8_SCHED;
	s_setprio 1
	v_mfma_f32_16x16x32_bf16 v[62:65], v[152:155], v[184:187], v[62:65]
	v_mfma_f32_16x16x32_bf16 v[58:61], v[160:163], v[184:187], v[58:61]
	v_mfma_f32_16x16x32_bf16 v[46:49], v[152:155], v[192:195], v[46:49]
	v_mfma_f32_16x16x32_bf16 v[42:45], v[160:163], v[192:195], v[42:45]
	v_mfma_f32_16x16x32_bf16 v[30:33], v[152:155], v[200:203], v[30:33]
	v_mfma_f32_16x16x32_bf16 v[26:29], v[160:163], v[200:203], v[26:29]
	v_mfma_f32_16x16x32_bf16 v[14:17], v[152:155], v[208:211], v[14:17]
	v_mfma_f32_16x16x32_bf16 v[10:13], v[160:163], v[208:211], v[10:13]
	v_mfma_f32_16x16x32_bf16 v[62:65], v[156:159], v[188:191], v[62:65]
	v_mfma_f32_16x16x32_bf16 v[58:61], v[164:167], v[188:191], v[58:61]
	v_mfma_f32_16x16x32_bf16 v[46:49], v[156:159], v[196:199], v[46:49]
	v_mfma_f32_16x16x32_bf16 v[42:45], v[164:167], v[196:199], v[42:45]
	v_mfma_f32_16x16x32_bf16 v[30:33], v[156:159], v[204:207], v[30:33]
	v_mfma_f32_16x16x32_bf16 v[26:29], v[164:167], v[204:207], v[26:29]
	v_mfma_f32_16x16x32_bf16 v[14:17], v[156:159], v[212:215], v[14:17]
	v_mfma_f32_16x16x32_bf16 v[10:13], v[164:167], v[212:215], v[10:13]
	s_setprio 0
	s_setprio 1
	v_mfma_f32_16x16x32_bf16 v[54:57], v[168:171], v[184:187], v[54:57]
	v_mfma_f32_16x16x32_bf16 v[50:53], v[176:179], v[184:187], v[50:53]
	v_mfma_f32_16x16x32_bf16 v[38:41], v[168:171], v[192:195], v[38:41]
	v_mfma_f32_16x16x32_bf16 v[34:37], v[176:179], v[192:195], v[34:37]
	v_mfma_f32_16x16x32_bf16 v[22:25], v[168:171], v[200:203], v[22:25]
	v_mfma_f32_16x16x32_bf16 v[18:21], v[176:179], v[200:203], v[18:21]
	v_mfma_f32_16x16x32_bf16 v[6:9], v[168:171], v[208:211], v[6:9]
	v_mfma_f32_16x16x32_bf16 v[2:5], v[176:179], v[208:211], v[2:5]
	v_mfma_f32_16x16x32_bf16 v[54:57], v[172:175], v[188:191], v[54:57]
	v_mfma_f32_16x16x32_bf16 v[50:53], v[180:183], v[188:191], v[50:53]
	v_mfma_f32_16x16x32_bf16 v[38:41], v[172:175], v[196:199], v[38:41]
	v_mfma_f32_16x16x32_bf16 v[34:37], v[180:183], v[196:199], v[34:37]
	v_mfma_f32_16x16x32_bf16 v[22:25], v[172:175], v[204:207], v[22:25]
	v_mfma_f32_16x16x32_bf16 v[18:21], v[180:183], v[204:207], v[18:21]
	v_mfma_f32_16x16x32_bf16 v[6:9], v[172:175], v[212:215], v[6:9]
	v_mfma_f32_16x16x32_bf16 v[2:5], v[180:183], v[212:215], v[2:5]
	s_setprio 0
	s_barrier
	v_add_u32_e32 v164, s56, v146
	v_add_u32_e32 v180, s57, v146
	ds_read_b128 v[152:155], v164
	ds_read_b128 v[156:159], v164 offset:1024
	ds_read_b128 v[160:163], v164 offset:2048
	ds_read_b128 v[164:167], v164 offset:3072
	ds_read_b128 v[168:171], v180
	ds_read_b128 v[172:175], v180 offset:1024
	ds_read_b128 v[176:179], v180 offset:2048
	ds_read_b128 v[180:183], v180 offset:3072
	s_add_u32 s0, s42, 0x40000
	s_addc_u32 s1, s43, 0
	s_mov_b32 m0, s84
	v_lshl_add_u64 v[222:223], s[0:1], 0, v[132:133]
	ds_read_b128 v[184:187], v151 offset:32768
	ds_read_b128 v[188:191], v151 offset:33792
	ds_read_b128 v[192:195], v151 offset:34816
	ds_read_b128 v[196:199], v151 offset:35840
	ds_read_b128 v[200:203], v151 offset:36864
	ds_read_b128 v[204:207], v151 offset:37888
	ds_read_b128 v[208:211], v151 offset:38912
	ds_read_b128 v[212:215], v151 offset:39936
	global_load_lds_dwordx4 v[222:223], off
	s_mov_b32 m0, s85
	v_lshl_add_u64 v[222:223], s[0:1], 0, v[134:135]
	global_load_lds_dwordx4 v[222:223], off
	s_waitcnt vmcnt(8) lgkmcnt(0)
	s_barrier
	s_setprio 1
	v_mfma_f32_16x16x32_bf16 v[126:129], v[152:155], v[184:187], v[126:129]
	v_mfma_f32_16x16x32_bf16 v[122:125], v[160:163], v[184:187], v[122:125]
	v_mfma_f32_16x16x32_bf16 v[110:113], v[152:155], v[192:195], v[110:113]
	v_mfma_f32_16x16x32_bf16 v[106:109], v[160:163], v[192:195], v[106:109]
	v_mfma_f32_16x16x32_bf16 v[94:97], v[152:155], v[200:203], v[94:97]
	v_mfma_f32_16x16x32_bf16 v[90:93], v[160:163], v[200:203], v[90:93]
	v_mfma_f32_16x16x32_bf16 v[78:81], v[152:155], v[208:211], v[78:81]
	v_mfma_f32_16x16x32_bf16 v[74:77], v[160:163], v[208:211], v[74:77]
	v_mfma_f32_16x16x32_bf16 v[126:129], v[156:159], v[188:191], v[126:129]
	v_mfma_f32_16x16x32_bf16 v[122:125], v[164:167], v[188:191], v[122:125]
	v_mfma_f32_16x16x32_bf16 v[110:113], v[156:159], v[196:199], v[110:113]
	v_mfma_f32_16x16x32_bf16 v[106:109], v[164:167], v[196:199], v[106:109]
	v_mfma_f32_16x16x32_bf16 v[94:97], v[156:159], v[204:207], v[94:97]
	v_mfma_f32_16x16x32_bf16 v[90:93], v[164:167], v[204:207], v[90:93]
	v_mfma_f32_16x16x32_bf16 v[78:81], v[156:159], v[212:215], v[78:81]
	v_mfma_f32_16x16x32_bf16 v[74:77], v[164:167], v[212:215], v[74:77]
	s_setprio 0
	s_setprio 1
	v_mfma_f32_16x16x32_bf16 v[118:121], v[168:171], v[184:187], v[118:121]
	v_mfma_f32_16x16x32_bf16 v[114:117], v[176:179], v[184:187], v[114:117]
	v_mfma_f32_16x16x32_bf16 v[102:105], v[168:171], v[192:195], v[102:105]
	v_mfma_f32_16x16x32_bf16 v[98:101], v[176:179], v[192:195], v[98:101]
	v_mfma_f32_16x16x32_bf16 v[86:89], v[168:171], v[200:203], v[86:89]
	v_mfma_f32_16x16x32_bf16 v[82:85], v[176:179], v[200:203], v[82:85]
	v_mfma_f32_16x16x32_bf16 v[70:73], v[168:171], v[208:211], v[70:73]
	v_mfma_f32_16x16x32_bf16 v[66:69], v[176:179], v[208:211], v[66:69]
	v_mfma_f32_16x16x32_bf16 v[118:121], v[172:175], v[188:191], v[118:121]
	v_mfma_f32_16x16x32_bf16 v[114:117], v[180:183], v[188:191], v[114:117]
	v_mfma_f32_16x16x32_bf16 v[102:105], v[172:175], v[196:199], v[102:105]
	v_mfma_f32_16x16x32_bf16 v[98:101], v[180:183], v[196:199], v[98:101]
	v_mfma_f32_16x16x32_bf16 v[86:89], v[172:175], v[204:207], v[86:89]
	v_mfma_f32_16x16x32_bf16 v[82:85], v[180:183], v[204:207], v[82:85]
	v_mfma_f32_16x16x32_bf16 v[70:73], v[172:175], v[212:215], v[70:73]
	v_mfma_f32_16x16x32_bf16 v[66:69], v[180:183], v[212:215], v[66:69]
	s_setprio 0
	s_barrier
; #define PG8_STAGE(bufoff, gbase, voff) do { _Pragma("unroll") for (int _i = 0; _i < 2; ++_i) \
;         __builtin_amdgcn_global_load_lds((const unsigned*)((const char*)(gbase) + (voff)[_i]), (PG8_LAS unsigned*)(lds + (bufoff) + ldsw + _i * 8192), 16, 0, 0); } while (0)
; #define PG8_LDA(dst, b, h) do { _Pragma("unroll") for (int m = 0; m < 4; ++m) _Pragma("unroll") for (int k = 0; k < 2; ++k) dst[m][k] = *(const PG8_LAS bf16x8*)(lds + PG8_SA(b, h) + aoff + m * 2048 + k * 1024); } while (0)
; #define PG8_MMA(ai, bj, At, Bt) do { __builtin_amdgcn_s_setprio(1); _Pragma("unroll") for (int m = 0; m < 4; ++m) _Pragma("unroll") for (int n = 0; n < 2; ++n) _Pragma("unroll") for (int k = 0; k < 2; ++k) \
;         acc[ai][bj][m][n] = __builtin_amdgcn_mfma_f32_16x16x32_bf16(Bt[n][k], At[m][k], acc[ai][bj][m][n], 0, 0, 0); __builtin_amdgcn_s_setprio(0); } while (0)
; #define PG8_WAIT_V(n) asm volatile("s_waitcnt vmcnt(" #n ")" ::: "memory")
; #define PG8_WAIT_L(n) do { asm volatile("s_waitcnt lgkmcnt(" #n ")" ::: "memory"); __builtin_amdgcn_s_waitcnt(0xC07F); } while (0)
; #define PG8_BAR __builtin_amdgcn_s_barrier()
; #define PG8_SCHED __builtin_amdgcn_sched_barrier(0)
; template <class Epi, class Sched, bool SEG3 = false>
; __device__ __forceinline__ void gemm_phase(PG8_LAS unsigned char* lds, const Gemm g, const Sched& S, const Epi& E) {
;     ...
;             PG8_LDA(At, 1, 1); PG8_STAGE(PG8_SB(1, 0), b3, voffB); PG8_STAGE(PG8_SB(1, 1), b3 + hsB, voffB); PG8_STAGE(PG8_SA(1, 0), a3, voffA);
;             PG8_WAIT_V(8); PG8_WAIT_L(0); PG8_BAR; if (cur.half != 0) { PG8_MMA(1, 0, At, B0); PG8_MMA(1, 1, At, B1); } PG8_BAR; PG8_SCHED;
;         }
	s_mov_b32 m0, s86
	v_lshl_add_u64 v[142:143], v[142:143], 0, s[6:7]
	s_add_u32 s0, s40, 0x40080
	ds_read_b128 v[184:187], v151 offset:49152
	ds_read_b128 v[188:191], v151 offset:50176
	ds_read_b128 v[192:195], v151 offset:51200
	ds_read_b128 v[196:199], v151 offset:52224
	ds_read_b128 v[200:203], v151 offset:53248
	ds_read_b128 v[204:207], v151 offset:54272
	ds_read_b128 v[208:211], v151 offset:55296
	ds_read_b128 v[212:215], v151 offset:56320
	global_load_lds_dwordx4 v[142:143], off
	v_lshl_add_u64 v[142:143], v[216:217], 0, s[6:7]
	s_mov_b32 m0, s87
	s_addc_u32 s1, s41, 0
	global_load_lds_dwordx4 v[142:143], off
	s_mov_b32 m0, s90
	v_lshl_add_u64 v[142:143], s[0:1], 0, v[130:131]
	global_load_lds_dwordx4 v[142:143], off
	s_mov_b32 m0, s91
	v_lshl_add_u64 v[142:143], s[0:1], 0, v[136:137]
	global_load_lds_dwordx4 v[142:143], off
	s_mov_b32 m0, s88
	v_lshl_add_u64 v[142:143], v[218:219], 0, s[6:7]
	global_load_lds_dwordx4 v[142:143], off
	s_mov_b32 m0, s89
	v_lshl_add_u64 v[142:143], v[220:221], 0, s[6:7]
	global_load_lds_dwordx4 v[142:143], off
	s_waitcnt vmcnt(8) lgkmcnt(0)
	s_barrier
	s_setprio 1
	v_mfma_f32_16x16x32_bf16 v[62:65], v[152:155], v[184:187], v[62:65]
	v_mfma_f32_16x16x32_bf16 v[58:61], v[160:163], v[184:187], v[58:61]
	v_mfma_f32_16x16x32_bf16 v[46:49], v[152:155], v[192:195], v[46:49]
	v_mfma_f32_16x16x32_bf16 v[42:45], v[160:163], v[192:195], v[42:45]
	v_mfma_f32_16x16x32_bf16 v[30:33], v[152:155], v[200:203], v[30:33]
	v_mfma_f32_16x16x32_bf16 v[26:29], v[160:163], v[200:203], v[26:29]
	v_mfma_f32_16x16x32_bf16 v[14:17], v[152:155], v[208:211], v[14:17]
	v_mfma_f32_16x16x32_bf16 v[10:13], v[160:163], v[208:211], v[10:13]
	v_mfma_f32_16x16x32_bf16 v[62:65], v[156:159], v[188:191], v[62:65]
	v_mfma_f32_16x16x32_bf16 v[58:61], v[164:167], v[188:191], v[58:61]
	v_mfma_f32_16x16x32_bf16 v[46:49], v[156:159], v[196:199], v[46:49]
	v_mfma_f32_16x16x32_bf16 v[42:45], v[164:167], v[196:199], v[42:45]
	v_mfma_f32_16x16x32_bf16 v[30:33], v[156:159], v[204:207], v[30:33]
	v_mfma_f32_16x16x32_bf16 v[26:29], v[164:167], v[204:207], v[26:29]
	v_mfma_f32_16x16x32_bf16 v[14:17], v[156:159], v[212:215], v[14:17]
	v_mfma_f32_16x16x32_bf16 v[10:13], v[164:167], v[212:215], v[10:13]
	s_setprio 0
	s_setprio 1
	v_mfma_f32_16x16x32_bf16 v[54:57], v[168:171], v[184:187], v[54:57]
	v_mfma_f32_16x16x32_bf16 v[50:53], v[176:179], v[184:187], v[50:53]
	v_mfma_f32_16x16x32_bf16 v[38:41], v[168:171], v[192:195], v[38:41]
	v_mfma_f32_16x16x32_bf16 v[34:37], v[176:179], v[192:195], v[34:37]
	v_mfma_f32_16x16x32_bf16 v[22:25], v[168:171], v[200:203], v[22:25]
	v_mfma_f32_16x16x32_bf16 v[18:21], v[176:179], v[200:203], v[18:21]
	v_mfma_f32_16x16x32_bf16 v[6:9], v[168:171], v[208:211], v[6:9]
	v_mfma_f32_16x16x32_bf16 v[2:5], v[176:179], v[208:211], v[2:5]
	v_mfma_f32_16x16x32_bf16 v[54:57], v[172:175], v[188:191], v[54:57]
	v_mfma_f32_16x16x32_bf16 v[50:53], v[180:183], v[188:191], v[50:53]
	v_mfma_f32_16x16x32_bf16 v[38:41], v[172:175], v[196:199], v[38:41]
	v_mfma_f32_16x16x32_bf16 v[34:37], v[180:183], v[196:199], v[34:37]
	v_mfma_f32_16x16x32_bf16 v[22:25], v[172:175], v[204:207], v[22:25]
	v_mfma_f32_16x16x32_bf16 v[18:21], v[180:183], v[204:207], v[18:21]
	v_mfma_f32_16x16x32_bf16 v[6:9], v[172:175], v[212:215], v[6:9]
	v_mfma_f32_16x16x32_bf16 v[2:5], v[180:183], v[212:215], v[2:5]
	s_setprio 0
	s_barrier
	s_add_u32 s38, s38, 0x100
	s_addc_u32 s39, s39, 0
	s_add_u32 s96, s96, 0x100
	s_addc_u32 s97, s97, 0
	s_cmp_ge_i32 vcc_lo, s73
	s_mov_b32 s40, vcc_lo
	s_cbranch_scc0 .LBB0_269
	s_and_b64 vcc, exec, s[24:25]
	s_cbranch_vccz .LBB0_272

; #define PG8_STAGE(bufoff, gbase, voff) do { _Pragma("unroll") for (int _i = 0; _i < 2; ++_i) \
;         __builtin_amdgcn_global_load_lds((const unsigned*)((const char*)(gbase) + (voff)[_i]), (PG8_LAS unsigned*)(lds + (bufoff) + ldsw + _i * 8192), 16, 0, 0); } while (0)
; #define PG8_LDA(dst, b, h) do { _Pragma("unroll") for (int m = 0; m < 4; ++m) _Pragma("unroll") for (int k = 0; k < 2; ++k) dst[m][k] = *(const PG8_LAS bf16x8*)(lds + PG8_SA(b, h) + aoff + m * 2048 + k * 1024); } while (0)
; #define PG8_LDB(dst, b, h) do { _Pragma("unroll") for (int n = 0; n < 2; ++n) _Pragma("unroll") for (int k = 0; k < 2; ++k) dst[n][k] = *(const PG8_LAS bf16x8*)(lds + PG8_SB(b, h) + boff + n * 2048 + k * 1024); } while (0)
; #define PG8_MMA(ai, bj, At, Bt) do { __builtin_amdgcn_s_setprio(1); _Pragma("unroll") for (int m = 0; m < 4; ++m) _Pragma("unroll") for (int n = 0; n < 2; ++n) _Pragma("unroll") for (int k = 0; k < 2; ++k) \
;         acc[ai][bj][m][n] = __builtin_amdgcn_mfma_f32_16x16x32_bf16(Bt[n][k], At[m][k], acc[ai][bj][m][n], 0, 0, 0); __builtin_amdgcn_s_setprio(0); } while (0)
; #define PG8_WAIT_V(n) asm volatile("s_waitcnt vmcnt(" #n ")" ::: "memory")
; #define PG8_WAIT_L(n) do { asm volatile("s_waitcnt lgkmcnt(" #n ")" ::: "memory"); __builtin_amdgcn_s_waitcnt(0xC07F); } while (0)
; #define PG8_BAR __builtin_amdgcn_s_barrier()
; #define PG8_SCHED __builtin_amdgcn_sched_barrier(0)
; template <class Epi, class Sched, bool SEG3 = false>
; __device__ __forceinline__ void gemm_phase(PG8_LAS unsigned char* lds, const Gemm g, const Sched& S, const Epi& E) {
;     ...
;             const char* a1 = cA + (size_t)(t + 1) * kstep;
;             const char* a2 = last ? nA : cA + (size_t)(t + 2) * kstep; const char* b2 = last ? nB : cB + (size_t)(t + 2) * kstep;
;             const char* a3 = a2 + kstep; const char* b3 = b2 + kstep;
;             PG8_LDB(B0, 0, 0); PG8_LDB(B1, 0, 1); PG8_SCHED; PG8_LDA(At, 0, 0); PG8_STAGE(PG8_SA(1, 1), a1 + hsA, voffA);
;             PG8_WAIT_V(8); PG8_WAIT_L(0); PG8_BAR; if (cur.half != 1) { PG8_MMA(0, 0, At, B0); PG8_MMA(0, 1, At, B1); } PG8_BAR; PG8_SCHED;
;             PG8_LDA(At, 0, 1); PG8_STAGE(PG8_SB(0, 0), b2, voffB); PG8_STAGE(PG8_SB(0, 1), b2 + hsB, voffB); PG8_STAGE(PG8_SA(0, 0), a2, voffA);
;             PG8_WAIT_V(8); PG8_WAIT_L(0); PG8_BAR; if (cur.half != 0) { PG8_MMA(1, 0, At, B0); PG8_MMA(1, 1, At, B1); } PG8_BAR; PG8_SCHED;
.LBB0_313:
	v_add_u32_e32 v142, s54, v146
	ds_read_b128 v[152:155], v142
	ds_read_b128 v[156:159], v142 offset:1024
	ds_read_b128 v[160:163], v142 offset:2048
	ds_read_b128 v[164:167], v142 offset:3072
	v_add_u32_e32 v142, s55, v146
	ds_read_b128 v[168:171], v142
	ds_read_b128 v[172:175], v142 offset:1024
	ds_read_b128 v[176:179], v142 offset:2048
	ds_read_b128 v[180:183], v142 offset:3072
	s_add_i32 s93, s40, 2
	s_add_u32 s0, s38, 0xfffc0080
	s_addc_u32 s1, s39, -1
	s_cmp_eq_u32 s87, s40
	s_cselect_b32 s40, s90, s91
	s_cselect_b32 s43, s17, s1
	s_cselect_b32 s42, s29, s0
	s_cselect_b32 s41, s31, s92
	v_lshl_add_u64 v[142:143], s[38:39], 0, v[138:139]
	s_add_i32 m0, s77, 0xc000
	ds_read_b128 v[184:187], v151
	ds_read_b128 v[188:191], v151 offset:1024
	ds_read_b128 v[192:195], v151 offset:2048
	ds_read_b128 v[196:199], v151 offset:3072
	ds_read_b128 v[200:203], v151 offset:4096
	ds_read_b128 v[204:207], v151 offset:5120
	ds_read_b128 v[208:211], v151 offset:6144
	ds_read_b128 v[212:215], v151 offset:7168
	global_load_lds_dwordx4 v[142:143], off
	s_add_i32 m0, s77, 0xe000
	v_lshl_add_u64 v[142:143], s[38:39], 0, v[140:141]
	global_load_lds_dwordx4 v[142:143], off
	s_waitcnt vmcnt(8) lgkmcnt(0)
	s_barrier
	s_setprio 1
	v_mfma_f32_16x16x32_bf16 v[126:129], v[152:155], v[184:187], v[126:129]
	v_mfma_f32_16x16x32_bf16 v[122:125], v[160:163], v[184:187], v[122:125]
	v_mfma_f32_16x16x32_bf16 v[110:113], v[152:155], v[192:195], v[110:113]
	v_mfma_f32_16x16x32_bf16 v[106:109], v[160:163], v[192:195], v[106:109]
	v_mfma_f32_16x16x32_bf16 v[94:97], v[152:155], v[200:203], v[94:97]
	v_mfma_f32_16x16x32_bf16 v[90:93], v[160:163], v[200:203], v[90:93]
	v_mfma_f32_16x16x32_bf16 v[78:81], v[152:155], v[208:211], v[78:81]
	v_mfma_f32_16x16x32_bf16 v[74:77], v[160:163], v[208:211], v[74:77]
	v_mfma_f32_16x16x32_bf16 v[126:129], v[156:159], v[188:191], v[126:129]
	v_mfma_f32_16x16x32_bf16 v[122:125], v[164:167], v[188:191], v[122:125]
	v_mfma_f32_16x16x32_bf16 v[110:113], v[156:159], v[196:199], v[110:113]
	v_mfma_f32_16x16x32_bf16 v[106:109], v[164:167], v[196:199], v[106:109]
	v_mfma_f32_16x16x32_bf16 v[94:97], v[156:159], v[204:207], v[94:97]
	v_mfma_f32_16x16x32_bf16 v[90:93], v[164:167], v[204:207], v[90:93]
	v_mfma_f32_16x16x32_bf16 v[78:81], v[156:159], v[212:215], v[78:81]
	v_mfma_f32_16x16x32_bf16 v[74:77], v[164:167], v[212:215], v[74:77]
	s_setprio 0
	s_setprio 1
	v_mfma_f32_16x16x32_bf16 v[118:121], v[168:171], v[184:187], v[118:121]
	v_mfma_f32_16x16x32_bf16 v[114:117], v[176:179], v[184:187], v[114:117]
	v_mfma_f32_16x16x32_bf16 v[102:105], v[168:171], v[192:195], v[102:105]
	v_mfma_f32_16x16x32_bf16 v[98:101], v[176:179], v[192:195], v[98:101]
	v_mfma_f32_16x16x32_bf16 v[86:89], v[168:171], v[200:203], v[86:89]
	v_mfma_f32_16x16x32_bf16 v[82:85], v[176:179], v[200:203], v[82:85]
	v_mfma_f32_16x16x32_bf16 v[70:73], v[168:171], v[208:211], v[70:73]
	v_mfma_f32_16x16x32_bf16 v[66:69], v[176:179], v[208:211], v[66:69]
	v_mfma_f32_16x16x32_bf16 v[118:121], v[172:175], v[188:191], v[118:121]
	v_mfma_f32_16x16x32_bf16 v[114:117], v[180:183], v[188:191], v[114:117]
	v_mfma_f32_16x16x32_bf16 v[102:105], v[172:175], v[196:199], v[102:105]
	v_mfma_f32_16x16x32_bf16 v[98:101], v[180:183], v[196:199], v[98:101]
	v_mfma_f32_16x16x32_bf16 v[86:89], v[172:175], v[204:207], v[86:89]
	v_mfma_f32_16x16x32_bf16 v[82:85], v[180:183], v[204:207], v[82:85]
	v_mfma_f32_16x16x32_bf16 v[70:73], v[172:175], v[212:215], v[70:73]
	v_mfma_f32_16x16x32_bf16 v[66:69], v[180:183], v[212:215], v[66:69]
	s_setprio 0
	s_barrier
	s_mov_b32 m0, s19
	v_lshl_add_u64 v[142:143], s[40:41], 0, v[130:131]
	s_add_u32 s0, s40, 0x40000
	ds_read_b128 v[184:187], v151 offset:16384
	ds_read_b128 v[188:191], v151 offset:17408
	ds_read_b128 v[192:195], v151 offset:18432
	ds_read_b128 v[196:199], v151 offset:19456
	ds_read_b128 v[200:203], v151 offset:20480
	ds_read_b128 v[204:207], v151 offset:21504
	ds_read_b128 v[208:211], v151 offset:22528
	ds_read_b128 v[212:215], v151 offset:23552
	global_load_lds_dwordx4 v[142:143], off
	v_lshl_add_u64 v[216:217], s[40:41], 0, v[136:137]
	s_mov_b32 m0, s74
	s_addc_u32 s1, s41, 0
	global_load_lds_dwordx4 v[216:217], off
	v_lshl_add_u64 v[218:219], s[0:1], 0, v[130:131]
	s_mov_b32 m0, s75
	v_lshl_add_u64 v[220:221], s[42:43], 0, v[134:135]
	global_load_lds_dwordx4 v[218:219], off
	s_mov_b32 m0, s76
	v_lshl_add_u64 v[218:219], s[0:1], 0, v[136:137]
	global_load_lds_dwordx4 v[218:219], off
	s_mov_b32 m0, s77
	v_lshl_add_u64 v[218:219], s[42:43], 0, v[132:133]
	global_load_lds_dwordx4 v[218:219], off
	s_mov_b32 m0, s78
	s_nop 0
	global_load_lds_dwordx4 v[220:221], off
	s_waitcnt vmcnt(8) lgkmcnt(0)
	s_barrier
; #define PG8_STAGE(bufoff, gbase, voff) do { _Pragma("unroll") for (int _i = 0; _i < 2; ++_i) \
;         __builtin_amdgcn_global_load_lds((const unsigned*)((const char*)(gbase) + (voff)[_i]), (PG8_LAS unsigned*)(lds + (bufoff) + ldsw + _i * 8192), 16, 0, 0); } while (0)
; #define PG8_LDA(dst, b, h) do { _Pragma("unroll") for (int m = 0; m < 4; ++m) _Pragma("unroll") for (int k = 0; k < 2; ++k) dst[m][k] = *(const PG8_LAS bf16x8*)(lds + PG8_SA(b, h) + aoff + m * 2048 + k * 1024); } while (0)
; #define PG8_LDB(dst, b, h) do { _Pragma("unroll") for (int n = 0; n < 2; ++n) _Pragma("unroll") for (int k = 0; k < 2; ++k) dst[n][k] = *(const PG8_LAS bf16x8*)(lds + PG8_SB(b, h) + boff + n * 2048 + k * 1024); } while (0)
; #define PG8_MMA(ai, bj, At, Bt) do { __builtin_amdgcn_s_setprio(1); _Pragma("unroll") for (int m = 0; m < 4; ++m) _Pragma("unroll") for (int n = 0; n < 2; ++n) _Pragma("unroll") for (int k = 0; k < 2; ++k) \
;         acc[ai][bj][m][n] = __builtin_amdgcn_mfma_f32_16x16x32_bf16(Bt[n][k], At[m][k], acc[ai][bj][m][n], 0, 0, 0); __builtin_amdgcn_s_setprio(0); } while (0)
; #define PG8_WAIT_V(n) asm volatile("s_waitcnt vmcnt(" #n ")" ::: "memory")
; #define PG8_WAIT_L(n) do { asm volatile("s_waitcnt lgkmcnt(" #n ")" ::: "memory"); __builtin_amdgcn_s_waitcnt(0xC07F); } while (0)
; #define PG8_BAR __builtin_amdgcn_s_barrier()
; #define PG8_SCHED __builtin_amdgcn_sched_barrier(0)
; template <class Epi, class Sched, bool SEG3 = false>
; __device__ __forceinline__ void gemm_phase(PG8_LAS unsigned char* lds, const Gemm g, const Sched& S, const Epi& E) {
;     ...
;             PG8_WAIT_V(8); PG8_WAIT_L(0); PG8_BAR; if (cur.half != 0) { PG8_MMA(1, 0, At, B0); PG8_MMA(1, 1, At, B1); } PG8_BAR; PG8_SCHED;
;             PG8_LDB(B0, 1, 0); PG8_LDB(B1, 1, 1); PG8_SCHED; PG8_LDA(At, 1, 0); PG8_STAGE(PG8_SA(0, 1), a2 + hsA, voffA);
;             PG8_WAIT_V(8); PG8_WAIT_L(0); PG8_BAR; if (cur.half != 1) { PG8_MMA(0, 0, At, B0); PG8_MMA(0, 1, At, B1); } PG8_BAR; PG8_SCHED;
	s_setprio 1
	v_mfma_f32_16x16x32_bf16 v[62:65], v[152:155], v[184:187], v[62:65]
	v_mfma_f32_16x16x32_bf16 v[58:61], v[160:163], v[184:187], v[58:61]
	v_mfma_f32_16x16x32_bf16 v[46:49], v[152:155], v[192:195], v[46:49]
	v_mfma_f32_16x16x32_bf16 v[42:45], v[160:163], v[192:195], v[42:45]
	v_mfma_f32_16x16x32_bf16 v[30:33], v[152:155], v[200:203], v[30:33]
	v_mfma_f32_16x16x32_bf16 v[26:29], v[160:163], v[200:203], v[26:29]
	v_mfma_f32_16x16x32_bf16 v[14:17], v[152:155], v[208:211], v[14:17]
	v_mfma_f32_16x16x32_bf16 v[10:13], v[160:163], v[208:211], v[10:13]
	v_mfma_f32_16x16x32_bf16 v[62:65], v[156:159], v[188:191], v[62:65]
	v_mfma_f32_16x16x32_bf16 v[58:61], v[164:167], v[188:191], v[58:61]
	v_mfma_f32_16x16x32_bf16 v[46:49], v[156:159], v[196:199], v[46:49]
	v_mfma_f32_16x16x32_bf16 v[42:45], v[164:167], v[196:199], v[42:45]
	v_mfma_f32_16x16x32_bf16 v[30:33], v[156:159], v[204:207], v[30:33]
	v_mfma_f32_16x16x32_bf16 v[26:29], v[164:167], v[204:207], v[26:29]
	v_mfma_f32_16x16x32_bf16 v[14:17], v[156:159], v[212:215], v[14:17]
	v_mfma_f32_16x16x32_bf16 v[10:13], v[164:167], v[212:215], v[10:13]
	s_setprio 0
	s_setprio 1
	v_mfma_f32_16x16x32_bf16 v[54:57], v[168:171], v[184:187], v[54:57]
	v_mfma_f32_16x16x32_bf16 v[50:53], v[176:179], v[184:187], v[50:53]
	v_mfma_f32_16x16x32_bf16 v[38:41], v[168:171], v[192:195], v[38:41]
	v_mfma_f32_16x16x32_bf16 v[34:37], v[176:179], v[192:195], v[34:37]
	v_mfma_f32_16x16x32_bf16 v[22:25], v[168:171], v[200:203], v[22:25]
	v_mfma_f32_16x16x32_bf16 v[18:21], v[176:179], v[200:203], v[18:21]
	v_mfma_f32_16x16x32_bf16 v[6:9], v[168:171], v[208:211], v[6:9]
	v_mfma_f32_16x16x32_bf16 v[2:5], v[176:179], v[208:211], v[2:5]
	v_mfma_f32_16x16x32_bf16 v[54:57], v[172:175], v[188:191], v[54:57]
	v_mfma_f32_16x16x32_bf16 v[50:53], v[180:183], v[188:191], v[50:53]
	v_mfma_f32_16x16x32_bf16 v[38:41], v[172:175], v[196:199], v[38:41]
	v_mfma_f32_16x16x32_bf16 v[34:37], v[180:183], v[196:199], v[34:37]
	v_mfma_f32_16x16x32_bf16 v[22:25], v[172:175], v[204:207], v[22:25]
	v_mfma_f32_16x16x32_bf16 v[18:21], v[180:183], v[204:207], v[18:21]
	v_mfma_f32_16x16x32_bf16 v[6:9], v[172:175], v[212:215], v[6:9]
	v_mfma_f32_16x16x32_bf16 v[2:5], v[180:183], v[212:215], v[2:5]
	s_setprio 0
	s_barrier
	v_add_u32_e32 v164, s56, v146
	v_add_u32_e32 v180, s57, v146
	ds_read_b128 v[152:155], v164
	ds_read_b128 v[156:159], v164 offset:1024
	ds_read_b128 v[160:163], v164 offset:2048
	ds_read_b128 v[164:167], v164 offset:3072
	ds_read_b128 v[168:171], v180
	ds_read_b128 v[172:175], v180 offset:1024
	ds_read_b128 v[176:179], v180 offset:2048
	ds_read_b128 v[180:183], v180 offset:3072
	s_add_u32 s0, s42, 0x40000
	s_addc_u32 s1, s43, 0
	s_mov_b32 m0, s79
	v_lshl_add_u64 v[222:223], s[0:1], 0, v[132:133]
	ds_read_b128 v[184:187], v151 offset:32768
	ds_read_b128 v[188:191], v151 offset:33792
	ds_read_b128 v[192:195], v151 offset:34816
	ds_read_b128 v[196:199], v151 offset:35840
	ds_read_b128 v[200:203], v151 offset:36864
	ds_read_b128 v[204:207], v151 offset:37888
	ds_read_b128 v[208:211], v151 offset:38912
	ds_read_b128 v[212:215], v151 offset:39936
	global_load_lds_dwordx4 v[222:223], off
	s_mov_b32 m0, s80
	v_lshl_add_u64 v[222:223], s[0:1], 0, v[134:135]
	global_load_lds_dwordx4 v[222:223], off
	s_waitcnt vmcnt(8) lgkmcnt(0)
	s_barrier
	s_setprio 1
	v_mfma_f32_16x16x32_bf16 v[126:129], v[152:155], v[184:187], v[126:129]
	v_mfma_f32_16x16x32_bf16 v[122:125], v[160:163], v[184:187], v[122:125]
	v_mfma_f32_16x16x32_bf16 v[110:113], v[152:155], v[192:195], v[110:113]
	v_mfma_f32_16x16x32_bf16 v[106:109], v[160:163], v[192:195], v[106:109]
	v_mfma_f32_16x16x32_bf16 v[94:97], v[152:155], v[200:203], v[94:97]
	v_mfma_f32_16x16x32_bf16 v[90:93], v[160:163], v[200:203], v[90:93]
	v_mfma_f32_16x16x32_bf16 v[78:81], v[152:155], v[208:211], v[78:81]
	v_mfma_f32_16x16x32_bf16 v[74:77], v[160:163], v[208:211], v[74:77]
	v_mfma_f32_16x16x32_bf16 v[126:129], v[156:159], v[188:191], v[126:129]
	v_mfma_f32_16x16x32_bf16 v[122:125], v[164:167], v[188:191], v[122:125]
	v_mfma_f32_16x16x32_bf16 v[110:113], v[156:159], v[196:199], v[110:113]
	v_mfma_f32_16x16x32_bf16 v[106:109], v[164:167], v[196:199], v[106:109]
	v_mfma_f32_16x16x32_bf16 v[94:97], v[156:159], v[204:207], v[94:97]
	v_mfma_f32_16x16x32_bf16 v[90:93], v[164:167], v[204:207], v[90:93]
	v_mfma_f32_16x16x32_bf16 v[78:81], v[156:159], v[212:215], v[78:81]
	v_mfma_f32_16x16x32_bf16 v[74:77], v[164:167], v[212:215], v[74:77]
	s_setprio 0
	s_setprio 1
	v_mfma_f32_16x16x32_bf16 v[118:121], v[168:171], v[184:187], v[118:121]
	v_mfma_f32_16x16x32_bf16 v[114:117], v[176:179], v[184:187], v[114:117]
	v_mfma_f32_16x16x32_bf16 v[102:105], v[168:171], v[192:195], v[102:105]
	v_mfma_f32_16x16x32_bf16 v[98:101], v[176:179], v[192:195], v[98:101]
	v_mfma_f32_16x16x32_bf16 v[86:89], v[168:171], v[200:203], v[86:89]
	v_mfma_f32_16x16x32_bf16 v[82:85], v[176:179], v[200:203], v[82:85]
	v_mfma_f32_16x16x32_bf16 v[70:73], v[168:171], v[208:211], v[70:73]
	v_mfma_f32_16x16x32_bf16 v[66:69], v[176:179], v[208:211], v[66:69]
	v_mfma_f32_16x16x32_bf16 v[118:121], v[172:175], v[188:191], v[118:121]
	v_mfma_f32_16x16x32_bf16 v[114:117], v[180:183], v[188:191], v[114:117]
	v_mfma_f32_16x16x32_bf16 v[102:105], v[172:175], v[196:199], v[102:105]
	v_mfma_f32_16x16x32_bf16 v[98:101], v[180:183], v[196:199], v[98:101]
	v_mfma_f32_16x16x32_bf16 v[86:89], v[172:175], v[204:207], v[86:89]
	v_mfma_f32_16x16x32_bf16 v[82:85], v[180:183], v[204:207], v[82:85]
	v_mfma_f32_16x16x32_bf16 v[70:73], v[172:175], v[212:215], v[70:73]
	v_mfma_f32_16x16x32_bf16 v[66:69], v[180:183], v[212:215], v[66:69]
	s_setprio 0
	s_barrier
; #define PG8_STAGE(bufoff, gbase, voff) do { _Pragma("unroll") for (int _i = 0; _i < 2; ++_i) \
;         __builtin_amdgcn_global_load_lds((const unsigned*)((const char*)(gbase) + (voff)[_i]), (PG8_LAS unsigned*)(lds + (bufoff) + ldsw + _i * 8192), 16, 0, 0); } while (0)
; #define PG8_LDA(dst, b, h) do { _Pragma("unroll") for (int m = 0; m < 4; ++m) _Pragma("unroll") for (int k = 0; k < 2; ++k) dst[m][k] = *(const PG8_LAS bf16x8*)(lds + PG8_SA(b, h) + aoff + m * 2048 + k * 1024); } while (0)
; #define PG8_MMA(ai, bj, At, Bt) do { __builtin_amdgcn_s_setprio(1); _Pragma("unroll") for (int m = 0; m < 4; ++m) _Pragma("unroll") for (int n = 0; n < 2; ++n) _Pragma("unroll") for (int k = 0; k < 2; ++k) \
;         acc[ai][bj][m][n] = __builtin_amdgcn_mfma_f32_16x16x32_bf16(Bt[n][k], At[m][k], acc[ai][bj][m][n], 0, 0, 0); __builtin_amdgcn_s_setprio(0); } while (0)
; #define PG8_WAIT_V(n) asm volatile("s_waitcnt vmcnt(" #n ")" ::: "memory")
; #define PG8_WAIT_L(n) do { asm volatile("s_waitcnt lgkmcnt(" #n ")" ::: "memory"); __builtin_amdgcn_s_waitcnt(0xC07F); } while (0)
; #define PG8_BAR __builtin_amdgcn_s_barrier()
; #define PG8_SCHED __builtin_amdgcn_sched_barrier(0)
; template <class Epi, class Sched, bool SEG3 = false>
; __device__ __forceinline__ void gemm_phase(PG8_LAS unsigned char* lds, const Gemm g, const Sched& S, const Epi& E) {
;     ...
;             PG8_LDA(At, 1, 1); PG8_STAGE(PG8_SB(1, 0), b3, voffB); PG8_STAGE(PG8_SB(1, 1), b3 + hsB, voffB); PG8_STAGE(PG8_SA(1, 0), a3, voffA);
;             PG8_WAIT_V(8); PG8_WAIT_L(0); PG8_BAR; if (cur.half != 0) { PG8_MMA(1, 0, At, B0); PG8_MMA(1, 1, At, B1); } PG8_BAR; PG8_SCHED;
;         }
	s_mov_b32 m0, s81
	v_lshl_add_u64 v[142:143], v[142:143], 0, s[6:7]
	s_add_u32 s0, s40, 0x40080
	ds_read_b128 v[184:187], v151 offset:49152
	ds_read_b128 v[188:191], v151 offset:50176
	ds_read_b128 v[192:195], v151 offset:51200
	ds_read_b128 v[196:199], v151 offset:52224
	ds_read_b128 v[200:203], v151 offset:53248
	ds_read_b128 v[204:207], v151 offset:54272
	ds_read_b128 v[208:211], v151 offset:55296
	ds_read_b128 v[212:215], v151 offset:56320
	global_load_lds_dwordx4 v[142:143], off
	v_lshl_add_u64 v[142:143], v[216:217], 0, s[6:7]
	s_mov_b32 m0, s82
	s_addc_u32 s1, s41, 0
	global_load_lds_dwordx4 v[142:143], off
	s_mov_b32 m0, s85
	v_lshl_add_u64 v[142:143], s[0:1], 0, v[130:131]
	global_load_lds_dwordx4 v[142:143], off
	s_mov_b32 m0, s86
	v_lshl_add_u64 v[142:143], s[0:1], 0, v[136:137]
	global_load_lds_dwordx4 v[142:143], off
	s_mov_b32 m0, s83
	v_lshl_add_u64 v[142:143], v[218:219], 0, s[6:7]
	global_load_lds_dwordx4 v[142:143], off
	s_mov_b32 m0, s84
	v_lshl_add_u64 v[142:143], v[220:221], 0, s[6:7]
	global_load_lds_dwordx4 v[142:143], off
	s_waitcnt vmcnt(8) lgkmcnt(0)
	s_barrier
	s_setprio 1
	v_mfma_f32_16x16x32_bf16 v[62:65], v[152:155], v[184:187], v[62:65]
	v_mfma_f32_16x16x32_bf16 v[58:61], v[160:163], v[184:187], v[58:61]
	v_mfma_f32_16x16x32_bf16 v[46:49], v[152:155], v[192:195], v[46:49]
	v_mfma_f32_16x16x32_bf16 v[42:45], v[160:163], v[192:195], v[42:45]
	v_mfma_f32_16x16x32_bf16 v[30:33], v[152:155], v[200:203], v[30:33]
	v_mfma_f32_16x16x32_bf16 v[26:29], v[160:163], v[200:203], v[26:29]
	v_mfma_f32_16x16x32_bf16 v[14:17], v[152:155], v[208:211], v[14:17]
	v_mfma_f32_16x16x32_bf16 v[10:13], v[160:163], v[208:211], v[10:13]
	v_mfma_f32_16x16x32_bf16 v[62:65], v[156:159], v[188:191], v[62:65]
	v_mfma_f32_16x16x32_bf16 v[58:61], v[164:167], v[188:191], v[58:61]
	v_mfma_f32_16x16x32_bf16 v[46:49], v[156:159], v[196:199], v[46:49]
	v_mfma_f32_16x16x32_bf16 v[42:45], v[164:167], v[196:199], v[42:45]
	v_mfma_f32_16x16x32_bf16 v[30:33], v[156:159], v[204:207], v[30:33]
	v_mfma_f32_16x16x32_bf16 v[26:29], v[164:167], v[204:207], v[26:29]
	v_mfma_f32_16x16x32_bf16 v[14:17], v[156:159], v[212:215], v[14:17]
	v_mfma_f32_16x16x32_bf16 v[10:13], v[164:167], v[212:215], v[10:13]
	s_setprio 0
	s_setprio 1
	v_mfma_f32_16x16x32_bf16 v[54:57], v[168:171], v[184:187], v[54:57]
	v_mfma_f32_16x16x32_bf16 v[50:53], v[176:179], v[184:187], v[50:53]
	v_mfma_f32_16x16x32_bf16 v[38:41], v[168:171], v[192:195], v[38:41]
	v_mfma_f32_16x16x32_bf16 v[34:37], v[176:179], v[192:195], v[34:37]
	v_mfma_f32_16x16x32_bf16 v[22:25], v[168:171], v[200:203], v[22:25]
	v_mfma_f32_16x16x32_bf16 v[18:21], v[176:179], v[200:203], v[18:21]
	v_mfma_f32_16x16x32_bf16 v[6:9], v[168:171], v[208:211], v[6:9]
	v_mfma_f32_16x16x32_bf16 v[2:5], v[176:179], v[208:211], v[2:5]
	v_mfma_f32_16x16x32_bf16 v[54:57], v[172:175], v[188:191], v[54:57]
	v_mfma_f32_16x16x32_bf16 v[50:53], v[180:183], v[188:191], v[50:53]
	v_mfma_f32_16x16x32_bf16 v[38:41], v[172:175], v[196:199], v[38:41]
	v_mfma_f32_16x16x32_bf16 v[34:37], v[180:183], v[196:199], v[34:37]
	v_mfma_f32_16x16x32_bf16 v[22:25], v[172:175], v[204:207], v[22:25]
	v_mfma_f32_16x16x32_bf16 v[18:21], v[180:183], v[204:207], v[18:21]
	v_mfma_f32_16x16x32_bf16 v[6:9], v[172:175], v[212:215], v[6:9]
	v_mfma_f32_16x16x32_bf16 v[2:5], v[180:183], v[212:215], v[2:5]
	s_setprio 0
	s_barrier
	s_add_u32 s38, s38, 0x100
	s_addc_u32 s39, s39, 0
	s_add_u32 s91, s91, 0x100
	s_addc_u32 s92, s92, 0
	s_cmp_ge_i32 s93, s4
	s_mov_b32 s40, s93
	s_cbranch_scc0 .LBB0_313
	s_and_b64 vcc, exec, s[24:25]
	s_cbranch_vccz .LBB0_316

; #define PG8_STAGE(bufoff, gbase, voff) do { _Pragma("unroll") for (int _i = 0; _i < 2; ++_i) \
;         __builtin_amdgcn_global_load_lds((const unsigned*)((const char*)(gbase) + (voff)[_i]), (PG8_LAS unsigned*)(lds + (bufoff) + ldsw + _i * 8192), 16, 0, 0); } while (0)
; #define PG8_LDA(dst, b, h) do { _Pragma("unroll") for (int m = 0; m < 4; ++m) _Pragma("unroll") for (int k = 0; k < 2; ++k) dst[m][k] = *(const PG8_LAS bf16x8*)(lds + PG8_SA(b, h) + aoff + m * 2048 + k * 1024); } while (0)
; #define PG8_LDB(dst, b, h) do { _Pragma("unroll") for (int n = 0; n < 2; ++n) _Pragma("unroll") for (int k = 0; k < 2; ++k) dst[n][k] = *(const PG8_LAS bf16x8*)(lds + PG8_SB(b, h) + boff + n * 2048 + k * 1024); } while (0)
; #define PG8_MMA(ai, bj, At, Bt) do { __builtin_amdgcn_s_setprio(1); _Pragma("unroll") for (int m = 0; m < 4; ++m) _Pragma("unroll") for (int n = 0; n < 2; ++n) _Pragma("unroll") for (int k = 0; k < 2; ++k) \
;         acc[ai][bj][m][n] = __builtin_amdgcn_mfma_f32_16x16x32_bf16(Bt[n][k], At[m][k], acc[ai][bj][m][n], 0, 0, 0); __builtin_amdgcn_s_setprio(0); } while (0)
; #define PG8_WAIT_V(n) asm volatile("s_waitcnt vmcnt(" #n ")" ::: "memory")
; #define PG8_WAIT_L(n) do { asm volatile("s_waitcnt lgkmcnt(" #n ")" ::: "memory"); __builtin_amdgcn_s_waitcnt(0xC07F); } while (0)
; #define PG8_BAR __builtin_amdgcn_s_barrier()
; #define PG8_SCHED __builtin_amdgcn_sched_barrier(0)
; template <class Epi, class Sched, bool SEG3 = false>
; __device__ __forceinline__ void gemm_phase(PG8_LAS unsigned char* lds, const Gemm g, const Sched& S, const Epi& E) {
;     ...
;             const char* a1 = cA + (size_t)(t + 1) * kstep;
;             const char* a2 = last ? nA : cA + (size_t)(t + 2) * kstep; const char* b2 = last ? nB : cB + (size_t)(t + 2) * kstep;
;             const char* a3 = a2 + kstep; const char* b3 = b2 + kstep;
;             PG8_LDB(B0, 0, 0); PG8_LDB(B1, 0, 1); PG8_SCHED; PG8_LDA(At, 0, 0); PG8_STAGE(PG8_SA(1, 1), a1 + hsA, voffA);
;             PG8_WAIT_V(8); PG8_WAIT_L(0); PG8_BAR; if (cur.half != 1) { PG8_MMA(0, 0, At, B0); PG8_MMA(0, 1, At, B1); } PG8_BAR; PG8_SCHED;
;             PG8_LDA(At, 0, 1); PG8_STAGE(PG8_SB(0, 0), b2, voffB); PG8_STAGE(PG8_SB(0, 1), b2 + hsB, voffB); PG8_STAGE(PG8_SA(0, 0), a2, voffA);
;             PG8_WAIT_V(8); PG8_WAIT_L(0); PG8_BAR; if (cur.half != 0) { PG8_MMA(1, 0, At, B0); PG8_MMA(1, 1, At, B1); } PG8_BAR; PG8_SCHED;
.LBB0_437:
	s_add_u32 s6, s38, 0xfffc0080
	s_addc_u32 s7, s39, -1
	s_cmp_eq_u32 s65, s77
	s_cselect_b32 s43, s19, s7
	s_cselect_b32 s42, s21, s6
	s_cselect_b32 s41, s75, s79
	s_cselect_b32 s40, s76, s78
	s_barrier
	s_mov_b32 m0, s29
	v_lshl_add_u64 v[210:211], s[40:41], 0, v[196:197]
	s_add_u32 s6, s40, 0x40000
	ds_read_b128 v[186:189], v223 offset:16384
	ds_read_b128 v[190:193], v223 offset:17408
	ds_read_b128 v[178:181], v223 offset:18432
	ds_read_b128 v[182:185], v223 offset:19456
	ds_read_b128 v[170:173], v223 offset:20480
	ds_read_b128 v[174:177], v223 offset:21504
	ds_read_b128 v[162:165], v223 offset:22528
	ds_read_b128 v[166:169], v223 offset:23552
	global_load_lds_dwordx4 v[210:211], off
	v_lshl_add_u64 v[212:213], s[40:41], 0, v[200:201]
	s_mov_b32 m0, s31
	s_addc_u32 s7, s41, 0
	global_load_lds_dwordx4 v[212:213], off
	v_lshl_add_u64 v[214:215], s[6:7], 0, v[196:197]
	s_mov_b32 m0, s48
	v_lshl_add_u64 v[216:217], s[42:43], 0, v[198:199]
	global_load_lds_dwordx4 v[214:215], off
	v_lshl_add_u64 v[214:215], s[6:7], 0, v[200:201]
	s_mov_b32 m0, s49
	v_cndmask_b32_e64 v227, 0, 1, s[36:37]
	global_load_lds_dwordx4 v[214:215], off
	v_lshl_add_u64 v[214:215], s[42:43], 0, v[194:195]
	s_mov_b32 m0, s50
	v_cmp_ne_u32_e64 s[6:7], 1, v227
	global_load_lds_dwordx4 v[214:215], off
	s_mov_b32 m0, s51
	s_andn2_b64 vcc, exec, s[36:37]
	global_load_lds_dwordx4 v[216:217], off
	s_waitcnt vmcnt(8) lgkmcnt(0)
	s_barrier
	s_cbranch_vccnz .LBB0_439
	s_setprio 1
	v_mfma_f32_16x16x32_bf16 v[74:77], v[146:149], v[186:189], v[74:77]
	v_mfma_f32_16x16x32_bf16 v[66:69], v[154:157], v[186:189], v[66:69]
	v_mfma_f32_16x16x32_bf16 v[58:61], v[146:149], v[178:181], v[58:61]
	v_mfma_f32_16x16x32_bf16 v[50:53], v[154:157], v[178:181], v[50:53]
	v_mfma_f32_16x16x32_bf16 v[42:45], v[146:149], v[170:173], v[42:45]
	v_mfma_f32_16x16x32_bf16 v[34:37], v[154:157], v[170:173], v[34:37]
	v_mfma_f32_16x16x32_bf16 v[26:29], v[146:149], v[162:165], v[26:29]
	v_mfma_f32_16x16x32_bf16 v[22:25], v[154:157], v[162:165], v[22:25]
	v_mfma_f32_16x16x32_bf16 v[74:77], v[150:153], v[190:193], v[74:77]
	v_mfma_f32_16x16x32_bf16 v[66:69], v[158:161], v[190:193], v[66:69]
	v_mfma_f32_16x16x32_bf16 v[58:61], v[150:153], v[182:185], v[58:61]
	v_mfma_f32_16x16x32_bf16 v[50:53], v[158:161], v[182:185], v[50:53]
	v_mfma_f32_16x16x32_bf16 v[42:45], v[150:153], v[174:177], v[42:45]
	v_mfma_f32_16x16x32_bf16 v[34:37], v[158:161], v[174:177], v[34:37]
	v_mfma_f32_16x16x32_bf16 v[26:29], v[150:153], v[166:169], v[26:29]
	v_mfma_f32_16x16x32_bf16 v[22:25], v[158:161], v[166:169], v[22:25]
	s_setprio 0
	s_setprio 1
	v_mfma_f32_16x16x32_bf16 v[78:81], v[2:5], v[186:189], v[78:81]
	v_mfma_f32_16x16x32_bf16 v[62:65], v[2:5], v[178:181], v[62:65]
	v_mfma_f32_16x16x32_bf16 v[46:49], v[2:5], v[170:173], v[46:49]
	v_mfma_f32_16x16x32_bf16 v[2:5], v[2:5], v[162:165], v[30:33]
	v_mfma_f32_16x16x32_bf16 v[70:73], v[98:101], v[186:189], v[70:73]
	v_mfma_f32_16x16x32_bf16 v[54:57], v[98:101], v[178:181], v[54:57]
	v_mfma_f32_16x16x32_bf16 v[38:41], v[98:101], v[170:173], v[38:41]
	v_mfma_f32_16x16x32_bf16 v[30:33], v[6:9], v[166:169], v[2:5]
	v_mfma_f32_16x16x32_bf16 v[2:5], v[98:101], v[162:165], v[18:21]
	v_mfma_f32_16x16x32_bf16 v[78:81], v[6:9], v[190:193], v[78:81]
	v_mfma_f32_16x16x32_bf16 v[70:73], v[102:105], v[190:193], v[70:73]
	v_mfma_f32_16x16x32_bf16 v[62:65], v[6:9], v[182:185], v[62:65]
	v_mfma_f32_16x16x32_bf16 v[54:57], v[102:105], v[182:185], v[54:57]
	v_mfma_f32_16x16x32_bf16 v[46:49], v[6:9], v[174:177], v[46:49]
	v_mfma_f32_16x16x32_bf16 v[38:41], v[102:105], v[174:177], v[38:41]
	v_mfma_f32_16x16x32_bf16 v[18:21], v[102:105], v[166:169], v[2:5]
	s_setprio 0
; #define PG8_STAGE(bufoff, gbase, voff) do { _Pragma("unroll") for (int _i = 0; _i < 2; ++_i) \
;         __builtin_amdgcn_global_load_lds((const unsigned*)((const char*)(gbase) + (voff)[_i]), (PG8_LAS unsigned*)(lds + (bufoff) + ldsw + _i * 8192), 16, 0, 0); } while (0)
; #define PG8_LDA(dst, b, h) do { _Pragma("unroll") for (int m = 0; m < 4; ++m) _Pragma("unroll") for (int k = 0; k < 2; ++k) dst[m][k] = *(const PG8_LAS bf16x8*)(lds + PG8_SA(b, h) + aoff + m * 2048 + k * 1024); } while (0)
; #define PG8_LDB(dst, b, h) do { _Pragma("unroll") for (int n = 0; n < 2; ++n) _Pragma("unroll") for (int k = 0; k < 2; ++k) dst[n][k] = *(const PG8_LAS bf16x8*)(lds + PG8_SB(b, h) + boff + n * 2048 + k * 1024); } while (0)
; #define PG8_MMA(ai, bj, At, Bt) do { __builtin_amdgcn_s_setprio(1); _Pragma("unroll") for (int m = 0; m < 4; ++m) _Pragma("unroll") for (int n = 0; n < 2; ++n) _Pragma("unroll") for (int k = 0; k < 2; ++k) \
;         acc[ai][bj][m][n] = __builtin_amdgcn_mfma_f32_16x16x32_bf16(Bt[n][k], At[m][k], acc[ai][bj][m][n], 0, 0, 0); __builtin_amdgcn_s_setprio(0); } while (0)
; #define PG8_WAIT_V(n) asm volatile("s_waitcnt vmcnt(" #n ")" ::: "memory")
; #define PG8_WAIT_L(n) do { asm volatile("s_waitcnt lgkmcnt(" #n ")" ::: "memory"); __builtin_amdgcn_s_waitcnt(0xC07F); } while (0)
; #define PG8_BAR __builtin_amdgcn_s_barrier()
; #define PG8_SCHED __builtin_amdgcn_sched_barrier(0)
; template <class Epi, class Sched, bool SEG3 = false>
; __device__ __forceinline__ void gemm_phase(PG8_LAS unsigned char* lds, const Gemm g, const Sched& S, const Epi& E) {
;     ...
;             PG8_LDB(B0, 1, 0); PG8_LDB(B1, 1, 1); PG8_SCHED; PG8_LDA(At, 1, 0); PG8_STAGE(PG8_SA(0, 1), a2 + hsA, voffA);
;             PG8_WAIT_V(8); PG8_WAIT_L(0); PG8_BAR; if (cur.half != 1) { PG8_MMA(0, 0, At, B0); PG8_MMA(0, 1, At, B1); } PG8_BAR; PG8_SCHED;
;             PG8_LDA(At, 1, 1); PG8_STAGE(PG8_SB(1, 0), b3, voffB); PG8_STAGE(PG8_SB(1, 1), b3 + hsB, voffB); PG8_STAGE(PG8_SA(1, 0), a3, voffA);
;             PG8_WAIT_V(8); PG8_WAIT_L(0); PG8_BAR; if (cur.half != 0) { PG8_MMA(1, 0, At, B0); PG8_MMA(1, 1, At, B1); } PG8_BAR; PG8_SCHED;
.LBB0_439:
	s_barrier
	s_nop 0
	v_add_u32_e32 v2, s56, v219
	v_add_u32_e32 v102, s61, v219
	ds_read_b128 v[146:149], v2
	ds_read_b128 v[150:153], v2 offset:1024
	ds_read_b128 v[154:157], v2 offset:2048
	ds_read_b128 v[158:161], v2 offset:3072
	ds_read_b128 v[2:5], v102
	ds_read_b128 v[6:9], v102 offset:1024
	ds_read_b128 v[98:101], v102 offset:2048
	ds_read_b128 v[102:105], v102 offset:3072
	s_add_u32 s42, s42, 0x40000
	s_addc_u32 s43, s43, 0
	s_mov_b32 m0, s52
	v_lshl_add_u64 v[228:229], s[42:43], 0, v[194:195]
	ds_read_b128 v[186:189], v223 offset:32768
	ds_read_b128 v[190:193], v223 offset:33792
	ds_read_b128 v[178:181], v223 offset:34816
	ds_read_b128 v[182:185], v223 offset:35840
	ds_read_b128 v[170:173], v223 offset:36864
	ds_read_b128 v[174:177], v223 offset:37888
	ds_read_b128 v[162:165], v223 offset:38912
	ds_read_b128 v[166:169], v223 offset:39936
	global_load_lds_dwordx4 v[228:229], off
	v_lshl_add_u64 v[228:229], s[42:43], 0, v[198:199]
	s_mov_b32 m0, s53
	s_and_b64 vcc, exec, s[4:5]
	global_load_lds_dwordx4 v[228:229], off
	s_waitcnt vmcnt(8) lgkmcnt(0)
	s_barrier
	s_cbranch_vccnz .LBB0_441
	s_setprio 1
	v_mfma_f32_16x16x32_bf16 v[138:141], v[146:149], v[186:189], v[138:141]
	v_mfma_f32_16x16x32_bf16 v[130:133], v[154:157], v[186:189], v[130:133]
	v_mfma_f32_16x16x32_bf16 v[122:125], v[146:149], v[178:181], v[122:125]
	v_mfma_f32_16x16x32_bf16 v[114:117], v[154:157], v[178:181], v[114:117]
	v_mfma_f32_16x16x32_bf16 v[106:109], v[146:149], v[170:173], v[106:109]
	v_mfma_f32_16x16x32_bf16 v[10:13], v[154:157], v[170:173], v[10:13]
	v_mfma_f32_16x16x32_bf16 v[90:93], v[146:149], v[162:165], v[90:93]
	v_mfma_f32_16x16x32_bf16 v[82:85], v[154:157], v[162:165], v[82:85]
	v_mfma_f32_16x16x32_bf16 v[138:141], v[150:153], v[190:193], v[138:141]
	v_mfma_f32_16x16x32_bf16 v[130:133], v[158:161], v[190:193], v[130:133]
	v_mfma_f32_16x16x32_bf16 v[122:125], v[150:153], v[182:185], v[122:125]
	v_mfma_f32_16x16x32_bf16 v[114:117], v[158:161], v[182:185], v[114:117]
	v_mfma_f32_16x16x32_bf16 v[106:109], v[150:153], v[174:177], v[106:109]
	v_mfma_f32_16x16x32_bf16 v[10:13], v[158:161], v[174:177], v[10:13]
	v_mfma_f32_16x16x32_bf16 v[90:93], v[150:153], v[166:169], v[90:93]
	v_mfma_f32_16x16x32_bf16 v[82:85], v[158:161], v[166:169], v[82:85]
	s_setprio 0
	s_setprio 1
	v_mfma_f32_16x16x32_bf16 v[142:145], v[2:5], v[186:189], v[142:145]
	v_mfma_f32_16x16x32_bf16 v[134:137], v[98:101], v[186:189], v[134:137]
	v_mfma_f32_16x16x32_bf16 v[126:129], v[2:5], v[178:181], v[126:129]
	v_mfma_f32_16x16x32_bf16 v[118:121], v[98:101], v[178:181], v[118:121]
	v_mfma_f32_16x16x32_bf16 v[110:113], v[2:5], v[170:173], v[110:113]
	v_mfma_f32_16x16x32_bf16 v[14:17], v[98:101], v[170:173], v[14:17]
	v_mfma_f32_16x16x32_bf16 v[94:97], v[2:5], v[162:165], v[94:97]
	v_mfma_f32_16x16x32_bf16 v[86:89], v[98:101], v[162:165], v[86:89]
	v_mfma_f32_16x16x32_bf16 v[142:145], v[6:9], v[190:193], v[142:145]
	v_mfma_f32_16x16x32_bf16 v[134:137], v[102:105], v[190:193], v[134:137]
	v_mfma_f32_16x16x32_bf16 v[126:129], v[6:9], v[182:185], v[126:129]
	v_mfma_f32_16x16x32_bf16 v[118:121], v[102:105], v[182:185], v[118:121]
	v_mfma_f32_16x16x32_bf16 v[110:113], v[6:9], v[174:177], v[110:113]
	v_mfma_f32_16x16x32_bf16 v[14:17], v[102:105], v[174:177], v[14:17]
	v_mfma_f32_16x16x32_bf16 v[94:97], v[6:9], v[166:169], v[94:97]
	v_mfma_f32_16x16x32_bf16 v[86:89], v[102:105], v[166:169], v[86:89]
	s_setprio 0
.LBB0_441:
	s_barrier
	s_mov_b32 m0, s57
	v_lshl_add_u64 v[210:211], v[210:211], 0, s[12:13]
	s_add_u32 s4, s40, 0x40080
	ds_read_b128 v[186:189], v223 offset:49152
	ds_read_b128 v[190:193], v223 offset:50176
	ds_read_b128 v[178:181], v223 offset:51200
	ds_read_b128 v[182:185], v223 offset:52224
	ds_read_b128 v[170:173], v223 offset:53248
	ds_read_b128 v[174:177], v223 offset:54272
	ds_read_b128 v[162:165], v223 offset:55296
	ds_read_b128 v[166:169], v223 offset:56320
	global_load_lds_dwordx4 v[210:211], off
	v_lshl_add_u64 v[210:211], v[212:213], 0, s[12:13]
	s_mov_b32 m0, s58
	s_addc_u32 s5, s41, 0
	global_load_lds_dwordx4 v[210:211], off
	v_lshl_add_u64 v[210:211], s[4:5], 0, v[196:197]
	s_mov_b32 m0, s62
	s_and_b64 vcc, exec, s[6:7]
	global_load_lds_dwordx4 v[210:211], off
	s_mov_b32 m0, s63
	v_lshl_add_u64 v[210:211], s[4:5], 0, v[200:201]
	global_load_lds_dwordx4 v[210:211], off
	s_mov_b32 m0, s59
	v_lshl_add_u64 v[210:211], v[214:215], 0, s[12:13]
	global_load_lds_dwordx4 v[210:211], off
	s_mov_b32 m0, s60
	v_lshl_add_u64 v[210:211], v[216:217], 0, s[12:13]
	global_load_lds_dwordx4 v[210:211], off
	s_waitcnt vmcnt(8) lgkmcnt(0)
	s_barrier
	s_cbranch_vccnz .LBB0_434
	s_setprio 1
	v_mfma_f32_16x16x32_bf16 v[74:77], v[146:149], v[186:189], v[74:77]
	v_mfma_f32_16x16x32_bf16 v[66:69], v[154:157], v[186:189], v[66:69]
	v_mfma_f32_16x16x32_bf16 v[58:61], v[146:149], v[178:181], v[58:61]
	v_mfma_f32_16x16x32_bf16 v[50:53], v[154:157], v[178:181], v[50:53]
	v_mfma_f32_16x16x32_bf16 v[42:45], v[146:149], v[170:173], v[42:45]
	v_mfma_f32_16x16x32_bf16 v[34:37], v[154:157], v[170:173], v[34:37]
	v_mfma_f32_16x16x32_bf16 v[26:29], v[146:149], v[162:165], v[26:29]
	v_mfma_f32_16x16x32_bf16 v[22:25], v[154:157], v[162:165], v[22:25]
	v_mfma_f32_16x16x32_bf16 v[74:77], v[150:153], v[190:193], v[74:77]
	v_mfma_f32_16x16x32_bf16 v[66:69], v[158:161], v[190:193], v[66:69]
	v_mfma_f32_16x16x32_bf16 v[58:61], v[150:153], v[182:185], v[58:61]
	v_mfma_f32_16x16x32_bf16 v[50:53], v[158:161], v[182:185], v[50:53]
	v_mfma_f32_16x16x32_bf16 v[42:45], v[150:153], v[174:177], v[42:45]
	v_mfma_f32_16x16x32_bf16 v[34:37], v[158:161], v[174:177], v[34:37]
	v_mfma_f32_16x16x32_bf16 v[26:29], v[150:153], v[166:169], v[26:29]
	v_mfma_f32_16x16x32_bf16 v[22:25], v[158:161], v[166:169], v[22:25]
	s_setprio 0
	s_setprio 1
	v_mfma_f32_16x16x32_bf16 v[78:81], v[2:5], v[186:189], v[78:81]
	v_mfma_f32_16x16x32_bf16 v[62:65], v[2:5], v[178:181], v[62:65]
	v_mfma_f32_16x16x32_bf16 v[46:49], v[2:5], v[170:173], v[46:49]
	v_mfma_f32_16x16x32_bf16 v[2:5], v[2:5], v[162:165], v[30:33]
	v_mfma_f32_16x16x32_bf16 v[70:73], v[98:101], v[186:189], v[70:73]
	v_mfma_f32_16x16x32_bf16 v[54:57], v[98:101], v[178:181], v[54:57]
	v_mfma_f32_16x16x32_bf16 v[38:41], v[98:101], v[170:173], v[38:41]
	v_mfma_f32_16x16x32_bf16 v[30:33], v[6:9], v[166:169], v[2:5]
	v_mfma_f32_16x16x32_bf16 v[2:5], v[98:101], v[162:165], v[18:21]
	v_mfma_f32_16x16x32_bf16 v[78:81], v[6:9], v[190:193], v[78:81]
	v_mfma_f32_16x16x32_bf16 v[70:73], v[102:105], v[190:193], v[70:73]
	v_mfma_f32_16x16x32_bf16 v[62:65], v[6:9], v[182:185], v[62:65]
	v_mfma_f32_16x16x32_bf16 v[54:57], v[102:105], v[182:185], v[54:57]
	v_mfma_f32_16x16x32_bf16 v[46:49], v[6:9], v[174:177], v[46:49]
	v_mfma_f32_16x16x32_bf16 v[38:41], v[102:105], v[174:177], v[38:41]
	v_mfma_f32_16x16x32_bf16 v[18:21], v[102:105], v[166:169], v[2:5]
	s_setprio 0
	s_branch .LBB0_434

; #define PG8_STAGE(bufoff, gbase, voff) do { _Pragma("unroll") for (int _i = 0; _i < 2; ++_i) \
;         __builtin_amdgcn_global_load_lds((const unsigned*)((const char*)(gbase) + (voff)[_i]), (PG8_LAS unsigned*)(lds + (bufoff) + ldsw + _i * 8192), 16, 0, 0); } while (0)
; #define PG8_LDA(dst, b, h) do { _Pragma("unroll") for (int m = 0; m < 4; ++m) _Pragma("unroll") for (int k = 0; k < 2; ++k) dst[m][k] = *(const PG8_LAS bf16x8*)(lds + PG8_SA(b, h) + aoff + m * 2048 + k * 1024); } while (0)
; #define PG8_LDB(dst, b, h) do { _Pragma("unroll") for (int n = 0; n < 2; ++n) _Pragma("unroll") for (int k = 0; k < 2; ++k) dst[n][k] = *(const PG8_LAS bf16x8*)(lds + PG8_SB(b, h) + boff + n * 2048 + k * 1024); } while (0)
; #define PG8_MMA(ai, bj, At, Bt) do { __builtin_amdgcn_s_setprio(1); _Pragma("unroll") for (int m = 0; m < 4; ++m) _Pragma("unroll") for (int n = 0; n < 2; ++n) _Pragma("unroll") for (int k = 0; k < 2; ++k) \
;         acc[ai][bj][m][n] = __builtin_amdgcn_mfma_f32_16x16x32_bf16(Bt[n][k], At[m][k], acc[ai][bj][m][n], 0, 0, 0); __builtin_amdgcn_s_setprio(0); } while (0)
; #define PG8_WAIT_V(n) asm volatile("s_waitcnt vmcnt(" #n ")" ::: "memory")
; #define PG8_WAIT_L(n) do { asm volatile("s_waitcnt lgkmcnt(" #n ")" ::: "memory"); __builtin_amdgcn_s_waitcnt(0xC07F); } while (0)
; #define PG8_BAR __builtin_amdgcn_s_barrier()
; template <class Epi, class Sched, bool SEG3 = false>
; __device__ __forceinline__ void gemm_phase(PG8_LAS unsigned char* lds, const Gemm g, const Sched& S, const Epi& E) {
;     ...
;             const bool last = (t == ntc - 2);
;             const char* a1 = cA + (size_t)(t + 1) * kstep;
;             const char* a2 = last ? nA : cA + (size_t)(t + 2) * kstep; const char* b2 = last ? nB : cB + (size_t)(t + 2) * kstep;
;             const char* a3 = a2 + kstep; const char* b3 = b2 + kstep;
;             PG8_LDB(B0, 0, 0); PG8_LDB(B1, 0, 1); PG8_SCHED; PG8_LDA(At, 0, 0); PG8_STAGE(PG8_SA(1, 1), a1 + hsA, voffA);
;             PG8_WAIT_V(8); PG8_WAIT_L(0); PG8_BAR; if (cur.half != 1) { PG8_MMA(0, 0, At, B0); PG8_MMA(0, 1, At, B1); } PG8_BAR; PG8_SCHED;
;             PG8_LDA(At, 0, 1); PG8_STAGE(PG8_SB(0, 0), b2, voffB); PG8_STAGE(PG8_SB(0, 1), b2 + hsB, voffB); PG8_STAGE(PG8_SA(0, 0), a2, voffA);
;             PG8_WAIT_V(8); PG8_WAIT_L(0); PG8_BAR; if (cur.half != 0) { PG8_MMA(1, 0, At, B0); PG8_MMA(1, 1, At, B1); } PG8_BAR; PG8_SCHED;
.LBB0_554:
	ds_read_b128 v[98:101], v199
	ds_read_b128 v[110:113], v199 offset:1024
	ds_read_b128 v[122:125], v199 offset:2048
	ds_read_b128 v[134:137], v199 offset:3072
	ds_read_b128 v[146:149], v200
	ds_read_b128 v[150:153], v200 offset:1024
	ds_read_b128 v[170:173], v200 offset:2048
	ds_read_b128 v[174:177], v200 offset:3072
	s_add_i32 s68, s34, 2
	s_add_u32 s30, s28, 0x100
	s_addc_u32 s31, s29, 0
	s_cmp_eq_u32 s58, s34
	s_cselect_b32 s34, s26, s66
	s_cselect_b32 s37, s9, s31
	s_cselect_b32 s36, s8, s30
	s_cselect_b32 s35, s27, s67
	v_lshl_add_u64 v[218:219], s[28:29], 0, v[162:163]
	s_add_i32 m0, s46, 0xc000
	ds_read_b128 v[178:181], v201
	ds_read_b128 v[182:185], v201 offset:1024
	ds_read_b128 v[186:189], v201 offset:2048
	ds_read_b128 v[190:193], v201 offset:3072
	ds_read_b128 v[194:197], v201 offset:4096
	ds_read_b128 v[206:209], v201 offset:5120
	ds_read_b128 v[210:213], v201 offset:6144
	ds_read_b128 v[214:217], v201 offset:7168
	global_load_lds_dwordx4 v[218:219], off
	s_add_i32 m0, s46, 0xe000
	v_lshl_add_u64 v[218:219], s[28:29], 0, v[164:165]
	global_load_lds_dwordx4 v[218:219], off
	s_waitcnt vmcnt(8) lgkmcnt(0)
	s_barrier
	s_setprio 1
	v_mfma_f32_16x16x32_bf16 v[142:145], v[98:101], v[178:181], v[142:145]
	v_mfma_f32_16x16x32_bf16 v[138:141], v[122:125], v[178:181], v[138:141]
	v_mfma_f32_16x16x32_bf16 v[118:121], v[98:101], v[186:189], v[118:121]
	v_mfma_f32_16x16x32_bf16 v[114:117], v[122:125], v[186:189], v[114:117]
	v_mfma_f32_16x16x32_bf16 v[94:97], v[98:101], v[194:197], v[94:97]
	v_mfma_f32_16x16x32_bf16 v[90:93], v[122:125], v[194:197], v[90:93]
	v_mfma_f32_16x16x32_bf16 v[78:81], v[98:101], v[210:213], v[78:81]
	v_mfma_f32_16x16x32_bf16 v[74:77], v[122:125], v[210:213], v[74:77]
	v_mfma_f32_16x16x32_bf16 v[142:145], v[110:113], v[182:185], v[142:145]
	v_mfma_f32_16x16x32_bf16 v[138:141], v[134:137], v[182:185], v[138:141]
	v_mfma_f32_16x16x32_bf16 v[118:121], v[110:113], v[190:193], v[118:121]
	v_mfma_f32_16x16x32_bf16 v[114:117], v[134:137], v[190:193], v[114:117]
	v_mfma_f32_16x16x32_bf16 v[94:97], v[110:113], v[206:209], v[94:97]
	v_mfma_f32_16x16x32_bf16 v[90:93], v[134:137], v[206:209], v[90:93]
	v_mfma_f32_16x16x32_bf16 v[78:81], v[110:113], v[214:217], v[78:81]
	v_mfma_f32_16x16x32_bf16 v[74:77], v[134:137], v[214:217], v[74:77]
	s_setprio 0
	s_setprio 1
	v_mfma_f32_16x16x32_bf16 v[130:133], v[146:149], v[178:181], v[130:133]
	v_mfma_f32_16x16x32_bf16 v[126:129], v[170:173], v[178:181], v[126:129]
	v_mfma_f32_16x16x32_bf16 v[106:109], v[146:149], v[186:189], v[106:109]
	v_mfma_f32_16x16x32_bf16 v[102:105], v[170:173], v[186:189], v[102:105]
	v_mfma_f32_16x16x32_bf16 v[86:89], v[146:149], v[194:197], v[86:89]
	v_mfma_f32_16x16x32_bf16 v[82:85], v[170:173], v[194:197], v[82:85]
	v_mfma_f32_16x16x32_bf16 v[70:73], v[146:149], v[210:213], v[70:73]
	v_mfma_f32_16x16x32_bf16 v[66:69], v[170:173], v[210:213], v[66:69]
	v_mfma_f32_16x16x32_bf16 v[130:133], v[150:153], v[182:185], v[130:133]
	v_mfma_f32_16x16x32_bf16 v[126:129], v[174:177], v[182:185], v[126:129]
	v_mfma_f32_16x16x32_bf16 v[106:109], v[150:153], v[190:193], v[106:109]
	v_mfma_f32_16x16x32_bf16 v[102:105], v[174:177], v[190:193], v[102:105]
	v_mfma_f32_16x16x32_bf16 v[86:89], v[150:153], v[206:209], v[86:89]
	v_mfma_f32_16x16x32_bf16 v[82:85], v[174:177], v[206:209], v[82:85]
	v_mfma_f32_16x16x32_bf16 v[70:73], v[150:153], v[214:217], v[70:73]
	v_mfma_f32_16x16x32_bf16 v[66:69], v[174:177], v[214:217], v[66:69]
	s_setprio 0
	s_barrier
	s_mov_b32 m0, s42
	v_lshl_add_u64 v[218:219], s[34:35], 0, v[156:157]
	s_add_u32 s28, s34, 0xb0000
	ds_read_b128 v[178:181], v201 offset:16384
	ds_read_b128 v[182:185], v201 offset:17408
	ds_read_b128 v[186:189], v201 offset:18432
	ds_read_b128 v[190:193], v201 offset:19456
	ds_read_b128 v[194:197], v201 offset:20480
	ds_read_b128 v[206:209], v201 offset:21504
	ds_read_b128 v[210:213], v201 offset:22528
	ds_read_b128 v[214:217], v201 offset:23552
	global_load_lds_dwordx4 v[218:219], off
	v_lshl_add_u64 v[220:221], s[34:35], 0, v[160:161]
	s_mov_b32 m0, s43
	s_addc_u32 s29, s35, 0
	global_load_lds_dwordx4 v[220:221], off
	v_lshl_add_u64 v[222:223], s[28:29], 0, v[156:157]
	s_mov_b32 m0, s44
	v_lshl_add_u64 v[224:225], s[36:37], 0, v[158:159]
	global_load_lds_dwordx4 v[222:223], off
	s_mov_b32 m0, s45
	v_lshl_add_u64 v[222:223], s[28:29], 0, v[160:161]
	global_load_lds_dwordx4 v[222:223], off
	s_mov_b32 m0, s46
	v_lshl_add_u64 v[222:223], s[36:37], 0, v[154:155]
	global_load_lds_dwordx4 v[222:223], off
	s_mov_b32 m0, s47
	s_nop 0
	global_load_lds_dwordx4 v[224:225], off
	s_waitcnt vmcnt(8) lgkmcnt(0)
	s_barrier
; #define PG8_STAGE(bufoff, gbase, voff) do { _Pragma("unroll") for (int _i = 0; _i < 2; ++_i) \
;         __builtin_amdgcn_global_load_lds((const unsigned*)((const char*)(gbase) + (voff)[_i]), (PG8_LAS unsigned*)(lds + (bufoff) + ldsw + _i * 8192), 16, 0, 0); } while (0)
; #define PG8_LDA(dst, b, h) do { _Pragma("unroll") for (int m = 0; m < 4; ++m) _Pragma("unroll") for (int k = 0; k < 2; ++k) dst[m][k] = *(const PG8_LAS bf16x8*)(lds + PG8_SA(b, h) + aoff + m * 2048 + k * 1024); } while (0)
; #define PG8_LDB(dst, b, h) do { _Pragma("unroll") for (int n = 0; n < 2; ++n) _Pragma("unroll") for (int k = 0; k < 2; ++k) dst[n][k] = *(const PG8_LAS bf16x8*)(lds + PG8_SB(b, h) + boff + n * 2048 + k * 1024); } while (0)
; #define PG8_MMA(ai, bj, At, Bt) do { __builtin_amdgcn_s_setprio(1); _Pragma("unroll") for (int m = 0; m < 4; ++m) _Pragma("unroll") for (int n = 0; n < 2; ++n) _Pragma("unroll") for (int k = 0; k < 2; ++k) \
;         acc[ai][bj][m][n] = __builtin_amdgcn_mfma_f32_16x16x32_bf16(Bt[n][k], At[m][k], acc[ai][bj][m][n], 0, 0, 0); __builtin_amdgcn_s_setprio(0); } while (0)
; #define PG8_WAIT_V(n) asm volatile("s_waitcnt vmcnt(" #n ")" ::: "memory")
; #define PG8_WAIT_L(n) do { asm volatile("s_waitcnt lgkmcnt(" #n ")" ::: "memory"); __builtin_amdgcn_s_waitcnt(0xC07F); } while (0)
; #define PG8_BAR __builtin_amdgcn_s_barrier()
; #define PG8_SCHED __builtin_amdgcn_sched_barrier(0)
; template <class Epi, class Sched, bool SEG3 = false>
; __device__ __forceinline__ void gemm_phase(PG8_LAS unsigned char* lds, const Gemm g, const Sched& S, const Epi& E) {
;     ...
;             PG8_WAIT_V(8); PG8_WAIT_L(0); PG8_BAR; if (cur.half != 0) { PG8_MMA(1, 0, At, B0); PG8_MMA(1, 1, At, B1); } PG8_BAR; PG8_SCHED;
;             PG8_LDB(B0, 1, 0); PG8_LDB(B1, 1, 1); PG8_SCHED; PG8_LDA(At, 1, 0); PG8_STAGE(PG8_SA(0, 1), a2 + hsA, voffA);
;             PG8_WAIT_V(8); PG8_WAIT_L(0); PG8_BAR; if (cur.half != 1) { PG8_MMA(0, 0, At, B0); PG8_MMA(0, 1, At, B1); } PG8_BAR; PG8_SCHED;
	s_setprio 1
	v_mfma_f32_16x16x32_bf16 v[62:65], v[98:101], v[178:181], v[62:65]
	v_mfma_f32_16x16x32_bf16 v[58:61], v[122:125], v[178:181], v[58:61]
	v_mfma_f32_16x16x32_bf16 v[46:49], v[98:101], v[186:189], v[46:49]
	v_mfma_f32_16x16x32_bf16 v[42:45], v[122:125], v[186:189], v[42:45]
	v_mfma_f32_16x16x32_bf16 v[30:33], v[98:101], v[194:197], v[30:33]
	v_mfma_f32_16x16x32_bf16 v[26:29], v[122:125], v[194:197], v[26:29]
	v_mfma_f32_16x16x32_bf16 v[14:17], v[98:101], v[210:213], v[14:17]
	v_mfma_f32_16x16x32_bf16 v[10:13], v[122:125], v[210:213], v[10:13]
	v_mfma_f32_16x16x32_bf16 v[62:65], v[110:113], v[182:185], v[62:65]
	v_mfma_f32_16x16x32_bf16 v[58:61], v[134:137], v[182:185], v[58:61]
	v_mfma_f32_16x16x32_bf16 v[46:49], v[110:113], v[190:193], v[46:49]
	v_mfma_f32_16x16x32_bf16 v[42:45], v[134:137], v[190:193], v[42:45]
	v_mfma_f32_16x16x32_bf16 v[30:33], v[110:113], v[206:209], v[30:33]
	v_mfma_f32_16x16x32_bf16 v[26:29], v[134:137], v[206:209], v[26:29]
	v_mfma_f32_16x16x32_bf16 v[14:17], v[110:113], v[214:217], v[14:17]
	v_mfma_f32_16x16x32_bf16 v[10:13], v[134:137], v[214:217], v[10:13]
	s_setprio 0
	s_setprio 1
	v_mfma_f32_16x16x32_bf16 v[54:57], v[146:149], v[178:181], v[54:57]
	v_mfma_f32_16x16x32_bf16 v[50:53], v[170:173], v[178:181], v[50:53]
	v_mfma_f32_16x16x32_bf16 v[38:41], v[146:149], v[186:189], v[38:41]
	v_mfma_f32_16x16x32_bf16 v[34:37], v[170:173], v[186:189], v[34:37]
	v_mfma_f32_16x16x32_bf16 v[22:25], v[146:149], v[194:197], v[22:25]
	v_mfma_f32_16x16x32_bf16 v[18:21], v[170:173], v[194:197], v[18:21]
	v_mfma_f32_16x16x32_bf16 v[6:9], v[146:149], v[210:213], v[6:9]
	v_mfma_f32_16x16x32_bf16 v[2:5], v[170:173], v[210:213], v[2:5]
	v_mfma_f32_16x16x32_bf16 v[54:57], v[150:153], v[182:185], v[54:57]
	v_mfma_f32_16x16x32_bf16 v[50:53], v[174:177], v[182:185], v[50:53]
	v_mfma_f32_16x16x32_bf16 v[38:41], v[150:153], v[190:193], v[38:41]
	v_mfma_f32_16x16x32_bf16 v[34:37], v[174:177], v[190:193], v[34:37]
	v_mfma_f32_16x16x32_bf16 v[22:25], v[150:153], v[206:209], v[22:25]
	v_mfma_f32_16x16x32_bf16 v[18:21], v[174:177], v[206:209], v[18:21]
	v_mfma_f32_16x16x32_bf16 v[6:9], v[150:153], v[214:217], v[6:9]
	v_mfma_f32_16x16x32_bf16 v[2:5], v[174:177], v[214:217], v[2:5]
	s_setprio 0
	s_barrier
	ds_read_b128 v[98:101], v202
	ds_read_b128 v[110:113], v202 offset:1024
	ds_read_b128 v[122:125], v202 offset:2048
	ds_read_b128 v[134:137], v202 offset:3072
	ds_read_b128 v[146:149], v203
	ds_read_b128 v[150:153], v203 offset:1024
	ds_read_b128 v[170:173], v203 offset:2048
	ds_read_b128 v[174:177], v203 offset:3072
	s_add_u32 s28, s36, 0xb0000
	s_addc_u32 s29, s37, 0
	s_mov_b32 m0, s48
	v_lshl_add_u64 v[226:227], s[28:29], 0, v[154:155]
	ds_read_b128 v[178:181], v201 offset:32768
	ds_read_b128 v[182:185], v201 offset:33792
	ds_read_b128 v[186:189], v201 offset:34816
	ds_read_b128 v[190:193], v201 offset:35840
	ds_read_b128 v[194:197], v201 offset:36864
	ds_read_b128 v[206:209], v201 offset:37888
	ds_read_b128 v[210:213], v201 offset:38912
	ds_read_b128 v[214:217], v201 offset:39936
	global_load_lds_dwordx4 v[226:227], off
	s_mov_b32 m0, s49
	v_lshl_add_u64 v[226:227], s[28:29], 0, v[158:159]
	global_load_lds_dwordx4 v[226:227], off
	s_waitcnt vmcnt(8) lgkmcnt(0)
	s_barrier
	s_setprio 1
	v_mfma_f32_16x16x32_bf16 v[142:145], v[98:101], v[178:181], v[142:145]
	v_mfma_f32_16x16x32_bf16 v[138:141], v[122:125], v[178:181], v[138:141]
	v_mfma_f32_16x16x32_bf16 v[118:121], v[98:101], v[186:189], v[118:121]
	v_mfma_f32_16x16x32_bf16 v[114:117], v[122:125], v[186:189], v[114:117]
	v_mfma_f32_16x16x32_bf16 v[94:97], v[98:101], v[194:197], v[94:97]
	v_mfma_f32_16x16x32_bf16 v[90:93], v[122:125], v[194:197], v[90:93]
	v_mfma_f32_16x16x32_bf16 v[78:81], v[98:101], v[210:213], v[78:81]
	v_mfma_f32_16x16x32_bf16 v[74:77], v[122:125], v[210:213], v[74:77]
	v_mfma_f32_16x16x32_bf16 v[142:145], v[110:113], v[182:185], v[142:145]
	v_mfma_f32_16x16x32_bf16 v[138:141], v[134:137], v[182:185], v[138:141]
	v_mfma_f32_16x16x32_bf16 v[118:121], v[110:113], v[190:193], v[118:121]
	v_mfma_f32_16x16x32_bf16 v[114:117], v[134:137], v[190:193], v[114:117]
	v_mfma_f32_16x16x32_bf16 v[94:97], v[110:113], v[206:209], v[94:97]
	v_mfma_f32_16x16x32_bf16 v[90:93], v[134:137], v[206:209], v[90:93]
	v_mfma_f32_16x16x32_bf16 v[78:81], v[110:113], v[214:217], v[78:81]
	v_mfma_f32_16x16x32_bf16 v[74:77], v[134:137], v[214:217], v[74:77]
	s_setprio 0
	s_setprio 1
	v_mfma_f32_16x16x32_bf16 v[130:133], v[146:149], v[178:181], v[130:133]
	v_mfma_f32_16x16x32_bf16 v[126:129], v[170:173], v[178:181], v[126:129]
	v_mfma_f32_16x16x32_bf16 v[106:109], v[146:149], v[186:189], v[106:109]
	v_mfma_f32_16x16x32_bf16 v[102:105], v[170:173], v[186:189], v[102:105]
	v_mfma_f32_16x16x32_bf16 v[86:89], v[146:149], v[194:197], v[86:89]
	v_mfma_f32_16x16x32_bf16 v[82:85], v[170:173], v[194:197], v[82:85]
	v_mfma_f32_16x16x32_bf16 v[70:73], v[146:149], v[210:213], v[70:73]
	v_mfma_f32_16x16x32_bf16 v[66:69], v[170:173], v[210:213], v[66:69]
	v_mfma_f32_16x16x32_bf16 v[130:133], v[150:153], v[182:185], v[130:133]
	v_mfma_f32_16x16x32_bf16 v[126:129], v[174:177], v[182:185], v[126:129]
	v_mfma_f32_16x16x32_bf16 v[106:109], v[150:153], v[190:193], v[106:109]
	v_mfma_f32_16x16x32_bf16 v[102:105], v[174:177], v[190:193], v[102:105]
	v_mfma_f32_16x16x32_bf16 v[86:89], v[150:153], v[206:209], v[86:89]
	v_mfma_f32_16x16x32_bf16 v[82:85], v[174:177], v[206:209], v[82:85]
	v_mfma_f32_16x16x32_bf16 v[70:73], v[150:153], v[214:217], v[70:73]
	v_mfma_f32_16x16x32_bf16 v[66:69], v[174:177], v[214:217], v[66:69]
	s_setprio 0
	s_barrier
; #define PG8_STAGE(bufoff, gbase, voff) do { _Pragma("unroll") for (int _i = 0; _i < 2; ++_i) \
;         __builtin_amdgcn_global_load_lds((const unsigned*)((const char*)(gbase) + (voff)[_i]), (PG8_LAS unsigned*)(lds + (bufoff) + ldsw + _i * 8192), 16, 0, 0); } while (0)
; #define PG8_LDA(dst, b, h) do { _Pragma("unroll") for (int m = 0; m < 4; ++m) _Pragma("unroll") for (int k = 0; k < 2; ++k) dst[m][k] = *(const PG8_LAS bf16x8*)(lds + PG8_SA(b, h) + aoff + m * 2048 + k * 1024); } while (0)
; #define PG8_MMA(ai, bj, At, Bt) do { __builtin_amdgcn_s_setprio(1); _Pragma("unroll") for (int m = 0; m < 4; ++m) _Pragma("unroll") for (int n = 0; n < 2; ++n) _Pragma("unroll") for (int k = 0; k < 2; ++k) \
;         acc[ai][bj][m][n] = __builtin_amdgcn_mfma_f32_16x16x32_bf16(Bt[n][k], At[m][k], acc[ai][bj][m][n], 0, 0, 0); __builtin_amdgcn_s_setprio(0); } while (0)
; #define PG8_WAIT_V(n) asm volatile("s_waitcnt vmcnt(" #n ")" ::: "memory")
; #define PG8_WAIT_L(n) do { asm volatile("s_waitcnt lgkmcnt(" #n ")" ::: "memory"); __builtin_amdgcn_s_waitcnt(0xC07F); } while (0)
; #define PG8_BAR __builtin_amdgcn_s_barrier()
; #define PG8_SCHED __builtin_amdgcn_sched_barrier(0)
; template <class Epi, class Sched, bool SEG3 = false>
; __device__ __forceinline__ void gemm_phase(PG8_LAS unsigned char* lds, const Gemm g, const Sched& S, const Epi& E) {
;     ...
;             PG8_LDA(At, 1, 1); PG8_STAGE(PG8_SB(1, 0), b3, voffB); PG8_STAGE(PG8_SB(1, 1), b3 + hsB, voffB); PG8_STAGE(PG8_SA(1, 0), a3, voffA);
;             PG8_WAIT_V(8); PG8_WAIT_L(0); PG8_BAR; if (cur.half != 0) { PG8_MMA(1, 0, At, B0); PG8_MMA(1, 1, At, B1); } PG8_BAR; PG8_SCHED;
;         }
	s_mov_b32 m0, s52
	v_lshl_add_u64 v[218:219], v[218:219], 0, s[20:21]
	s_add_u32 s28, s34, 0xb0080
	ds_read_b128 v[178:181], v201 offset:49152
	ds_read_b128 v[182:185], v201 offset:50176
	ds_read_b128 v[186:189], v201 offset:51200
	ds_read_b128 v[190:193], v201 offset:52224
	ds_read_b128 v[194:197], v201 offset:53248
	ds_read_b128 v[206:209], v201 offset:54272
	ds_read_b128 v[210:213], v201 offset:55296
	ds_read_b128 v[214:217], v201 offset:56320
	global_load_lds_dwordx4 v[218:219], off
	v_lshl_add_u64 v[218:219], v[220:221], 0, s[20:21]
	s_mov_b32 m0, s53
	s_addc_u32 s29, s35, 0
	global_load_lds_dwordx4 v[218:219], off
	s_mov_b32 m0, s56
	v_lshl_add_u64 v[218:219], s[28:29], 0, v[156:157]
	global_load_lds_dwordx4 v[218:219], off
	s_mov_b32 m0, s57
	v_lshl_add_u64 v[218:219], s[28:29], 0, v[160:161]
	global_load_lds_dwordx4 v[218:219], off
	s_mov_b32 m0, s54
	v_lshl_add_u64 v[218:219], v[222:223], 0, s[20:21]
	global_load_lds_dwordx4 v[218:219], off
	s_mov_b32 m0, s55
	v_lshl_add_u64 v[218:219], v[224:225], 0, s[20:21]
	global_load_lds_dwordx4 v[218:219], off
	s_waitcnt vmcnt(8) lgkmcnt(0)
	s_barrier
	s_setprio 1
	v_mfma_f32_16x16x32_bf16 v[62:65], v[98:101], v[178:181], v[62:65]
	v_mfma_f32_16x16x32_bf16 v[58:61], v[122:125], v[178:181], v[58:61]
	v_mfma_f32_16x16x32_bf16 v[46:49], v[98:101], v[186:189], v[46:49]
	v_mfma_f32_16x16x32_bf16 v[42:45], v[122:125], v[186:189], v[42:45]
	v_mfma_f32_16x16x32_bf16 v[30:33], v[98:101], v[194:197], v[30:33]
	v_mfma_f32_16x16x32_bf16 v[26:29], v[122:125], v[194:197], v[26:29]
	v_mfma_f32_16x16x32_bf16 v[14:17], v[98:101], v[210:213], v[14:17]
	v_mfma_f32_16x16x32_bf16 v[10:13], v[122:125], v[210:213], v[10:13]
	v_mfma_f32_16x16x32_bf16 v[62:65], v[110:113], v[182:185], v[62:65]
	v_mfma_f32_16x16x32_bf16 v[58:61], v[134:137], v[182:185], v[58:61]
	v_mfma_f32_16x16x32_bf16 v[46:49], v[110:113], v[190:193], v[46:49]
	v_mfma_f32_16x16x32_bf16 v[42:45], v[134:137], v[190:193], v[42:45]
	v_mfma_f32_16x16x32_bf16 v[30:33], v[110:113], v[206:209], v[30:33]
	v_mfma_f32_16x16x32_bf16 v[26:29], v[134:137], v[206:209], v[26:29]
	v_mfma_f32_16x16x32_bf16 v[14:17], v[110:113], v[214:217], v[14:17]
	v_mfma_f32_16x16x32_bf16 v[10:13], v[134:137], v[214:217], v[10:13]
	s_setprio 0
	s_setprio 1
	v_mfma_f32_16x16x32_bf16 v[54:57], v[146:149], v[178:181], v[54:57]
	v_mfma_f32_16x16x32_bf16 v[50:53], v[170:173], v[178:181], v[50:53]
	v_mfma_f32_16x16x32_bf16 v[38:41], v[146:149], v[186:189], v[38:41]
	v_mfma_f32_16x16x32_bf16 v[34:37], v[170:173], v[186:189], v[34:37]
	v_mfma_f32_16x16x32_bf16 v[22:25], v[146:149], v[194:197], v[22:25]
	v_mfma_f32_16x16x32_bf16 v[18:21], v[170:173], v[194:197], v[18:21]
	v_mfma_f32_16x16x32_bf16 v[6:9], v[146:149], v[210:213], v[6:9]
	v_mfma_f32_16x16x32_bf16 v[2:5], v[170:173], v[210:213], v[2:5]
	v_mfma_f32_16x16x32_bf16 v[54:57], v[150:153], v[182:185], v[54:57]
	v_mfma_f32_16x16x32_bf16 v[50:53], v[174:177], v[182:185], v[50:53]
	v_mfma_f32_16x16x32_bf16 v[38:41], v[150:153], v[190:193], v[38:41]
	v_mfma_f32_16x16x32_bf16 v[34:37], v[174:177], v[190:193], v[34:37]
	v_mfma_f32_16x16x32_bf16 v[22:25], v[150:153], v[206:209], v[22:25]
	v_mfma_f32_16x16x32_bf16 v[18:21], v[174:177], v[206:209], v[18:21]
	v_mfma_f32_16x16x32_bf16 v[6:9], v[150:153], v[214:217], v[6:9]
	v_mfma_f32_16x16x32_bf16 v[2:5], v[174:177], v[214:217], v[2:5]
	s_setprio 0
	s_barrier
	s_add_u32 s66, s66, 0x100
	s_addc_u32 s67, s67, 0
	s_cmp_ge_i32 s68, s51
	s_mov_b64 s[28:29], s[30:31]
	s_mov_b32 s34, s68
	s_cbranch_scc0 .LBB0_554
	s_and_b64 vcc, exec, s[24:25]
	s_cbranch_vccz .LBB0_557

; #define PG8_STAGE(bufoff, gbase, voff) do { _Pragma("unroll") for (int _i = 0; _i < 2; ++_i) \
;         __builtin_amdgcn_global_load_lds((const unsigned*)((const char*)(gbase) + (voff)[_i]), (PG8_LAS unsigned*)(lds + (bufoff) + ldsw + _i * 8192), 16, 0, 0); } while (0)
; #define PG8_LDA(dst, b, h) do { _Pragma("unroll") for (int m = 0; m < 4; ++m) _Pragma("unroll") for (int k = 0; k < 2; ++k) dst[m][k] = *(const PG8_LAS bf16x8*)(lds + PG8_SA(b, h) + aoff + m * 2048 + k * 1024); } while (0)
; #define PG8_LDB(dst, b, h) do { _Pragma("unroll") for (int n = 0; n < 2; ++n) _Pragma("unroll") for (int k = 0; k < 2; ++k) dst[n][k] = *(const PG8_LAS bf16x8*)(lds + PG8_SB(b, h) + boff + n * 2048 + k * 1024); } while (0)
; #define PG8_MMA(ai, bj, At, Bt) do { __builtin_amdgcn_s_setprio(1); _Pragma("unroll") for (int m = 0; m < 4; ++m) _Pragma("unroll") for (int n = 0; n < 2; ++n) _Pragma("unroll") for (int k = 0; k < 2; ++k) \
;         acc[ai][bj][m][n] = __builtin_amdgcn_mfma_f32_16x16x32_bf16(Bt[n][k], At[m][k], acc[ai][bj][m][n], 0, 0, 0); __builtin_amdgcn_s_setprio(0); } while (0)
; #define PG8_WAIT_V(n) asm volatile("s_waitcnt vmcnt(" #n ")" ::: "memory")
; #define PG8_WAIT_L(n) do { asm volatile("s_waitcnt lgkmcnt(" #n ")" ::: "memory"); __builtin_amdgcn_s_waitcnt(0xC07F); } while (0)
; #define PG8_BAR __builtin_amdgcn_s_barrier()
; template <class Epi, class Sched, bool SEG3 = false>
; __device__ __forceinline__ void gemm_phase(PG8_LAS unsigned char* lds, const Gemm g, const Sched& S, const Epi& E) {
;     ...
;             const bool last = (t == ntc - 2);
;             const char* a1 = cA + (size_t)(t + 1) * kstep;
;             const char* a2 = last ? nA : cA + (size_t)(t + 2) * kstep; const char* b2 = last ? nB : cB + (size_t)(t + 2) * kstep;
;             const char* a3 = a2 + kstep; const char* b3 = b2 + kstep;
;             PG8_LDB(B0, 0, 0); PG8_LDB(B1, 0, 1); PG8_SCHED; PG8_LDA(At, 0, 0); PG8_STAGE(PG8_SA(1, 1), a1 + hsA, voffA);
;             PG8_WAIT_V(8); PG8_WAIT_L(0); PG8_BAR; if (cur.half != 1) { PG8_MMA(0, 0, At, B0); PG8_MMA(0, 1, At, B1); } PG8_BAR; PG8_SCHED;
;             PG8_LDA(At, 0, 1); PG8_STAGE(PG8_SB(0, 0), b2, voffB); PG8_STAGE(PG8_SB(0, 1), b2 + hsB, voffB); PG8_STAGE(PG8_SA(0, 0), a2, voffA);
;             PG8_WAIT_V(8); PG8_WAIT_L(0); PG8_BAR; if (cur.half != 0) { PG8_MMA(1, 0, At, B0); PG8_MMA(1, 1, At, B1); } PG8_BAR; PG8_SCHED;
.LBB0_655:
	ds_read_b128 v[10:13], v187
	ds_read_b128 v[14:17], v187 offset:1024
	ds_read_b128 v[34:37], v187 offset:2048
	ds_read_b128 v[38:41], v187 offset:3072
	ds_read_b128 v[146:149], v188
	ds_read_b128 v[174:177], v188 offset:1024
	ds_read_b128 v[178:181], v188 offset:2048
	ds_read_b128 v[182:185], v188 offset:3072
	s_add_i32 s20, s10, 2
	s_add_u32 s11, s8, 0xfffc0080
	s_addc_u32 s12, s9, -1
	s_cmp_eq_u32 s86, s10
	s_cselect_b32 s10, s16, s17
	s_cselect_b32 s13, s7, s12
	s_cselect_b32 s12, s14, s11
	s_cselect_b32 s11, s15, s19
	v_lshl_add_u64 v[244:245], s[8:9], 0, v[168:169]
	s_add_i32 m0, s73, 0xc000
	ds_read_b128 v[212:215], v189
	ds_read_b128 v[216:219], v189 offset:1024
	ds_read_b128 v[220:223], v189 offset:2048
	ds_read_b128 v[224:227], v189 offset:3072
	ds_read_b128 v[228:231], v189 offset:4096
	ds_read_b128 v[232:235], v189 offset:5120
	ds_read_b128 v[236:239], v189 offset:6144
	ds_read_b128 v[240:243], v189 offset:7168
	global_load_lds_dwordx4 v[244:245], off
	s_add_i32 m0, s73, 0xe000
	v_lshl_add_u64 v[244:245], s[8:9], 0, v[170:171]
	global_load_lds_dwordx4 v[244:245], off
	s_waitcnt vmcnt(8) lgkmcnt(0)
	s_barrier
	s_setprio 1
	v_mfma_f32_16x16x32_bf16 v[142:145], v[10:13], v[212:215], v[142:145]
	v_mfma_f32_16x16x32_bf16 v[138:141], v[34:37], v[212:215], v[138:141]
	v_mfma_f32_16x16x32_bf16 v[126:129], v[10:13], v[220:223], v[126:129]
	v_mfma_f32_16x16x32_bf16 v[122:125], v[34:37], v[220:223], v[122:125]
	v_mfma_f32_16x16x32_bf16 v[110:113], v[10:13], v[228:231], v[110:113]
	v_mfma_f32_16x16x32_bf16 v[106:109], v[34:37], v[228:231], v[106:109]
	v_mfma_f32_16x16x32_bf16 v[94:97], v[10:13], v[236:239], v[94:97]
	v_mfma_f32_16x16x32_bf16 v[90:93], v[34:37], v[236:239], v[90:93]
	v_mfma_f32_16x16x32_bf16 v[142:145], v[14:17], v[216:219], v[142:145]
	v_mfma_f32_16x16x32_bf16 v[138:141], v[38:41], v[216:219], v[138:141]
	v_mfma_f32_16x16x32_bf16 v[126:129], v[14:17], v[224:227], v[126:129]
	v_mfma_f32_16x16x32_bf16 v[122:125], v[38:41], v[224:227], v[122:125]
	v_mfma_f32_16x16x32_bf16 v[110:113], v[14:17], v[232:235], v[110:113]
	v_mfma_f32_16x16x32_bf16 v[106:109], v[38:41], v[232:235], v[106:109]
	v_mfma_f32_16x16x32_bf16 v[94:97], v[14:17], v[240:243], v[94:97]
	v_mfma_f32_16x16x32_bf16 v[90:93], v[38:41], v[240:243], v[90:93]
	s_setprio 0
	s_setprio 1
	v_mfma_f32_16x16x32_bf16 v[134:137], v[146:149], v[212:215], v[134:137]
	v_mfma_f32_16x16x32_bf16 v[130:133], v[178:181], v[212:215], v[130:133]
	v_mfma_f32_16x16x32_bf16 v[118:121], v[146:149], v[220:223], v[118:121]
	v_mfma_f32_16x16x32_bf16 v[114:117], v[178:181], v[220:223], v[114:117]
	v_mfma_f32_16x16x32_bf16 v[102:105], v[146:149], v[228:231], v[102:105]
	v_mfma_f32_16x16x32_bf16 v[98:101], v[178:181], v[228:231], v[98:101]
	v_mfma_f32_16x16x32_bf16 v[86:89], v[146:149], v[236:239], v[86:89]
	v_mfma_f32_16x16x32_bf16 v[82:85], v[178:181], v[236:239], v[82:85]
	v_mfma_f32_16x16x32_bf16 v[134:137], v[174:177], v[216:219], v[134:137]
	v_mfma_f32_16x16x32_bf16 v[130:133], v[182:185], v[216:219], v[130:133]
	v_mfma_f32_16x16x32_bf16 v[118:121], v[174:177], v[224:227], v[118:121]
	v_mfma_f32_16x16x32_bf16 v[114:117], v[182:185], v[224:227], v[114:117]
	v_mfma_f32_16x16x32_bf16 v[102:105], v[174:177], v[232:235], v[102:105]
	v_mfma_f32_16x16x32_bf16 v[98:101], v[182:185], v[232:235], v[98:101]
	v_mfma_f32_16x16x32_bf16 v[86:89], v[174:177], v[240:243], v[86:89]
	v_mfma_f32_16x16x32_bf16 v[82:85], v[182:185], v[240:243], v[82:85]
	s_setprio 0
	s_barrier
	s_mov_b32 m0, s69
	v_lshl_add_u64 v[244:245], s[10:11], 0, v[152:153]
	s_add_u32 s54, s10, 0x40000
	ds_read_b128 v[212:215], v189 offset:16384
	ds_read_b128 v[216:219], v189 offset:17408
	ds_read_b128 v[220:223], v189 offset:18432
	ds_read_b128 v[224:227], v189 offset:19456
	ds_read_b128 v[228:231], v189 offset:20480
	ds_read_b128 v[232:235], v189 offset:21504
	ds_read_b128 v[236:239], v189 offset:22528
	ds_read_b128 v[240:243], v189 offset:23552
	global_load_lds_dwordx4 v[244:245], off
	v_lshl_add_u64 v[246:247], s[10:11], 0, v[156:157]
	s_mov_b32 m0, s70
	s_addc_u32 s55, s11, 0
	global_load_lds_dwordx4 v[246:247], off
	v_lshl_add_u64 v[248:249], s[54:55], 0, v[152:153]
	s_mov_b32 m0, s71
	v_lshl_add_u64 v[250:251], s[12:13], 0, v[154:155]
	global_load_lds_dwordx4 v[248:249], off
	s_mov_b32 m0, s72
	v_lshl_add_u64 v[248:249], s[54:55], 0, v[156:157]
	global_load_lds_dwordx4 v[248:249], off
	s_mov_b32 m0, s73
	v_lshl_add_u64 v[248:249], s[12:13], 0, v[150:151]
	global_load_lds_dwordx4 v[248:249], off
	s_mov_b32 m0, s74
	s_nop 0
	global_load_lds_dwordx4 v[250:251], off
	s_waitcnt vmcnt(8) lgkmcnt(0)
	s_barrier
; #define PG8_STAGE(bufoff, gbase, voff) do { _Pragma("unroll") for (int _i = 0; _i < 2; ++_i) \
;         __builtin_amdgcn_global_load_lds((const unsigned*)((const char*)(gbase) + (voff)[_i]), (PG8_LAS unsigned*)(lds + (bufoff) + ldsw + _i * 8192), 16, 0, 0); } while (0)
; #define PG8_LDA(dst, b, h) do { _Pragma("unroll") for (int m = 0; m < 4; ++m) _Pragma("unroll") for (int k = 0; k < 2; ++k) dst[m][k] = *(const PG8_LAS bf16x8*)(lds + PG8_SA(b, h) + aoff + m * 2048 + k * 1024); } while (0)
; #define PG8_LDB(dst, b, h) do { _Pragma("unroll") for (int n = 0; n < 2; ++n) _Pragma("unroll") for (int k = 0; k < 2; ++k) dst[n][k] = *(const PG8_LAS bf16x8*)(lds + PG8_SB(b, h) + boff + n * 2048 + k * 1024); } while (0)
; #define PG8_MMA(ai, bj, At, Bt) do { __builtin_amdgcn_s_setprio(1); _Pragma("unroll") for (int m = 0; m < 4; ++m) _Pragma("unroll") for (int n = 0; n < 2; ++n) _Pragma("unroll") for (int k = 0; k < 2; ++k) \
;         acc[ai][bj][m][n] = __builtin_amdgcn_mfma_f32_16x16x32_bf16(Bt[n][k], At[m][k], acc[ai][bj][m][n], 0, 0, 0); __builtin_amdgcn_s_setprio(0); } while (0)
; #define PG8_WAIT_V(n) asm volatile("s_waitcnt vmcnt(" #n ")" ::: "memory")
; #define PG8_WAIT_L(n) do { asm volatile("s_waitcnt lgkmcnt(" #n ")" ::: "memory"); __builtin_amdgcn_s_waitcnt(0xC07F); } while (0)
; #define PG8_BAR __builtin_amdgcn_s_barrier()
; #define PG8_SCHED __builtin_amdgcn_sched_barrier(0)
; template <class Epi, class Sched, bool SEG3 = false>
; __device__ __forceinline__ void gemm_phase(PG8_LAS unsigned char* lds, const Gemm g, const Sched& S, const Epi& E) {
;     ...
;             PG8_WAIT_V(8); PG8_WAIT_L(0); PG8_BAR; if (cur.half != 0) { PG8_MMA(1, 0, At, B0); PG8_MMA(1, 1, At, B1); } PG8_BAR; PG8_SCHED;
;             PG8_LDB(B0, 1, 0); PG8_LDB(B1, 1, 1); PG8_SCHED; PG8_LDA(At, 1, 0); PG8_STAGE(PG8_SA(0, 1), a2 + hsA, voffA);
;             PG8_WAIT_V(8); PG8_WAIT_L(0); PG8_BAR; if (cur.half != 1) { PG8_MMA(0, 0, At, B0); PG8_MMA(0, 1, At, B1); } PG8_BAR; PG8_SCHED;
	s_setprio 1
	v_mfma_f32_16x16x32_bf16 v[78:81], v[10:13], v[212:215], v[78:81]
	v_mfma_f32_16x16x32_bf16 v[74:77], v[34:37], v[212:215], v[74:77]
	v_mfma_f32_16x16x32_bf16 v[62:65], v[10:13], v[220:223], v[62:65]
	v_mfma_f32_16x16x32_bf16 v[58:61], v[34:37], v[220:223], v[58:61]
	v_mfma_f32_16x16x32_bf16 v[46:49], v[10:13], v[228:231], v[46:49]
	v_mfma_f32_16x16x32_bf16 v[42:45], v[34:37], v[228:231], v[42:45]
	v_mfma_f32_16x16x32_bf16 v[10:13], v[10:13], v[236:239], v[22:25]
	v_mfma_f32_16x16x32_bf16 v[78:81], v[14:17], v[216:219], v[78:81]
	v_mfma_f32_16x16x32_bf16 v[74:77], v[38:41], v[216:219], v[74:77]
	v_mfma_f32_16x16x32_bf16 v[62:65], v[14:17], v[224:227], v[62:65]
	v_mfma_f32_16x16x32_bf16 v[58:61], v[38:41], v[224:227], v[58:61]
	v_mfma_f32_16x16x32_bf16 v[46:49], v[14:17], v[232:235], v[46:49]
	v_mfma_f32_16x16x32_bf16 v[42:45], v[38:41], v[232:235], v[42:45]
	v_mfma_f32_16x16x32_bf16 v[10:13], v[14:17], v[240:243], v[10:13]
	v_mfma_f32_16x16x32_bf16 v[14:17], v[34:37], v[236:239], v[18:21]
	v_mfma_f32_16x16x32_bf16 v[14:17], v[38:41], v[240:243], v[14:17]
	s_setprio 0
	s_setprio 1
	v_mfma_f32_16x16x32_bf16 v[18:21], v[146:149], v[212:215], v[70:73]
	v_mfma_f32_16x16x32_bf16 v[34:37], v[174:177], v[216:219], v[18:21]
	v_mfma_f32_16x16x32_bf16 v[18:21], v[178:181], v[212:215], v[66:69]
	v_mfma_f32_16x16x32_bf16 v[38:41], v[182:185], v[216:219], v[18:21]
	v_mfma_f32_16x16x32_bf16 v[18:21], v[146:149], v[220:223], v[54:57]
	v_mfma_f32_16x16x32_bf16 v[54:57], v[174:177], v[224:227], v[18:21]
	v_mfma_f32_16x16x32_bf16 v[18:21], v[178:181], v[220:223], v[50:53]
	v_mfma_f32_16x16x32_bf16 v[50:53], v[182:185], v[224:227], v[18:21]
	v_mfma_f32_16x16x32_bf16 v[18:21], v[146:149], v[228:231], v[30:33]
	v_mfma_f32_16x16x32_bf16 v[30:33], v[174:177], v[232:235], v[18:21]
	v_mfma_f32_16x16x32_bf16 v[18:21], v[178:181], v[228:231], v[26:29]
	v_mfma_f32_16x16x32_bf16 v[6:9], v[146:149], v[236:239], v[6:9]
	v_mfma_f32_16x16x32_bf16 v[2:5], v[178:181], v[236:239], v[2:5]
	v_mfma_f32_16x16x32_bf16 v[26:29], v[182:185], v[232:235], v[18:21]
	v_mfma_f32_16x16x32_bf16 v[6:9], v[174:177], v[240:243], v[6:9]
	v_mfma_f32_16x16x32_bf16 v[2:5], v[182:185], v[240:243], v[2:5]
	s_setprio 0
	s_barrier
	s_nop 0
	ds_read_b128 v[18:21], v190
	ds_read_b128 v[22:25], v190 offset:1024
	ds_read_b128 v[66:69], v190 offset:2048
	ds_read_b128 v[70:73], v190 offset:3072
	ds_read_b128 v[146:149], v191
	ds_read_b128 v[174:177], v191 offset:1024
	ds_read_b128 v[178:181], v191 offset:2048
	ds_read_b128 v[182:185], v191 offset:3072
	s_add_u32 s12, s12, 0x40000
	s_addc_u32 s13, s13, 0
	s_mov_b32 m0, s75
	v_lshl_add_u64 v[252:253], s[12:13], 0, v[150:151]
	ds_read_b128 v[212:215], v189 offset:32768
	ds_read_b128 v[216:219], v189 offset:33792
	ds_read_b128 v[220:223], v189 offset:34816
	ds_read_b128 v[224:227], v189 offset:35840
	ds_read_b128 v[228:231], v189 offset:36864
	ds_read_b128 v[232:235], v189 offset:37888
	ds_read_b128 v[236:239], v189 offset:38912
	ds_read_b128 v[240:243], v189 offset:39936
	global_load_lds_dwordx4 v[252:253], off
	s_mov_b32 m0, s76
	v_lshl_add_u64 v[252:253], s[12:13], 0, v[154:155]
	global_load_lds_dwordx4 v[252:253], off
	s_waitcnt vmcnt(8) lgkmcnt(0)
	s_barrier
	s_setprio 1
	v_mfma_f32_16x16x32_bf16 v[142:145], v[18:21], v[212:215], v[142:145]
	v_mfma_f32_16x16x32_bf16 v[138:141], v[66:69], v[212:215], v[138:141]
	v_mfma_f32_16x16x32_bf16 v[126:129], v[18:21], v[220:223], v[126:129]
	v_mfma_f32_16x16x32_bf16 v[122:125], v[66:69], v[220:223], v[122:125]
	v_mfma_f32_16x16x32_bf16 v[110:113], v[18:21], v[228:231], v[110:113]
	v_mfma_f32_16x16x32_bf16 v[106:109], v[66:69], v[228:231], v[106:109]
	v_mfma_f32_16x16x32_bf16 v[94:97], v[18:21], v[236:239], v[94:97]
	v_mfma_f32_16x16x32_bf16 v[90:93], v[66:69], v[236:239], v[90:93]
	v_mfma_f32_16x16x32_bf16 v[142:145], v[22:25], v[216:219], v[142:145]
	v_mfma_f32_16x16x32_bf16 v[138:141], v[70:73], v[216:219], v[138:141]
	v_mfma_f32_16x16x32_bf16 v[126:129], v[22:25], v[224:227], v[126:129]
	v_mfma_f32_16x16x32_bf16 v[122:125], v[70:73], v[224:227], v[122:125]
	v_mfma_f32_16x16x32_bf16 v[110:113], v[22:25], v[232:235], v[110:113]
	v_mfma_f32_16x16x32_bf16 v[106:109], v[70:73], v[232:235], v[106:109]
	v_mfma_f32_16x16x32_bf16 v[94:97], v[22:25], v[240:243], v[94:97]
	v_mfma_f32_16x16x32_bf16 v[90:93], v[70:73], v[240:243], v[90:93]
	s_setprio 0
	s_setprio 1
	v_mfma_f32_16x16x32_bf16 v[134:137], v[146:149], v[212:215], v[134:137]
	v_mfma_f32_16x16x32_bf16 v[130:133], v[178:181], v[212:215], v[130:133]
	v_mfma_f32_16x16x32_bf16 v[118:121], v[146:149], v[220:223], v[118:121]
	v_mfma_f32_16x16x32_bf16 v[114:117], v[178:181], v[220:223], v[114:117]
	v_mfma_f32_16x16x32_bf16 v[102:105], v[146:149], v[228:231], v[102:105]
	v_mfma_f32_16x16x32_bf16 v[98:101], v[178:181], v[228:231], v[98:101]
	v_mfma_f32_16x16x32_bf16 v[86:89], v[146:149], v[236:239], v[86:89]
	v_mfma_f32_16x16x32_bf16 v[82:85], v[178:181], v[236:239], v[82:85]
	v_mfma_f32_16x16x32_bf16 v[134:137], v[174:177], v[216:219], v[134:137]
	v_mfma_f32_16x16x32_bf16 v[130:133], v[182:185], v[216:219], v[130:133]
	v_mfma_f32_16x16x32_bf16 v[118:121], v[174:177], v[224:227], v[118:121]
	v_mfma_f32_16x16x32_bf16 v[114:117], v[182:185], v[224:227], v[114:117]
	v_mfma_f32_16x16x32_bf16 v[102:105], v[174:177], v[232:235], v[102:105]
	v_mfma_f32_16x16x32_bf16 v[98:101], v[182:185], v[232:235], v[98:101]
	v_mfma_f32_16x16x32_bf16 v[86:89], v[174:177], v[240:243], v[86:89]
	v_mfma_f32_16x16x32_bf16 v[82:85], v[182:185], v[240:243], v[82:85]
	s_setprio 0
	s_barrier
; #define PG8_STAGE(bufoff, gbase, voff) do { _Pragma("unroll") for (int _i = 0; _i < 2; ++_i) \
;         __builtin_amdgcn_global_load_lds((const unsigned*)((const char*)(gbase) + (voff)[_i]), (PG8_LAS unsigned*)(lds + (bufoff) + ldsw + _i * 8192), 16, 0, 0); } while (0)
; #define PG8_LDA(dst, b, h) do { _Pragma("unroll") for (int m = 0; m < 4; ++m) _Pragma("unroll") for (int k = 0; k < 2; ++k) dst[m][k] = *(const PG8_LAS bf16x8*)(lds + PG8_SA(b, h) + aoff + m * 2048 + k * 1024); } while (0)
; #define PG8_MMA(ai, bj, At, Bt) do { __builtin_amdgcn_s_setprio(1); _Pragma("unroll") for (int m = 0; m < 4; ++m) _Pragma("unroll") for (int n = 0; n < 2; ++n) _Pragma("unroll") for (int k = 0; k < 2; ++k) \
;         acc[ai][bj][m][n] = __builtin_amdgcn_mfma_f32_16x16x32_bf16(Bt[n][k], At[m][k], acc[ai][bj][m][n], 0, 0, 0); __builtin_amdgcn_s_setprio(0); } while (0)
; #define PG8_WAIT_V(n) asm volatile("s_waitcnt vmcnt(" #n ")" ::: "memory")
; #define PG8_WAIT_L(n) do { asm volatile("s_waitcnt lgkmcnt(" #n ")" ::: "memory"); __builtin_amdgcn_s_waitcnt(0xC07F); } while (0)
; #define PG8_BAR __builtin_amdgcn_s_barrier()
; #define PG8_SCHED __builtin_amdgcn_sched_barrier(0)
; template <class Epi, class Sched, bool SEG3 = false>
; __device__ __forceinline__ void gemm_phase(PG8_LAS unsigned char* lds, const Gemm g, const Sched& S, const Epi& E) {
;     ...
;             PG8_LDA(At, 1, 1); PG8_STAGE(PG8_SB(1, 0), b3, voffB); PG8_STAGE(PG8_SB(1, 1), b3 + hsB, voffB); PG8_STAGE(PG8_SA(1, 0), a3, voffA);
;             PG8_WAIT_V(8); PG8_WAIT_L(0); PG8_BAR; if (cur.half != 0) { PG8_MMA(1, 0, At, B0); PG8_MMA(1, 1, At, B1); } PG8_BAR; PG8_SCHED;
;         }
	s_mov_b32 m0, s79
	v_lshl_add_u64 v[244:245], v[244:245], 0, s[30:31]
	s_add_u32 s10, s10, 0x40080
	ds_read_b128 v[212:215], v189 offset:49152
	ds_read_b128 v[216:219], v189 offset:50176
	ds_read_b128 v[220:223], v189 offset:51200
	ds_read_b128 v[224:227], v189 offset:52224
	ds_read_b128 v[228:231], v189 offset:53248
	ds_read_b128 v[232:235], v189 offset:54272
	ds_read_b128 v[236:239], v189 offset:55296
	ds_read_b128 v[240:243], v189 offset:56320
	global_load_lds_dwordx4 v[244:245], off
	v_lshl_add_u64 v[244:245], v[246:247], 0, s[30:31]
	s_mov_b32 m0, s80
	s_addc_u32 s11, s11, 0
	global_load_lds_dwordx4 v[244:245], off
	s_mov_b32 m0, s84
	v_lshl_add_u64 v[244:245], s[10:11], 0, v[152:153]
	global_load_lds_dwordx4 v[244:245], off
	s_mov_b32 m0, s85
	v_lshl_add_u64 v[244:245], s[10:11], 0, v[156:157]
	global_load_lds_dwordx4 v[244:245], off
	s_mov_b32 m0, s82
	v_lshl_add_u64 v[244:245], v[248:249], 0, s[30:31]
	global_load_lds_dwordx4 v[244:245], off
	s_mov_b32 m0, s83
	v_lshl_add_u64 v[244:245], v[250:251], 0, s[30:31]
	global_load_lds_dwordx4 v[244:245], off
	s_waitcnt vmcnt(8) lgkmcnt(0)
	s_barrier
	s_setprio 1
	v_mfma_f32_16x16x32_bf16 v[78:81], v[18:21], v[212:215], v[78:81]
	v_mfma_f32_16x16x32_bf16 v[62:65], v[18:21], v[220:223], v[62:65]
	v_mfma_f32_16x16x32_bf16 v[46:49], v[18:21], v[228:231], v[46:49]
	v_mfma_f32_16x16x32_bf16 v[10:13], v[18:21], v[236:239], v[10:13]
	v_mfma_f32_16x16x32_bf16 v[78:81], v[22:25], v[216:219], v[78:81]
	v_mfma_f32_16x16x32_bf16 v[74:77], v[66:69], v[212:215], v[74:77]
	v_mfma_f32_16x16x32_bf16 v[62:65], v[22:25], v[224:227], v[62:65]
	v_mfma_f32_16x16x32_bf16 v[58:61], v[66:69], v[220:223], v[58:61]
	v_mfma_f32_16x16x32_bf16 v[46:49], v[22:25], v[232:235], v[46:49]
	v_mfma_f32_16x16x32_bf16 v[42:45], v[66:69], v[228:231], v[42:45]
	v_mfma_f32_16x16x32_bf16 v[22:25], v[22:25], v[240:243], v[10:13]
	v_mfma_f32_16x16x32_bf16 v[10:13], v[66:69], v[236:239], v[14:17]
	v_mfma_f32_16x16x32_bf16 v[74:77], v[70:73], v[216:219], v[74:77]
	v_mfma_f32_16x16x32_bf16 v[58:61], v[70:73], v[224:227], v[58:61]
	v_mfma_f32_16x16x32_bf16 v[42:45], v[70:73], v[232:235], v[42:45]
	v_mfma_f32_16x16x32_bf16 v[18:21], v[70:73], v[240:243], v[10:13]
	s_setprio 0
	s_setprio 1
	v_mfma_f32_16x16x32_bf16 v[10:13], v[146:149], v[212:215], v[34:37]
	v_mfma_f32_16x16x32_bf16 v[70:73], v[174:177], v[216:219], v[10:13]
	v_mfma_f32_16x16x32_bf16 v[10:13], v[178:181], v[212:215], v[38:41]
	v_mfma_f32_16x16x32_bf16 v[66:69], v[182:185], v[216:219], v[10:13]
	v_mfma_f32_16x16x32_bf16 v[10:13], v[146:149], v[220:223], v[54:57]
	v_mfma_f32_16x16x32_bf16 v[54:57], v[174:177], v[224:227], v[10:13]
	v_mfma_f32_16x16x32_bf16 v[10:13], v[178:181], v[220:223], v[50:53]
	v_mfma_f32_16x16x32_bf16 v[50:53], v[182:185], v[224:227], v[10:13]
	v_mfma_f32_16x16x32_bf16 v[10:13], v[146:149], v[228:231], v[30:33]
	v_mfma_f32_16x16x32_bf16 v[30:33], v[174:177], v[232:235], v[10:13]
	v_mfma_f32_16x16x32_bf16 v[10:13], v[178:181], v[228:231], v[26:29]
	v_mfma_f32_16x16x32_bf16 v[6:9], v[146:149], v[236:239], v[6:9]
	v_mfma_f32_16x16x32_bf16 v[2:5], v[178:181], v[236:239], v[2:5]
	v_mfma_f32_16x16x32_bf16 v[26:29], v[182:185], v[232:235], v[10:13]
	v_mfma_f32_16x16x32_bf16 v[6:9], v[174:177], v[240:243], v[6:9]
	v_mfma_f32_16x16x32_bf16 v[2:5], v[182:185], v[240:243], v[2:5]
	s_setprio 0
	s_barrier
	s_add_u32 s8, s8, 0x100
	s_addc_u32 s9, s9, 0
	s_add_u32 s17, s17, 0x100
	s_addc_u32 s19, s19, 0
	s_cmp_ge_i32 s20, s77
	s_mov_b32 s10, s20
	s_cbranch_scc0 .LBB0_655
	s_and_b64 vcc, exec, s[36:37]
	s_cbranch_vccz .LBB0_658

; #define PG8_STAGE(bufoff, gbase, voff) do { _Pragma("unroll") for (int _i = 0; _i < 2; ++_i) \
;         __builtin_amdgcn_global_load_lds((const unsigned*)((const char*)(gbase) + (voff)[_i]), (PG8_LAS unsigned*)(lds + (bufoff) + ldsw + _i * 8192), 16, 0, 0); } while (0)
; #define PG8_LDA(dst, b, h) do { _Pragma("unroll") for (int m = 0; m < 4; ++m) _Pragma("unroll") for (int k = 0; k < 2; ++k) dst[m][k] = *(const PG8_LAS bf16x8*)(lds + PG8_SA(b, h) + aoff + m * 2048 + k * 1024); } while (0)
; #define PG8_LDB(dst, b, h) do { _Pragma("unroll") for (int n = 0; n < 2; ++n) _Pragma("unroll") for (int k = 0; k < 2; ++k) dst[n][k] = *(const PG8_LAS bf16x8*)(lds + PG8_SB(b, h) + boff + n * 2048 + k * 1024); } while (0)
; #define PG8_MMA(ai, bj, At, Bt) do { __builtin_amdgcn_s_setprio(1); _Pragma("unroll") for (int m = 0; m < 4; ++m) _Pragma("unroll") for (int n = 0; n < 2; ++n) _Pragma("unroll") for (int k = 0; k < 2; ++k) \
;         acc[ai][bj][m][n] = __builtin_amdgcn_mfma_f32_16x16x32_bf16(Bt[n][k], At[m][k], acc[ai][bj][m][n], 0, 0, 0); __builtin_amdgcn_s_setprio(0); } while (0)
; #define PG8_WAIT_V(n) asm volatile("s_waitcnt vmcnt(" #n ")" ::: "memory")
; #define PG8_WAIT_L(n) do { asm volatile("s_waitcnt lgkmcnt(" #n ")" ::: "memory"); __builtin_amdgcn_s_waitcnt(0xC07F); } while (0)
; #define PG8_BAR __builtin_amdgcn_s_barrier()
; template <class Epi, class Sched, bool SEG3 = false>
; __device__ __forceinline__ void gemm_phase(PG8_LAS unsigned char* lds, const Gemm g, const Sched& S, const Epi& E) {
;     ...
;             const bool last = (t == ntc - 2);
;             const char* a1 = cA + (size_t)(t + 1) * kstep;
;             const char* a2 = last ? nA : cA + (size_t)(t + 2) * kstep; const char* b2 = last ? nB : cB + (size_t)(t + 2) * kstep;
;             const char* a3 = a2 + kstep; const char* b3 = b2 + kstep;
;             PG8_LDB(B0, 0, 0); PG8_LDB(B1, 0, 1); PG8_SCHED; PG8_LDA(At, 0, 0); PG8_STAGE(PG8_SA(1, 1), a1 + hsA, voffA);
;             PG8_WAIT_V(8); PG8_WAIT_L(0); PG8_BAR; if (cur.half != 1) { PG8_MMA(0, 0, At, B0); PG8_MMA(0, 1, At, B1); } PG8_BAR; PG8_SCHED;
;             PG8_LDA(At, 0, 1); PG8_STAGE(PG8_SB(0, 0), b2, voffB); PG8_STAGE(PG8_SB(0, 1), b2 + hsB, voffB); PG8_STAGE(PG8_SA(0, 0), a2, voffA);
;             PG8_WAIT_V(8); PG8_WAIT_L(0); PG8_BAR; if (cur.half != 0) { PG8_MMA(1, 0, At, B0); PG8_MMA(1, 1, At, B1); } PG8_BAR; PG8_SCHED;
.LBB0_2007:
	ds_read_b128 v[124:127], v231
	ds_read_b128 v[132:135], v231 offset:1024
	ds_read_b128 v[140:143], v231 offset:2048
	ds_read_b128 v[144:147], v231 offset:3072
	ds_read_b128 v[148:151], v232
	ds_read_b128 v[152:155], v232 offset:1024
	ds_read_b128 v[156:159], v232 offset:2048
	ds_read_b128 v[160:163], v232 offset:3072
	s_add_i32 s65, s28, 2
	s_add_u32 s29, s6, 0xfffc0080
	s_addc_u32 s30, s7, -1
	s_cmp_eq_u32 s17, s28
	s_cselect_b32 s28, s22, s19
	s_cselect_b32 s31, s21, s30
	s_cselect_b32 s30, s20, s29
	s_cselect_b32 s29, s23, s27
	v_lshl_add_u64 v[98:99], s[6:7], 0, v[206:207]
	s_add_i32 m0, s50, 0xc000
	ds_read_b128 v[164:167], v233
	ds_read_b128 v[168:171], v233 offset:1024
	ds_read_b128 v[172:175], v233 offset:2048
	ds_read_b128 v[176:179], v233 offset:3072
	ds_read_b128 v[180:183], v233 offset:4096
	ds_read_b128 v[184:187], v233 offset:5120
	ds_read_b128 v[188:191], v233 offset:6144
	ds_read_b128 v[192:195], v233 offset:7168
	global_load_lds_dwordx4 v[98:99], off
	s_add_i32 m0, s50, 0xe000
	v_lshl_add_u64 v[98:99], s[6:7], 0, v[208:209]
	global_load_lds_dwordx4 v[98:99], off
	s_waitcnt vmcnt(8) lgkmcnt(0)
	s_barrier
	s_setprio 1
	v_mfma_f32_16x16x32_bf16 v[136:139], v[124:127], v[164:167], v[136:139]
	v_mfma_f32_16x16x32_bf16 v[128:131], v[140:143], v[164:167], v[128:131]
	v_mfma_f32_16x16x32_bf16 v[112:115], v[124:127], v[172:175], v[112:115]
	v_mfma_f32_16x16x32_bf16 v[108:111], v[140:143], v[172:175], v[108:111]
	v_mfma_f32_16x16x32_bf16 v[94:97], v[124:127], v[180:183], v[94:97]
	v_mfma_f32_16x16x32_bf16 v[90:93], v[140:143], v[180:183], v[90:93]
	v_mfma_f32_16x16x32_bf16 v[78:81], v[124:127], v[188:191], v[78:81]
	v_mfma_f32_16x16x32_bf16 v[74:77], v[140:143], v[188:191], v[74:77]
	v_mfma_f32_16x16x32_bf16 v[136:139], v[132:135], v[168:171], v[136:139]
	v_mfma_f32_16x16x32_bf16 v[128:131], v[144:147], v[168:171], v[128:131]
	v_mfma_f32_16x16x32_bf16 v[112:115], v[132:135], v[176:179], v[112:115]
	v_mfma_f32_16x16x32_bf16 v[108:111], v[144:147], v[176:179], v[108:111]
	v_mfma_f32_16x16x32_bf16 v[94:97], v[132:135], v[184:187], v[94:97]
	v_mfma_f32_16x16x32_bf16 v[90:93], v[144:147], v[184:187], v[90:93]
	v_mfma_f32_16x16x32_bf16 v[78:81], v[132:135], v[192:195], v[78:81]
	v_mfma_f32_16x16x32_bf16 v[74:77], v[144:147], v[192:195], v[74:77]
	s_setprio 0
	s_setprio 1
	v_mfma_f32_16x16x32_bf16 v[120:123], v[148:151], v[164:167], v[120:123]
	v_mfma_f32_16x16x32_bf16 v[116:119], v[156:159], v[164:167], v[116:119]
	v_mfma_f32_16x16x32_bf16 v[104:107], v[148:151], v[172:175], v[104:107]
	v_mfma_f32_16x16x32_bf16 v[98:101], v[156:159], v[172:175], v[100:103]
	v_mfma_f32_16x16x32_bf16 v[86:89], v[148:151], v[180:183], v[86:89]
	v_mfma_f32_16x16x32_bf16 v[82:85], v[156:159], v[180:183], v[82:85]
	v_mfma_f32_16x16x32_bf16 v[70:73], v[148:151], v[188:191], v[70:73]
	v_mfma_f32_16x16x32_bf16 v[66:69], v[156:159], v[188:191], v[66:69]
	v_mfma_f32_16x16x32_bf16 v[120:123], v[152:155], v[168:171], v[120:123]
	v_mfma_f32_16x16x32_bf16 v[116:119], v[160:163], v[168:171], v[116:119]
	v_mfma_f32_16x16x32_bf16 v[104:107], v[152:155], v[176:179], v[104:107]
	v_mfma_f32_16x16x32_bf16 v[98:101], v[160:163], v[176:179], v[98:101]
	v_mfma_f32_16x16x32_bf16 v[86:89], v[152:155], v[184:187], v[86:89]
	v_mfma_f32_16x16x32_bf16 v[82:85], v[160:163], v[184:187], v[82:85]
	v_mfma_f32_16x16x32_bf16 v[70:73], v[152:155], v[192:195], v[70:73]
	v_mfma_f32_16x16x32_bf16 v[66:69], v[160:163], v[192:195], v[66:69]
	s_setprio 0
	s_barrier
	s_mov_b32 m0, s46
	v_lshl_add_u64 v[214:215], s[28:29], 0, v[198:199]
	s_add_u32 s66, s28, 0x40000
	ds_read_b128 v[164:167], v233 offset:16384
	ds_read_b128 v[168:171], v233 offset:17408
	ds_read_b128 v[172:175], v233 offset:18432
	ds_read_b128 v[176:179], v233 offset:19456
	ds_read_b128 v[180:183], v233 offset:20480
	ds_read_b128 v[184:187], v233 offset:21504
	ds_read_b128 v[188:191], v233 offset:22528
	ds_read_b128 v[192:195], v233 offset:23552
	global_load_lds_dwordx4 v[214:215], off
	v_lshl_add_u64 v[216:217], s[28:29], 0, v[202:203]
	s_mov_b32 m0, s47
	s_addc_u32 s67, s29, 0
	global_load_lds_dwordx4 v[216:217], off
	v_lshl_add_u64 v[102:103], s[66:67], 0, v[198:199]
	s_mov_b32 m0, s48
	v_lshl_add_u64 v[218:219], s[30:31], 0, v[196:197]
	global_load_lds_dwordx4 v[102:103], off
	v_lshl_add_u64 v[102:103], s[66:67], 0, v[202:203]
	s_mov_b32 m0, s49
	v_lshl_add_u64 v[220:221], s[30:31], 0, v[200:201]
	global_load_lds_dwordx4 v[102:103], off
	s_mov_b32 m0, s50
	s_nop 0
	global_load_lds_dwordx4 v[218:219], off
	s_mov_b32 m0, s51
	s_nop 0
	global_load_lds_dwordx4 v[220:221], off
	s_waitcnt vmcnt(8) lgkmcnt(0)
	s_barrier
; #define PG8_STAGE(bufoff, gbase, voff) do { _Pragma("unroll") for (int _i = 0; _i < 2; ++_i) \
;         __builtin_amdgcn_global_load_lds((const unsigned*)((const char*)(gbase) + (voff)[_i]), (PG8_LAS unsigned*)(lds + (bufoff) + ldsw + _i * 8192), 16, 0, 0); } while (0)
; #define PG8_LDA(dst, b, h) do { _Pragma("unroll") for (int m = 0; m < 4; ++m) _Pragma("unroll") for (int k = 0; k < 2; ++k) dst[m][k] = *(const PG8_LAS bf16x8*)(lds + PG8_SA(b, h) + aoff + m * 2048 + k * 1024); } while (0)
; #define PG8_LDB(dst, b, h) do { _Pragma("unroll") for (int n = 0; n < 2; ++n) _Pragma("unroll") for (int k = 0; k < 2; ++k) dst[n][k] = *(const PG8_LAS bf16x8*)(lds + PG8_SB(b, h) + boff + n * 2048 + k * 1024); } while (0)
; #define PG8_MMA(ai, bj, At, Bt) do { __builtin_amdgcn_s_setprio(1); _Pragma("unroll") for (int m = 0; m < 4; ++m) _Pragma("unroll") for (int n = 0; n < 2; ++n) _Pragma("unroll") for (int k = 0; k < 2; ++k) \
;         acc[ai][bj][m][n] = __builtin_amdgcn_mfma_f32_16x16x32_bf16(Bt[n][k], At[m][k], acc[ai][bj][m][n], 0, 0, 0); __builtin_amdgcn_s_setprio(0); } while (0)
; #define PG8_WAIT_V(n) asm volatile("s_waitcnt vmcnt(" #n ")" ::: "memory")
; #define PG8_WAIT_L(n) do { asm volatile("s_waitcnt lgkmcnt(" #n ")" ::: "memory"); __builtin_amdgcn_s_waitcnt(0xC07F); } while (0)
; #define PG8_BAR __builtin_amdgcn_s_barrier()
; #define PG8_SCHED __builtin_amdgcn_sched_barrier(0)
; template <class Epi, class Sched, bool SEG3 = false>
; __device__ __forceinline__ void gemm_phase(PG8_LAS unsigned char* lds, const Gemm g, const Sched& S, const Epi& E) {
;     ...
;             PG8_WAIT_V(8); PG8_WAIT_L(0); PG8_BAR; if (cur.half != 0) { PG8_MMA(1, 0, At, B0); PG8_MMA(1, 1, At, B1); } PG8_BAR; PG8_SCHED;
;             PG8_LDB(B0, 1, 0); PG8_LDB(B1, 1, 1); PG8_SCHED; PG8_LDA(At, 1, 0); PG8_STAGE(PG8_SA(0, 1), a2 + hsA, voffA);
;             PG8_WAIT_V(8); PG8_WAIT_L(0); PG8_BAR; if (cur.half != 1) { PG8_MMA(0, 0, At, B0); PG8_MMA(0, 1, At, B1); } PG8_BAR; PG8_SCHED;
	s_setprio 1
	v_mfma_f32_16x16x32_bf16 v[62:65], v[124:127], v[164:167], v[62:65]
	v_mfma_f32_16x16x32_bf16 v[58:61], v[140:143], v[164:167], v[58:61]
	v_mfma_f32_16x16x32_bf16 v[46:49], v[124:127], v[172:175], v[46:49]
	v_mfma_f32_16x16x32_bf16 v[42:45], v[140:143], v[172:175], v[42:45]
	v_mfma_f32_16x16x32_bf16 v[30:33], v[124:127], v[180:183], v[30:33]
	v_mfma_f32_16x16x32_bf16 v[26:29], v[140:143], v[180:183], v[26:29]
	v_mfma_f32_16x16x32_bf16 v[14:17], v[124:127], v[188:191], v[14:17]
	v_mfma_f32_16x16x32_bf16 v[10:13], v[140:143], v[188:191], v[10:13]
	v_mfma_f32_16x16x32_bf16 v[62:65], v[132:135], v[168:171], v[62:65]
	v_mfma_f32_16x16x32_bf16 v[58:61], v[144:147], v[168:171], v[58:61]
	v_mfma_f32_16x16x32_bf16 v[46:49], v[132:135], v[176:179], v[46:49]
	v_mfma_f32_16x16x32_bf16 v[42:45], v[144:147], v[176:179], v[42:45]
	v_mfma_f32_16x16x32_bf16 v[30:33], v[132:135], v[184:187], v[30:33]
	v_mfma_f32_16x16x32_bf16 v[26:29], v[144:147], v[184:187], v[26:29]
	v_mfma_f32_16x16x32_bf16 v[14:17], v[132:135], v[192:195], v[14:17]
	v_mfma_f32_16x16x32_bf16 v[10:13], v[144:147], v[192:195], v[10:13]
	s_setprio 0
	s_setprio 1
	v_mfma_f32_16x16x32_bf16 v[54:57], v[148:151], v[164:167], v[54:57]
	v_mfma_f32_16x16x32_bf16 v[50:53], v[156:159], v[164:167], v[50:53]
	v_mfma_f32_16x16x32_bf16 v[38:41], v[148:151], v[172:175], v[38:41]
	v_mfma_f32_16x16x32_bf16 v[34:37], v[156:159], v[172:175], v[34:37]
	v_mfma_f32_16x16x32_bf16 v[22:25], v[148:151], v[180:183], v[22:25]
	v_mfma_f32_16x16x32_bf16 v[18:21], v[156:159], v[180:183], v[18:21]
	v_mfma_f32_16x16x32_bf16 v[6:9], v[148:151], v[188:191], v[6:9]
	v_mfma_f32_16x16x32_bf16 v[2:5], v[156:159], v[188:191], v[2:5]
	v_mfma_f32_16x16x32_bf16 v[54:57], v[152:155], v[168:171], v[54:57]
	v_mfma_f32_16x16x32_bf16 v[50:53], v[160:163], v[168:171], v[50:53]
	v_mfma_f32_16x16x32_bf16 v[38:41], v[152:155], v[176:179], v[38:41]
	v_mfma_f32_16x16x32_bf16 v[34:37], v[160:163], v[176:179], v[34:37]
	v_mfma_f32_16x16x32_bf16 v[22:25], v[152:155], v[184:187], v[22:25]
	v_mfma_f32_16x16x32_bf16 v[18:21], v[160:163], v[184:187], v[18:21]
	v_mfma_f32_16x16x32_bf16 v[6:9], v[152:155], v[192:195], v[6:9]
	v_mfma_f32_16x16x32_bf16 v[2:5], v[160:163], v[192:195], v[2:5]
	s_setprio 0
	s_barrier
	ds_read_b128 v[124:127], v234
	ds_read_b128 v[132:135], v234 offset:1024
	ds_read_b128 v[140:143], v234 offset:2048
	ds_read_b128 v[144:147], v234 offset:3072
	ds_read_b128 v[148:151], v235
	ds_read_b128 v[152:155], v235 offset:1024
	ds_read_b128 v[156:159], v235 offset:2048
	ds_read_b128 v[160:163], v235 offset:3072
	s_add_u32 s30, s30, 0x40000
	s_addc_u32 s31, s31, 0
	s_mov_b32 m0, s52
	v_lshl_add_u64 v[102:103], s[30:31], 0, v[196:197]
	ds_read_b128 v[164:167], v233 offset:32768
	ds_read_b128 v[168:171], v233 offset:33792
	ds_read_b128 v[172:175], v233 offset:34816
	ds_read_b128 v[176:179], v233 offset:35840
	ds_read_b128 v[180:183], v233 offset:36864
	ds_read_b128 v[184:187], v233 offset:37888
	ds_read_b128 v[188:191], v233 offset:38912
	ds_read_b128 v[192:195], v233 offset:39936
	global_load_lds_dwordx4 v[102:103], off
	s_mov_b32 m0, s53
	v_lshl_add_u64 v[102:103], s[30:31], 0, v[200:201]
	global_load_lds_dwordx4 v[102:103], off
	s_waitcnt vmcnt(8) lgkmcnt(0)
	s_barrier
	s_setprio 1
	v_mfma_f32_16x16x32_bf16 v[136:139], v[124:127], v[164:167], v[136:139]
	v_mfma_f32_16x16x32_bf16 v[128:131], v[140:143], v[164:167], v[128:131]
	v_mfma_f32_16x16x32_bf16 v[112:115], v[124:127], v[172:175], v[112:115]
	v_mfma_f32_16x16x32_bf16 v[108:111], v[140:143], v[172:175], v[108:111]
	v_mfma_f32_16x16x32_bf16 v[94:97], v[124:127], v[180:183], v[94:97]
	v_mfma_f32_16x16x32_bf16 v[90:93], v[140:143], v[180:183], v[90:93]
	v_mfma_f32_16x16x32_bf16 v[78:81], v[124:127], v[188:191], v[78:81]
	v_mfma_f32_16x16x32_bf16 v[74:77], v[140:143], v[188:191], v[74:77]
	v_mfma_f32_16x16x32_bf16 v[136:139], v[132:135], v[168:171], v[136:139]
	v_mfma_f32_16x16x32_bf16 v[128:131], v[144:147], v[168:171], v[128:131]
	v_mfma_f32_16x16x32_bf16 v[112:115], v[132:135], v[176:179], v[112:115]
	v_mfma_f32_16x16x32_bf16 v[108:111], v[144:147], v[176:179], v[108:111]
	v_mfma_f32_16x16x32_bf16 v[94:97], v[132:135], v[184:187], v[94:97]
	v_mfma_f32_16x16x32_bf16 v[90:93], v[144:147], v[184:187], v[90:93]
	v_mfma_f32_16x16x32_bf16 v[78:81], v[132:135], v[192:195], v[78:81]
	v_mfma_f32_16x16x32_bf16 v[74:77], v[144:147], v[192:195], v[74:77]
	s_setprio 0
	s_setprio 1
	v_mfma_f32_16x16x32_bf16 v[120:123], v[148:151], v[164:167], v[120:123]
	v_mfma_f32_16x16x32_bf16 v[116:119], v[156:159], v[164:167], v[116:119]
	v_mfma_f32_16x16x32_bf16 v[102:105], v[148:151], v[172:175], v[104:107]
	v_mfma_f32_16x16x32_bf16 v[98:101], v[156:159], v[172:175], v[98:101]
	v_mfma_f32_16x16x32_bf16 v[86:89], v[148:151], v[180:183], v[86:89]
	v_mfma_f32_16x16x32_bf16 v[82:85], v[156:159], v[180:183], v[82:85]
	v_mfma_f32_16x16x32_bf16 v[70:73], v[148:151], v[188:191], v[70:73]
	v_mfma_f32_16x16x32_bf16 v[66:69], v[156:159], v[188:191], v[66:69]
	v_mfma_f32_16x16x32_bf16 v[120:123], v[152:155], v[168:171], v[120:123]
	v_mfma_f32_16x16x32_bf16 v[116:119], v[160:163], v[168:171], v[116:119]
	v_mfma_f32_16x16x32_bf16 v[104:107], v[152:155], v[176:179], v[102:105]
	v_mfma_f32_16x16x32_bf16 v[100:103], v[160:163], v[176:179], v[98:101]
	v_mfma_f32_16x16x32_bf16 v[86:89], v[152:155], v[184:187], v[86:89]
	v_mfma_f32_16x16x32_bf16 v[82:85], v[160:163], v[184:187], v[82:85]
	v_mfma_f32_16x16x32_bf16 v[70:73], v[152:155], v[192:195], v[70:73]
	v_mfma_f32_16x16x32_bf16 v[66:69], v[160:163], v[192:195], v[66:69]
	s_setprio 0
	s_barrier
; #define PG8_STAGE(bufoff, gbase, voff) do { _Pragma("unroll") for (int _i = 0; _i < 2; ++_i) \
;         __builtin_amdgcn_global_load_lds((const unsigned*)((const char*)(gbase) + (voff)[_i]), (PG8_LAS unsigned*)(lds + (bufoff) + ldsw + _i * 8192), 16, 0, 0); } while (0)
; #define PG8_LDA(dst, b, h) do { _Pragma("unroll") for (int m = 0; m < 4; ++m) _Pragma("unroll") for (int k = 0; k < 2; ++k) dst[m][k] = *(const PG8_LAS bf16x8*)(lds + PG8_SA(b, h) + aoff + m * 2048 + k * 1024); } while (0)
; #define PG8_MMA(ai, bj, At, Bt) do { __builtin_amdgcn_s_setprio(1); _Pragma("unroll") for (int m = 0; m < 4; ++m) _Pragma("unroll") for (int n = 0; n < 2; ++n) _Pragma("unroll") for (int k = 0; k < 2; ++k) \
;         acc[ai][bj][m][n] = __builtin_amdgcn_mfma_f32_16x16x32_bf16(Bt[n][k], At[m][k], acc[ai][bj][m][n], 0, 0, 0); __builtin_amdgcn_s_setprio(0); } while (0)
; #define PG8_WAIT_V(n) asm volatile("s_waitcnt vmcnt(" #n ")" ::: "memory")
; #define PG8_WAIT_L(n) do { asm volatile("s_waitcnt lgkmcnt(" #n ")" ::: "memory"); __builtin_amdgcn_s_waitcnt(0xC07F); } while (0)
; #define PG8_BAR __builtin_amdgcn_s_barrier()
; #define PG8_SCHED __builtin_amdgcn_sched_barrier(0)
; template <class Epi, class Sched, bool SEG3 = false>
; __device__ __forceinline__ void gemm_phase(PG8_LAS unsigned char* lds, const Gemm g, const Sched& S, const Epi& E) {
;     ...
;             PG8_LDA(At, 1, 1); PG8_STAGE(PG8_SB(1, 0), b3, voffB); PG8_STAGE(PG8_SB(1, 1), b3 + hsB, voffB); PG8_STAGE(PG8_SA(1, 0), a3, voffA);
;             PG8_WAIT_V(8); PG8_WAIT_L(0); PG8_BAR; if (cur.half != 0) { PG8_MMA(1, 0, At, B0); PG8_MMA(1, 1, At, B1); } PG8_BAR; PG8_SCHED;
;         }
	s_mov_b32 m0, s55
	v_lshl_add_u64 v[98:99], v[214:215], 0, s[12:13]
	s_add_u32 s28, s28, 0x40080
	ds_read_b128 v[164:167], v233 offset:49152
	ds_read_b128 v[168:171], v233 offset:50176
	ds_read_b128 v[172:175], v233 offset:51200
	ds_read_b128 v[176:179], v233 offset:52224
	ds_read_b128 v[180:183], v233 offset:53248
	ds_read_b128 v[184:187], v233 offset:54272
	ds_read_b128 v[188:191], v233 offset:55296
	ds_read_b128 v[192:195], v233 offset:56320
	global_load_lds_dwordx4 v[98:99], off
	v_lshl_add_u64 v[98:99], v[216:217], 0, s[12:13]
	s_mov_b32 m0, s56
	s_addc_u32 s29, s29, 0
	global_load_lds_dwordx4 v[98:99], off
	s_mov_b32 m0, s59
	v_lshl_add_u64 v[98:99], s[28:29], 0, v[198:199]
	global_load_lds_dwordx4 v[98:99], off
	s_mov_b32 m0, s60
	v_lshl_add_u64 v[98:99], s[28:29], 0, v[202:203]
	global_load_lds_dwordx4 v[98:99], off
	s_mov_b32 m0, s57
	v_lshl_add_u64 v[98:99], v[218:219], 0, s[12:13]
	global_load_lds_dwordx4 v[98:99], off
	s_mov_b32 m0, s58
	v_lshl_add_u64 v[98:99], v[220:221], 0, s[12:13]
	global_load_lds_dwordx4 v[98:99], off
	s_waitcnt vmcnt(8) lgkmcnt(0)
	s_barrier
	s_setprio 1
	v_mfma_f32_16x16x32_bf16 v[62:65], v[124:127], v[164:167], v[62:65]
	v_mfma_f32_16x16x32_bf16 v[58:61], v[140:143], v[164:167], v[58:61]
	v_mfma_f32_16x16x32_bf16 v[46:49], v[124:127], v[172:175], v[46:49]
	v_mfma_f32_16x16x32_bf16 v[42:45], v[140:143], v[172:175], v[42:45]
	v_mfma_f32_16x16x32_bf16 v[30:33], v[124:127], v[180:183], v[30:33]
	v_mfma_f32_16x16x32_bf16 v[26:29], v[140:143], v[180:183], v[26:29]
	v_mfma_f32_16x16x32_bf16 v[14:17], v[124:127], v[188:191], v[14:17]
	v_mfma_f32_16x16x32_bf16 v[10:13], v[140:143], v[188:191], v[10:13]
	v_mfma_f32_16x16x32_bf16 v[62:65], v[132:135], v[168:171], v[62:65]
	v_mfma_f32_16x16x32_bf16 v[58:61], v[144:147], v[168:171], v[58:61]
	v_mfma_f32_16x16x32_bf16 v[46:49], v[132:135], v[176:179], v[46:49]
	v_mfma_f32_16x16x32_bf16 v[42:45], v[144:147], v[176:179], v[42:45]
	v_mfma_f32_16x16x32_bf16 v[30:33], v[132:135], v[184:187], v[30:33]
	v_mfma_f32_16x16x32_bf16 v[26:29], v[144:147], v[184:187], v[26:29]
	v_mfma_f32_16x16x32_bf16 v[14:17], v[132:135], v[192:195], v[14:17]
	v_mfma_f32_16x16x32_bf16 v[10:13], v[144:147], v[192:195], v[10:13]
	s_setprio 0
	s_setprio 1
	v_mfma_f32_16x16x32_bf16 v[54:57], v[148:151], v[164:167], v[54:57]
	v_mfma_f32_16x16x32_bf16 v[50:53], v[156:159], v[164:167], v[50:53]
	v_mfma_f32_16x16x32_bf16 v[38:41], v[148:151], v[172:175], v[38:41]
	v_mfma_f32_16x16x32_bf16 v[34:37], v[156:159], v[172:175], v[34:37]
	v_mfma_f32_16x16x32_bf16 v[22:25], v[148:151], v[180:183], v[22:25]
	v_mfma_f32_16x16x32_bf16 v[18:21], v[156:159], v[180:183], v[18:21]
	v_mfma_f32_16x16x32_bf16 v[6:9], v[148:151], v[188:191], v[6:9]
	v_mfma_f32_16x16x32_bf16 v[2:5], v[156:159], v[188:191], v[2:5]
	v_mfma_f32_16x16x32_bf16 v[54:57], v[152:155], v[168:171], v[54:57]
	v_mfma_f32_16x16x32_bf16 v[50:53], v[160:163], v[168:171], v[50:53]
	v_mfma_f32_16x16x32_bf16 v[38:41], v[152:155], v[176:179], v[38:41]
	v_mfma_f32_16x16x32_bf16 v[34:37], v[160:163], v[176:179], v[34:37]
	v_mfma_f32_16x16x32_bf16 v[22:25], v[152:155], v[184:187], v[22:25]
	v_mfma_f32_16x16x32_bf16 v[18:21], v[160:163], v[184:187], v[18:21]
	v_mfma_f32_16x16x32_bf16 v[6:9], v[152:155], v[192:195], v[6:9]
	v_mfma_f32_16x16x32_bf16 v[2:5], v[160:163], v[192:195], v[2:5]
	s_setprio 0
	s_barrier
	s_add_u32 s6, s6, 0x100
	s_addc_u32 s7, s7, 0
	s_add_u32 s19, s19, 0x100
	s_addc_u32 s27, s27, 0
	s_cmp_ge_i32 s65, s25
	s_mov_b32 s28, s65
	s_cbranch_scc0 .LBB0_2007
	s_and_b64 vcc, exec, s[14:15]
	s_cbranch_vccz .LBB0_2010

; #define PG8_STAGE(bufoff, gbase, voff) do { _Pragma("unroll") for (int _i = 0; _i < 2; ++_i) \
;         __builtin_amdgcn_global_load_lds((const unsigned*)((const char*)(gbase) + (voff)[_i]), (PG8_LAS unsigned*)(lds + (bufoff) + ldsw + _i * 8192), 16, 0, 0); } while (0)
; #define PG8_LDA(dst, b, h) do { _Pragma("unroll") for (int m = 0; m < 4; ++m) _Pragma("unroll") for (int k = 0; k < 2; ++k) dst[m][k] = *(const PG8_LAS bf16x8*)(lds + PG8_SA(b, h) + aoff + m * 2048 + k * 1024); } while (0)
; #define PG8_LDB(dst, b, h) do { _Pragma("unroll") for (int n = 0; n < 2; ++n) _Pragma("unroll") for (int k = 0; k < 2; ++k) dst[n][k] = *(const PG8_LAS bf16x8*)(lds + PG8_SB(b, h) + boff + n * 2048 + k * 1024); } while (0)
; #define PG8_MMA(ai, bj, At, Bt) do { __builtin_amdgcn_s_setprio(1); _Pragma("unroll") for (int m = 0; m < 4; ++m) _Pragma("unroll") for (int n = 0; n < 2; ++n) _Pragma("unroll") for (int k = 0; k < 2; ++k) \
;         acc[ai][bj][m][n] = __builtin_amdgcn_mfma_f32_16x16x32_bf16(Bt[n][k], At[m][k], acc[ai][bj][m][n], 0, 0, 0); __builtin_amdgcn_s_setprio(0); } while (0)
; #define PG8_WAIT_V(n) asm volatile("s_waitcnt vmcnt(" #n ")" ::: "memory")
; #define PG8_WAIT_L(n) do { asm volatile("s_waitcnt lgkmcnt(" #n ")" ::: "memory"); __builtin_amdgcn_s_waitcnt(0xC07F); } while (0)
; #define PG8_BAR __builtin_amdgcn_s_barrier()
; template <class Epi, class Sched, bool SEG3 = false>
; __device__ __forceinline__ void gemm_phase(PG8_LAS unsigned char* lds, const Gemm g, const Sched& S, const Epi& E) {
;     ...
;             const bool last = (t == ntc - 2);
;             const char* a1 = cA + (size_t)(t + 1) * kstep;
;             const char* a2 = last ? nA : cA + (size_t)(t + 2) * kstep; const char* b2 = last ? nB : cB + (size_t)(t + 2) * kstep;
;             const char* a3 = a2 + kstep; const char* b3 = b2 + kstep;
;             PG8_LDB(B0, 0, 0); PG8_LDB(B1, 0, 1); PG8_SCHED; PG8_LDA(At, 0, 0); PG8_STAGE(PG8_SA(1, 1), a1 + hsA, voffA);
;             PG8_WAIT_V(8); PG8_WAIT_L(0); PG8_BAR; if (cur.half != 1) { PG8_MMA(0, 0, At, B0); PG8_MMA(0, 1, At, B1); } PG8_BAR; PG8_SCHED;
;             PG8_LDA(At, 0, 1); PG8_STAGE(PG8_SB(0, 0), b2, voffB); PG8_STAGE(PG8_SB(0, 1), b2 + hsB, voffB); PG8_STAGE(PG8_SA(0, 0), a2, voffA);
;             PG8_WAIT_V(8); PG8_WAIT_L(0); PG8_BAR; if (cur.half != 0) { PG8_MMA(1, 0, At, B0); PG8_MMA(1, 1, At, B1); } PG8_BAR; PG8_SCHED;
.LBB0_2133:
	ds_read_b128 v[34:37], v207
	ds_read_b128 v[38:41], v207 offset:1024
	ds_read_b128 v[42:45], v207 offset:2048
	ds_read_b128 v[46:49], v207 offset:3072
	ds_read_b128 v[114:117], v208
	ds_read_b128 v[126:129], v208 offset:1024
	ds_read_b128 v[138:141], v208 offset:2048
	ds_read_b128 v[150:153], v208 offset:3072
	s_add_i32 s70, s40, 2
	s_add_u32 s41, s38, 0xfffc0080
	s_addc_u32 s42, s39, -1
	s_cmp_eq_u32 s64, s40
	s_cselect_b32 s40, s37, s68
	s_cselect_b32 s43, s25, s42
	s_cselect_b32 s42, s27, s41
	s_cselect_b32 s41, s35, s69
	v_lshl_add_u64 v[218:219], s[38:39], 0, v[178:179]
	s_add_i32 m0, s52, 0xc000
	ds_read_b128 v[162:165], v209
	ds_read_b128 v[166:169], v209 offset:1024
	ds_read_b128 v[186:189], v209 offset:2048
	ds_read_b128 v[190:193], v209 offset:3072
	ds_read_b128 v[194:197], v209 offset:4096
	ds_read_b128 v[198:201], v209 offset:5120
	ds_read_b128 v[202:205], v209 offset:6144
	ds_read_b128 v[214:217], v209 offset:7168
	global_load_lds_dwordx4 v[218:219], off
	s_add_i32 m0, s52, 0xe000
	v_lshl_add_u64 v[218:219], s[38:39], 0, v[180:181]
	global_load_lds_dwordx4 v[218:219], off
	s_waitcnt vmcnt(8) lgkmcnt(0)
	s_barrier
	s_setprio 1
	v_mfma_f32_16x16x32_bf16 v[158:161], v[34:37], v[162:165], v[158:161]
	v_mfma_f32_16x16x32_bf16 v[154:157], v[42:45], v[162:165], v[154:157]
	v_mfma_f32_16x16x32_bf16 v[134:137], v[34:37], v[186:189], v[134:137]
	v_mfma_f32_16x16x32_bf16 v[130:133], v[42:45], v[186:189], v[130:133]
	v_mfma_f32_16x16x32_bf16 v[110:113], v[34:37], v[194:197], v[110:113]
	v_mfma_f32_16x16x32_bf16 v[106:109], v[42:45], v[194:197], v[106:109]
	v_mfma_f32_16x16x32_bf16 v[94:97], v[34:37], v[202:205], v[94:97]
	v_mfma_f32_16x16x32_bf16 v[90:93], v[42:45], v[202:205], v[90:93]
	v_mfma_f32_16x16x32_bf16 v[158:161], v[38:41], v[166:169], v[158:161]
	v_mfma_f32_16x16x32_bf16 v[154:157], v[46:49], v[166:169], v[154:157]
	v_mfma_f32_16x16x32_bf16 v[134:137], v[38:41], v[190:193], v[134:137]
	v_mfma_f32_16x16x32_bf16 v[130:133], v[46:49], v[190:193], v[130:133]
	v_mfma_f32_16x16x32_bf16 v[110:113], v[38:41], v[198:201], v[110:113]
	v_mfma_f32_16x16x32_bf16 v[106:109], v[46:49], v[198:201], v[106:109]
	v_mfma_f32_16x16x32_bf16 v[94:97], v[38:41], v[214:217], v[94:97]
	v_mfma_f32_16x16x32_bf16 v[90:93], v[46:49], v[214:217], v[90:93]
	s_setprio 0
	s_setprio 1
	v_mfma_f32_16x16x32_bf16 v[146:149], v[114:117], v[162:165], v[146:149]
	v_mfma_f32_16x16x32_bf16 v[142:145], v[138:141], v[162:165], v[142:145]
	v_mfma_f32_16x16x32_bf16 v[122:125], v[114:117], v[186:189], v[122:125]
	v_mfma_f32_16x16x32_bf16 v[118:121], v[138:141], v[186:189], v[118:121]
	v_mfma_f32_16x16x32_bf16 v[102:105], v[114:117], v[194:197], v[102:105]
	v_mfma_f32_16x16x32_bf16 v[98:101], v[138:141], v[194:197], v[98:101]
	v_mfma_f32_16x16x32_bf16 v[86:89], v[114:117], v[202:205], v[86:89]
	v_mfma_f32_16x16x32_bf16 v[82:85], v[138:141], v[202:205], v[82:85]
	v_mfma_f32_16x16x32_bf16 v[146:149], v[126:129], v[166:169], v[146:149]
	v_mfma_f32_16x16x32_bf16 v[142:145], v[150:153], v[166:169], v[142:145]
	v_mfma_f32_16x16x32_bf16 v[122:125], v[126:129], v[190:193], v[122:125]
	v_mfma_f32_16x16x32_bf16 v[118:121], v[150:153], v[190:193], v[118:121]
	v_mfma_f32_16x16x32_bf16 v[102:105], v[126:129], v[198:201], v[102:105]
	v_mfma_f32_16x16x32_bf16 v[98:101], v[150:153], v[198:201], v[98:101]
	v_mfma_f32_16x16x32_bf16 v[86:89], v[126:129], v[214:217], v[86:89]
	v_mfma_f32_16x16x32_bf16 v[82:85], v[150:153], v[214:217], v[82:85]
	s_setprio 0
	s_barrier
	s_mov_b32 m0, s48
	v_lshl_add_u64 v[218:219], s[40:41], 0, v[172:173]
	s_add_u32 s72, s40, 0x40000
	ds_read_b128 v[162:165], v209 offset:16384
	ds_read_b128 v[166:169], v209 offset:17408
	ds_read_b128 v[186:189], v209 offset:18432
	ds_read_b128 v[190:193], v209 offset:19456
	ds_read_b128 v[194:197], v209 offset:20480
	ds_read_b128 v[198:201], v209 offset:21504
	ds_read_b128 v[202:205], v209 offset:22528
	ds_read_b128 v[214:217], v209 offset:23552
	global_load_lds_dwordx4 v[218:219], off
	v_lshl_add_u64 v[220:221], s[40:41], 0, v[176:177]
	s_mov_b32 m0, s49
	s_addc_u32 s73, s41, 0
	global_load_lds_dwordx4 v[220:221], off
	v_lshl_add_u64 v[222:223], s[72:73], 0, v[172:173]
	s_mov_b32 m0, s50
	v_lshl_add_u64 v[224:225], s[42:43], 0, v[174:175]
	global_load_lds_dwordx4 v[222:223], off
	s_mov_b32 m0, s51
	v_lshl_add_u64 v[222:223], s[72:73], 0, v[176:177]
	global_load_lds_dwordx4 v[222:223], off
	s_mov_b32 m0, s52
	v_lshl_add_u64 v[222:223], s[42:43], 0, v[170:171]
	global_load_lds_dwordx4 v[222:223], off
	s_mov_b32 m0, s53
	s_nop 0
	global_load_lds_dwordx4 v[224:225], off
	s_waitcnt vmcnt(8) lgkmcnt(0)
	s_barrier
; #define PG8_STAGE(bufoff, gbase, voff) do { _Pragma("unroll") for (int _i = 0; _i < 2; ++_i) \
;         __builtin_amdgcn_global_load_lds((const unsigned*)((const char*)(gbase) + (voff)[_i]), (PG8_LAS unsigned*)(lds + (bufoff) + ldsw + _i * 8192), 16, 0, 0); } while (0)
; #define PG8_LDA(dst, b, h) do { _Pragma("unroll") for (int m = 0; m < 4; ++m) _Pragma("unroll") for (int k = 0; k < 2; ++k) dst[m][k] = *(const PG8_LAS bf16x8*)(lds + PG8_SA(b, h) + aoff + m * 2048 + k * 1024); } while (0)
; #define PG8_LDB(dst, b, h) do { _Pragma("unroll") for (int n = 0; n < 2; ++n) _Pragma("unroll") for (int k = 0; k < 2; ++k) dst[n][k] = *(const PG8_LAS bf16x8*)(lds + PG8_SB(b, h) + boff + n * 2048 + k * 1024); } while (0)
; #define PG8_MMA(ai, bj, At, Bt) do { __builtin_amdgcn_s_setprio(1); _Pragma("unroll") for (int m = 0; m < 4; ++m) _Pragma("unroll") for (int n = 0; n < 2; ++n) _Pragma("unroll") for (int k = 0; k < 2; ++k) \
;         acc[ai][bj][m][n] = __builtin_amdgcn_mfma_f32_16x16x32_bf16(Bt[n][k], At[m][k], acc[ai][bj][m][n], 0, 0, 0); __builtin_amdgcn_s_setprio(0); } while (0)
; #define PG8_WAIT_V(n) asm volatile("s_waitcnt vmcnt(" #n ")" ::: "memory")
; #define PG8_WAIT_L(n) do { asm volatile("s_waitcnt lgkmcnt(" #n ")" ::: "memory"); __builtin_amdgcn_s_waitcnt(0xC07F); } while (0)
; #define PG8_BAR __builtin_amdgcn_s_barrier()
; #define PG8_SCHED __builtin_amdgcn_sched_barrier(0)
; template <class Epi, class Sched, bool SEG3 = false>
; __device__ __forceinline__ void gemm_phase(PG8_LAS unsigned char* lds, const Gemm g, const Sched& S, const Epi& E) {
;     ...
;             PG8_WAIT_V(8); PG8_WAIT_L(0); PG8_BAR; if (cur.half != 0) { PG8_MMA(1, 0, At, B0); PG8_MMA(1, 1, At, B1); } PG8_BAR; PG8_SCHED;
;             PG8_LDB(B0, 1, 0); PG8_LDB(B1, 1, 1); PG8_SCHED; PG8_LDA(At, 1, 0); PG8_STAGE(PG8_SA(0, 1), a2 + hsA, voffA);
;             PG8_WAIT_V(8); PG8_WAIT_L(0); PG8_BAR; if (cur.half != 1) { PG8_MMA(0, 0, At, B0); PG8_MMA(0, 1, At, B1); } PG8_BAR; PG8_SCHED;
	s_setprio 1
	v_mfma_f32_16x16x32_bf16 v[78:81], v[34:37], v[162:165], v[78:81]
	v_mfma_f32_16x16x32_bf16 v[74:77], v[42:45], v[162:165], v[74:77]
	v_mfma_f32_16x16x32_bf16 v[62:65], v[34:37], v[186:189], v[62:65]
	v_mfma_f32_16x16x32_bf16 v[58:61], v[42:45], v[186:189], v[58:61]
	v_mfma_f32_16x16x32_bf16 v[30:33], v[34:37], v[194:197], v[30:33]
	v_mfma_f32_16x16x32_bf16 v[26:29], v[42:45], v[194:197], v[26:29]
	v_mfma_f32_16x16x32_bf16 v[14:17], v[34:37], v[202:205], v[14:17]
	v_mfma_f32_16x16x32_bf16 v[10:13], v[42:45], v[202:205], v[10:13]
	v_mfma_f32_16x16x32_bf16 v[78:81], v[38:41], v[166:169], v[78:81]
	v_mfma_f32_16x16x32_bf16 v[74:77], v[46:49], v[166:169], v[74:77]
	v_mfma_f32_16x16x32_bf16 v[62:65], v[38:41], v[190:193], v[62:65]
	v_mfma_f32_16x16x32_bf16 v[58:61], v[46:49], v[190:193], v[58:61]
	v_mfma_f32_16x16x32_bf16 v[30:33], v[38:41], v[198:201], v[30:33]
	v_mfma_f32_16x16x32_bf16 v[26:29], v[46:49], v[198:201], v[26:29]
	v_mfma_f32_16x16x32_bf16 v[14:17], v[38:41], v[214:217], v[14:17]
	v_mfma_f32_16x16x32_bf16 v[10:13], v[46:49], v[214:217], v[10:13]
	s_setprio 0
	s_setprio 1
	v_mfma_f32_16x16x32_bf16 v[22:25], v[114:117], v[194:197], v[22:25]
	v_mfma_f32_16x16x32_bf16 v[18:21], v[138:141], v[194:197], v[18:21]
	v_mfma_f32_16x16x32_bf16 v[6:9], v[114:117], v[202:205], v[6:9]
	v_mfma_f32_16x16x32_bf16 v[2:5], v[138:141], v[202:205], v[2:5]
	v_mfma_f32_16x16x32_bf16 v[34:37], v[114:117], v[162:165], v[70:73]
	v_mfma_f32_16x16x32_bf16 v[38:41], v[138:141], v[162:165], v[66:69]
	v_mfma_f32_16x16x32_bf16 v[42:45], v[114:117], v[186:189], v[54:57]
	v_mfma_f32_16x16x32_bf16 v[46:49], v[138:141], v[186:189], v[50:53]
	v_mfma_f32_16x16x32_bf16 v[22:25], v[126:129], v[198:201], v[22:25]
	v_mfma_f32_16x16x32_bf16 v[18:21], v[150:153], v[198:201], v[18:21]
	v_mfma_f32_16x16x32_bf16 v[6:9], v[126:129], v[214:217], v[6:9]
	v_mfma_f32_16x16x32_bf16 v[2:5], v[150:153], v[214:217], v[2:5]
	v_mfma_f32_16x16x32_bf16 v[34:37], v[126:129], v[166:169], v[34:37]
	v_mfma_f32_16x16x32_bf16 v[38:41], v[150:153], v[166:169], v[38:41]
	v_mfma_f32_16x16x32_bf16 v[42:45], v[126:129], v[190:193], v[42:45]
	v_mfma_f32_16x16x32_bf16 v[46:49], v[150:153], v[190:193], v[46:49]
	s_setprio 0
	s_barrier
	ds_read_b128 v[50:53], v210
	ds_read_b128 v[54:57], v210 offset:1024
	ds_read_b128 v[66:69], v210 offset:2048
	ds_read_b128 v[70:73], v210 offset:3072
	ds_read_b128 v[114:117], v211
	ds_read_b128 v[126:129], v211 offset:1024
	ds_read_b128 v[138:141], v211 offset:2048
	ds_read_b128 v[150:153], v211 offset:3072
	s_add_u32 s42, s42, 0x40000
	s_addc_u32 s43, s43, 0
	s_mov_b32 m0, s54
	v_lshl_add_u64 v[226:227], s[42:43], 0, v[170:171]
	ds_read_b128 v[162:165], v209 offset:32768
	ds_read_b128 v[166:169], v209 offset:33792
	ds_read_b128 v[186:189], v209 offset:34816
	ds_read_b128 v[190:193], v209 offset:35840
	ds_read_b128 v[194:197], v209 offset:36864
	ds_read_b128 v[198:201], v209 offset:37888
	ds_read_b128 v[202:205], v209 offset:38912
	ds_read_b128 v[214:217], v209 offset:39936
	global_load_lds_dwordx4 v[226:227], off
	s_mov_b32 m0, s55
	v_lshl_add_u64 v[226:227], s[42:43], 0, v[174:175]
	global_load_lds_dwordx4 v[226:227], off
	s_waitcnt vmcnt(8) lgkmcnt(0)
	s_barrier
	s_setprio 1
	v_mfma_f32_16x16x32_bf16 v[158:161], v[50:53], v[162:165], v[158:161]
	v_mfma_f32_16x16x32_bf16 v[154:157], v[66:69], v[162:165], v[154:157]
	v_mfma_f32_16x16x32_bf16 v[134:137], v[50:53], v[186:189], v[134:137]
	v_mfma_f32_16x16x32_bf16 v[130:133], v[66:69], v[186:189], v[130:133]
	v_mfma_f32_16x16x32_bf16 v[110:113], v[50:53], v[194:197], v[110:113]
	v_mfma_f32_16x16x32_bf16 v[106:109], v[66:69], v[194:197], v[106:109]
	v_mfma_f32_16x16x32_bf16 v[94:97], v[50:53], v[202:205], v[94:97]
	v_mfma_f32_16x16x32_bf16 v[90:93], v[66:69], v[202:205], v[90:93]
	v_mfma_f32_16x16x32_bf16 v[158:161], v[54:57], v[166:169], v[158:161]
	v_mfma_f32_16x16x32_bf16 v[154:157], v[70:73], v[166:169], v[154:157]
	v_mfma_f32_16x16x32_bf16 v[134:137], v[54:57], v[190:193], v[134:137]
	v_mfma_f32_16x16x32_bf16 v[130:133], v[70:73], v[190:193], v[130:133]
	v_mfma_f32_16x16x32_bf16 v[110:113], v[54:57], v[198:201], v[110:113]
	v_mfma_f32_16x16x32_bf16 v[106:109], v[70:73], v[198:201], v[106:109]
	v_mfma_f32_16x16x32_bf16 v[94:97], v[54:57], v[214:217], v[94:97]
	v_mfma_f32_16x16x32_bf16 v[90:93], v[70:73], v[214:217], v[90:93]
	s_setprio 0
	s_setprio 1
	v_mfma_f32_16x16x32_bf16 v[146:149], v[114:117], v[162:165], v[146:149]
	v_mfma_f32_16x16x32_bf16 v[142:145], v[138:141], v[162:165], v[142:145]
	v_mfma_f32_16x16x32_bf16 v[122:125], v[114:117], v[186:189], v[122:125]
	v_mfma_f32_16x16x32_bf16 v[118:121], v[138:141], v[186:189], v[118:121]
	v_mfma_f32_16x16x32_bf16 v[102:105], v[114:117], v[194:197], v[102:105]
	v_mfma_f32_16x16x32_bf16 v[98:101], v[138:141], v[194:197], v[98:101]
	v_mfma_f32_16x16x32_bf16 v[86:89], v[114:117], v[202:205], v[86:89]
	v_mfma_f32_16x16x32_bf16 v[82:85], v[138:141], v[202:205], v[82:85]
	v_mfma_f32_16x16x32_bf16 v[146:149], v[126:129], v[166:169], v[146:149]
	v_mfma_f32_16x16x32_bf16 v[142:145], v[150:153], v[166:169], v[142:145]
	v_mfma_f32_16x16x32_bf16 v[122:125], v[126:129], v[190:193], v[122:125]
	v_mfma_f32_16x16x32_bf16 v[118:121], v[150:153], v[190:193], v[118:121]
	v_mfma_f32_16x16x32_bf16 v[102:105], v[126:129], v[198:201], v[102:105]
	v_mfma_f32_16x16x32_bf16 v[98:101], v[150:153], v[198:201], v[98:101]
	v_mfma_f32_16x16x32_bf16 v[86:89], v[126:129], v[214:217], v[86:89]
	v_mfma_f32_16x16x32_bf16 v[82:85], v[150:153], v[214:217], v[82:85]
	s_setprio 0
	s_barrier
; #define PG8_STAGE(bufoff, gbase, voff) do { _Pragma("unroll") for (int _i = 0; _i < 2; ++_i) \
;         __builtin_amdgcn_global_load_lds((const unsigned*)((const char*)(gbase) + (voff)[_i]), (PG8_LAS unsigned*)(lds + (bufoff) + ldsw + _i * 8192), 16, 0, 0); } while (0)
; #define PG8_LDA(dst, b, h) do { _Pragma("unroll") for (int m = 0; m < 4; ++m) _Pragma("unroll") for (int k = 0; k < 2; ++k) dst[m][k] = *(const PG8_LAS bf16x8*)(lds + PG8_SA(b, h) + aoff + m * 2048 + k * 1024); } while (0)
; #define PG8_MMA(ai, bj, At, Bt) do { __builtin_amdgcn_s_setprio(1); _Pragma("unroll") for (int m = 0; m < 4; ++m) _Pragma("unroll") for (int n = 0; n < 2; ++n) _Pragma("unroll") for (int k = 0; k < 2; ++k) \
;         acc[ai][bj][m][n] = __builtin_amdgcn_mfma_f32_16x16x32_bf16(Bt[n][k], At[m][k], acc[ai][bj][m][n], 0, 0, 0); __builtin_amdgcn_s_setprio(0); } while (0)
; #define PG8_WAIT_V(n) asm volatile("s_waitcnt vmcnt(" #n ")" ::: "memory")
; #define PG8_WAIT_L(n) do { asm volatile("s_waitcnt lgkmcnt(" #n ")" ::: "memory"); __builtin_amdgcn_s_waitcnt(0xC07F); } while (0)
; #define PG8_BAR __builtin_amdgcn_s_barrier()
; #define PG8_SCHED __builtin_amdgcn_sched_barrier(0)
; template <class Epi, class Sched, bool SEG3 = false>
; __device__ __forceinline__ void gemm_phase(PG8_LAS unsigned char* lds, const Gemm g, const Sched& S, const Epi& E) {
;     ...
;             PG8_LDA(At, 1, 1); PG8_STAGE(PG8_SB(1, 0), b3, voffB); PG8_STAGE(PG8_SB(1, 1), b3 + hsB, voffB); PG8_STAGE(PG8_SA(1, 0), a3, voffA);
;             PG8_WAIT_V(8); PG8_WAIT_L(0); PG8_BAR; if (cur.half != 0) { PG8_MMA(1, 0, At, B0); PG8_MMA(1, 1, At, B1); } PG8_BAR; PG8_SCHED;
;         }
	s_mov_b32 m0, s58
	v_lshl_add_u64 v[218:219], v[218:219], 0, s[18:19]
	s_add_u32 s40, s40, 0x40080
	ds_read_b128 v[162:165], v209 offset:49152
	ds_read_b128 v[166:169], v209 offset:50176
	ds_read_b128 v[186:189], v209 offset:51200
	ds_read_b128 v[190:193], v209 offset:52224
	ds_read_b128 v[194:197], v209 offset:53248
	ds_read_b128 v[198:201], v209 offset:54272
	ds_read_b128 v[202:205], v209 offset:55296
	ds_read_b128 v[214:217], v209 offset:56320
	global_load_lds_dwordx4 v[218:219], off
	v_lshl_add_u64 v[218:219], v[220:221], 0, s[18:19]
	s_mov_b32 m0, s59
	s_addc_u32 s41, s41, 0
	global_load_lds_dwordx4 v[218:219], off
	s_mov_b32 m0, s62
	v_lshl_add_u64 v[218:219], s[40:41], 0, v[172:173]
	global_load_lds_dwordx4 v[218:219], off
	s_mov_b32 m0, s63
	v_lshl_add_u64 v[218:219], s[40:41], 0, v[176:177]
	global_load_lds_dwordx4 v[218:219], off
	s_mov_b32 m0, s60
	v_lshl_add_u64 v[218:219], v[222:223], 0, s[18:19]
	global_load_lds_dwordx4 v[218:219], off
	s_mov_b32 m0, s61
	v_lshl_add_u64 v[218:219], v[224:225], 0, s[18:19]
	global_load_lds_dwordx4 v[218:219], off
	s_waitcnt vmcnt(8) lgkmcnt(0)
	s_barrier
	s_setprio 1
	v_mfma_f32_16x16x32_bf16 v[78:81], v[50:53], v[162:165], v[78:81]
	v_mfma_f32_16x16x32_bf16 v[74:77], v[66:69], v[162:165], v[74:77]
	v_mfma_f32_16x16x32_bf16 v[62:65], v[50:53], v[186:189], v[62:65]
	v_mfma_f32_16x16x32_bf16 v[58:61], v[66:69], v[186:189], v[58:61]
	v_mfma_f32_16x16x32_bf16 v[30:33], v[50:53], v[194:197], v[30:33]
	v_mfma_f32_16x16x32_bf16 v[26:29], v[66:69], v[194:197], v[26:29]
	v_mfma_f32_16x16x32_bf16 v[14:17], v[50:53], v[202:205], v[14:17]
	v_mfma_f32_16x16x32_bf16 v[10:13], v[66:69], v[202:205], v[10:13]
	v_mfma_f32_16x16x32_bf16 v[78:81], v[54:57], v[166:169], v[78:81]
	v_mfma_f32_16x16x32_bf16 v[74:77], v[70:73], v[166:169], v[74:77]
	v_mfma_f32_16x16x32_bf16 v[62:65], v[54:57], v[190:193], v[62:65]
	v_mfma_f32_16x16x32_bf16 v[58:61], v[70:73], v[190:193], v[58:61]
	v_mfma_f32_16x16x32_bf16 v[30:33], v[54:57], v[198:201], v[30:33]
	v_mfma_f32_16x16x32_bf16 v[26:29], v[70:73], v[198:201], v[26:29]
	v_mfma_f32_16x16x32_bf16 v[14:17], v[54:57], v[214:217], v[14:17]
	v_mfma_f32_16x16x32_bf16 v[10:13], v[70:73], v[214:217], v[10:13]
	s_setprio 0
	s_setprio 1
	v_mfma_f32_16x16x32_bf16 v[34:37], v[114:117], v[162:165], v[34:37]
	v_mfma_f32_16x16x32_bf16 v[70:73], v[126:129], v[166:169], v[34:37]
	v_mfma_f32_16x16x32_bf16 v[34:37], v[138:141], v[162:165], v[38:41]
	v_mfma_f32_16x16x32_bf16 v[66:69], v[150:153], v[166:169], v[34:37]
	v_mfma_f32_16x16x32_bf16 v[34:37], v[114:117], v[186:189], v[42:45]
	v_mfma_f32_16x16x32_bf16 v[54:57], v[126:129], v[190:193], v[34:37]
	v_mfma_f32_16x16x32_bf16 v[34:37], v[138:141], v[186:189], v[46:49]
	v_mfma_f32_16x16x32_bf16 v[22:25], v[114:117], v[194:197], v[22:25]
	v_mfma_f32_16x16x32_bf16 v[18:21], v[138:141], v[194:197], v[18:21]
	v_mfma_f32_16x16x32_bf16 v[6:9], v[114:117], v[202:205], v[6:9]
	v_mfma_f32_16x16x32_bf16 v[2:5], v[138:141], v[202:205], v[2:5]
	v_mfma_f32_16x16x32_bf16 v[50:53], v[150:153], v[190:193], v[34:37]
	v_mfma_f32_16x16x32_bf16 v[22:25], v[126:129], v[198:201], v[22:25]
	v_mfma_f32_16x16x32_bf16 v[18:21], v[150:153], v[198:201], v[18:21]
	v_mfma_f32_16x16x32_bf16 v[6:9], v[126:129], v[214:217], v[6:9]
	v_mfma_f32_16x16x32_bf16 v[2:5], v[150:153], v[214:217], v[2:5]
	s_setprio 0
	s_barrier
	s_add_u32 s38, s38, 0x100
	s_addc_u32 s39, s39, 0
	s_add_u32 s68, s68, 0x100
	s_addc_u32 s69, s69, 0
	s_cmp_ge_i32 s70, s57
	s_mov_b32 s40, s70
	s_cbranch_scc0 .LBB0_2133
	s_and_b64 vcc, exec, s[22:23]
	s_cbranch_vccz .LBB0_2136

; #define PG8_STAGE(bufoff, gbase, voff) do { _Pragma("unroll") for (int _i = 0; _i < 2; ++_i) \
;         __builtin_amdgcn_global_load_lds((const unsigned*)((const char*)(gbase) + (voff)[_i]), (PG8_LAS unsigned*)(lds + (bufoff) + ldsw + _i * 8192), 16, 0, 0); } while (0)
; #define PG8_LDA(dst, b, h) do { _Pragma("unroll") for (int m = 0; m < 4; ++m) _Pragma("unroll") for (int k = 0; k < 2; ++k) dst[m][k] = *(const PG8_LAS bf16x8*)(lds + PG8_SA(b, h) + aoff + m * 2048 + k * 1024); } while (0)
; #define PG8_LDB(dst, b, h) do { _Pragma("unroll") for (int n = 0; n < 2; ++n) _Pragma("unroll") for (int k = 0; k < 2; ++k) dst[n][k] = *(const PG8_LAS bf16x8*)(lds + PG8_SB(b, h) + boff + n * 2048 + k * 1024); } while (0)
; #define PG8_MMA(ai, bj, At, Bt) do { __builtin_amdgcn_s_setprio(1); _Pragma("unroll") for (int m = 0; m < 4; ++m) _Pragma("unroll") for (int n = 0; n < 2; ++n) _Pragma("unroll") for (int k = 0; k < 2; ++k) \
;         acc[ai][bj][m][n] = __builtin_amdgcn_mfma_f32_16x16x32_bf16(Bt[n][k], At[m][k], acc[ai][bj][m][n], 0, 0, 0); __builtin_amdgcn_s_setprio(0); } while (0)
; #define PG8_WAIT_V(n) asm volatile("s_waitcnt vmcnt(" #n ")" ::: "memory")
; #define PG8_WAIT_L(n) do { asm volatile("s_waitcnt lgkmcnt(" #n ")" ::: "memory"); __builtin_amdgcn_s_waitcnt(0xC07F); } while (0)
; #define PG8_BAR __builtin_amdgcn_s_barrier()
; template <class Epi, class Sched, bool SEG3 = false>
; __device__ __forceinline__ void gemm_phase(PG8_LAS unsigned char* lds, const Gemm g, const Sched& S, const Epi& E) {
;     ...
;             const bool last = (t == ntc - 2);
;             const char* a1 = cA + (size_t)(t + 1) * kstep;
;             const char* a2 = last ? nA : cA + (size_t)(t + 2) * kstep; const char* b2 = last ? nB : cB + (size_t)(t + 2) * kstep;
;             const char* a3 = a2 + kstep; const char* b3 = b2 + kstep;
;             PG8_LDB(B0, 0, 0); PG8_LDB(B1, 0, 1); PG8_SCHED; PG8_LDA(At, 0, 0); PG8_STAGE(PG8_SA(1, 1), a1 + hsA, voffA);
;             PG8_WAIT_V(8); PG8_WAIT_L(0); PG8_BAR; if (cur.half != 1) { PG8_MMA(0, 0, At, B0); PG8_MMA(0, 1, At, B1); } PG8_BAR; PG8_SCHED;
;             PG8_LDA(At, 0, 1); PG8_STAGE(PG8_SB(0, 0), b2, voffB); PG8_STAGE(PG8_SB(0, 1), b2 + hsB, voffB); PG8_STAGE(PG8_SA(0, 0), a2, voffA);
;             PG8_WAIT_V(8); PG8_WAIT_L(0); PG8_BAR; if (cur.half != 0) { PG8_MMA(1, 0, At, B0); PG8_MMA(1, 1, At, B1); } PG8_BAR; PG8_SCHED;
.LBB0_2579:
	ds_read_b128 v[98:101], v199
	ds_read_b128 v[110:113], v199 offset:1024
	ds_read_b128 v[122:125], v199 offset:2048
	ds_read_b128 v[134:137], v199 offset:3072
	ds_read_b128 v[146:149], v200
	ds_read_b128 v[150:153], v200 offset:1024
	ds_read_b128 v[170:173], v200 offset:2048
	ds_read_b128 v[174:177], v200 offset:3072
	s_add_i32 s68, s34, 2
	s_add_u32 s30, s28, 0x100
	s_addc_u32 s31, s29, 0
	s_cmp_eq_u32 s58, s34
	s_cselect_b32 s34, s8, s66
	s_cselect_b32 s37, s27, s31
	s_cselect_b32 s36, s26, s30
	s_cselect_b32 s35, s9, s67
	v_lshl_add_u64 v[218:219], s[28:29], 0, v[162:163]
	s_add_i32 m0, s46, 0xc000
	ds_read_b128 v[178:181], v201
	ds_read_b128 v[182:185], v201 offset:1024
	ds_read_b128 v[186:189], v201 offset:2048
	ds_read_b128 v[190:193], v201 offset:3072
	ds_read_b128 v[194:197], v201 offset:4096
	ds_read_b128 v[206:209], v201 offset:5120
	ds_read_b128 v[210:213], v201 offset:6144
	ds_read_b128 v[214:217], v201 offset:7168
	global_load_lds_dwordx4 v[218:219], off
	s_add_i32 m0, s46, 0xe000
	v_lshl_add_u64 v[218:219], s[28:29], 0, v[164:165]
	global_load_lds_dwordx4 v[218:219], off
	s_waitcnt vmcnt(8) lgkmcnt(0)
	s_barrier
	s_setprio 1
	v_mfma_f32_16x16x32_bf16 v[142:145], v[98:101], v[178:181], v[142:145]
	v_mfma_f32_16x16x32_bf16 v[138:141], v[122:125], v[178:181], v[138:141]
	v_mfma_f32_16x16x32_bf16 v[118:121], v[98:101], v[186:189], v[118:121]
	v_mfma_f32_16x16x32_bf16 v[114:117], v[122:125], v[186:189], v[114:117]
	v_mfma_f32_16x16x32_bf16 v[94:97], v[98:101], v[194:197], v[94:97]
	v_mfma_f32_16x16x32_bf16 v[90:93], v[122:125], v[194:197], v[90:93]
	v_mfma_f32_16x16x32_bf16 v[78:81], v[98:101], v[210:213], v[78:81]
	v_mfma_f32_16x16x32_bf16 v[74:77], v[122:125], v[210:213], v[74:77]
	v_mfma_f32_16x16x32_bf16 v[142:145], v[110:113], v[182:185], v[142:145]
	v_mfma_f32_16x16x32_bf16 v[138:141], v[134:137], v[182:185], v[138:141]
	v_mfma_f32_16x16x32_bf16 v[118:121], v[110:113], v[190:193], v[118:121]
	v_mfma_f32_16x16x32_bf16 v[114:117], v[134:137], v[190:193], v[114:117]
	v_mfma_f32_16x16x32_bf16 v[94:97], v[110:113], v[206:209], v[94:97]
	v_mfma_f32_16x16x32_bf16 v[90:93], v[134:137], v[206:209], v[90:93]
	v_mfma_f32_16x16x32_bf16 v[78:81], v[110:113], v[214:217], v[78:81]
	v_mfma_f32_16x16x32_bf16 v[74:77], v[134:137], v[214:217], v[74:77]
	s_setprio 0
	s_setprio 1
	v_mfma_f32_16x16x32_bf16 v[130:133], v[146:149], v[178:181], v[130:133]
	v_mfma_f32_16x16x32_bf16 v[126:129], v[170:173], v[178:181], v[126:129]
	v_mfma_f32_16x16x32_bf16 v[106:109], v[146:149], v[186:189], v[106:109]
	v_mfma_f32_16x16x32_bf16 v[102:105], v[170:173], v[186:189], v[102:105]
	v_mfma_f32_16x16x32_bf16 v[86:89], v[146:149], v[194:197], v[86:89]
	v_mfma_f32_16x16x32_bf16 v[82:85], v[170:173], v[194:197], v[82:85]
	v_mfma_f32_16x16x32_bf16 v[70:73], v[146:149], v[210:213], v[70:73]
	v_mfma_f32_16x16x32_bf16 v[66:69], v[170:173], v[210:213], v[66:69]
	v_mfma_f32_16x16x32_bf16 v[130:133], v[150:153], v[182:185], v[130:133]
	v_mfma_f32_16x16x32_bf16 v[126:129], v[174:177], v[182:185], v[126:129]
	v_mfma_f32_16x16x32_bf16 v[106:109], v[150:153], v[190:193], v[106:109]
	v_mfma_f32_16x16x32_bf16 v[102:105], v[174:177], v[190:193], v[102:105]
	v_mfma_f32_16x16x32_bf16 v[86:89], v[150:153], v[206:209], v[86:89]
	v_mfma_f32_16x16x32_bf16 v[82:85], v[174:177], v[206:209], v[82:85]
	v_mfma_f32_16x16x32_bf16 v[70:73], v[150:153], v[214:217], v[70:73]
	v_mfma_f32_16x16x32_bf16 v[66:69], v[174:177], v[214:217], v[66:69]
	s_setprio 0
	s_barrier
	s_mov_b32 m0, s42
	v_lshl_add_u64 v[218:219], s[34:35], 0, v[156:157]
	s_add_u32 s28, s34, 0xb0000
	ds_read_b128 v[178:181], v201 offset:16384
	ds_read_b128 v[182:185], v201 offset:17408
	ds_read_b128 v[186:189], v201 offset:18432
	ds_read_b128 v[190:193], v201 offset:19456
	ds_read_b128 v[194:197], v201 offset:20480
	ds_read_b128 v[206:209], v201 offset:21504
	ds_read_b128 v[210:213], v201 offset:22528
	ds_read_b128 v[214:217], v201 offset:23552
	global_load_lds_dwordx4 v[218:219], off
	v_lshl_add_u64 v[220:221], s[34:35], 0, v[160:161]
	s_mov_b32 m0, s43
	s_addc_u32 s29, s35, 0
	global_load_lds_dwordx4 v[220:221], off
	v_lshl_add_u64 v[222:223], s[28:29], 0, v[156:157]
	s_mov_b32 m0, s44
	v_lshl_add_u64 v[224:225], s[36:37], 0, v[158:159]
	global_load_lds_dwordx4 v[222:223], off
	s_mov_b32 m0, s45
	v_lshl_add_u64 v[222:223], s[28:29], 0, v[160:161]
	global_load_lds_dwordx4 v[222:223], off
	s_mov_b32 m0, s46
	v_lshl_add_u64 v[222:223], s[36:37], 0, v[154:155]
	global_load_lds_dwordx4 v[222:223], off
	s_mov_b32 m0, s47
	s_nop 0
	global_load_lds_dwordx4 v[224:225], off
	s_waitcnt vmcnt(8) lgkmcnt(0)
	s_barrier
; #define PG8_STAGE(bufoff, gbase, voff) do { _Pragma("unroll") for (int _i = 0; _i < 2; ++_i) \
;         __builtin_amdgcn_global_load_lds((const unsigned*)((const char*)(gbase) + (voff)[_i]), (PG8_LAS unsigned*)(lds + (bufoff) + ldsw + _i * 8192), 16, 0, 0); } while (0)
; #define PG8_LDA(dst, b, h) do { _Pragma("unroll") for (int m = 0; m < 4; ++m) _Pragma("unroll") for (int k = 0; k < 2; ++k) dst[m][k] = *(const PG8_LAS bf16x8*)(lds + PG8_SA(b, h) + aoff + m * 2048 + k * 1024); } while (0)
; #define PG8_LDB(dst, b, h) do { _Pragma("unroll") for (int n = 0; n < 2; ++n) _Pragma("unroll") for (int k = 0; k < 2; ++k) dst[n][k] = *(const PG8_LAS bf16x8*)(lds + PG8_SB(b, h) + boff + n * 2048 + k * 1024); } while (0)
; #define PG8_MMA(ai, bj, At, Bt) do { __builtin_amdgcn_s_setprio(1); _Pragma("unroll") for (int m = 0; m < 4; ++m) _Pragma("unroll") for (int n = 0; n < 2; ++n) _Pragma("unroll") for (int k = 0; k < 2; ++k) \
;         acc[ai][bj][m][n] = __builtin_amdgcn_mfma_f32_16x16x32_bf16(Bt[n][k], At[m][k], acc[ai][bj][m][n], 0, 0, 0); __builtin_amdgcn_s_setprio(0); } while (0)
; #define PG8_WAIT_V(n) asm volatile("s_waitcnt vmcnt(" #n ")" ::: "memory")
; #define PG8_WAIT_L(n) do { asm volatile("s_waitcnt lgkmcnt(" #n ")" ::: "memory"); __builtin_amdgcn_s_waitcnt(0xC07F); } while (0)
; #define PG8_BAR __builtin_amdgcn_s_barrier()
; #define PG8_SCHED __builtin_amdgcn_sched_barrier(0)
; template <class Epi, class Sched, bool SEG3 = false>
; __device__ __forceinline__ void gemm_phase(PG8_LAS unsigned char* lds, const Gemm g, const Sched& S, const Epi& E) {
;     ...
;             PG8_WAIT_V(8); PG8_WAIT_L(0); PG8_BAR; if (cur.half != 0) { PG8_MMA(1, 0, At, B0); PG8_MMA(1, 1, At, B1); } PG8_BAR; PG8_SCHED;
;             PG8_LDB(B0, 1, 0); PG8_LDB(B1, 1, 1); PG8_SCHED; PG8_LDA(At, 1, 0); PG8_STAGE(PG8_SA(0, 1), a2 + hsA, voffA);
;             PG8_WAIT_V(8); PG8_WAIT_L(0); PG8_BAR; if (cur.half != 1) { PG8_MMA(0, 0, At, B0); PG8_MMA(0, 1, At, B1); } PG8_BAR; PG8_SCHED;
	s_setprio 1
	v_mfma_f32_16x16x32_bf16 v[62:65], v[98:101], v[178:181], v[62:65]
	v_mfma_f32_16x16x32_bf16 v[58:61], v[122:125], v[178:181], v[58:61]
	v_mfma_f32_16x16x32_bf16 v[46:49], v[98:101], v[186:189], v[46:49]
	v_mfma_f32_16x16x32_bf16 v[42:45], v[122:125], v[186:189], v[42:45]
	v_mfma_f32_16x16x32_bf16 v[30:33], v[98:101], v[194:197], v[30:33]
	v_mfma_f32_16x16x32_bf16 v[26:29], v[122:125], v[194:197], v[26:29]
	v_mfma_f32_16x16x32_bf16 v[14:17], v[98:101], v[210:213], v[14:17]
	v_mfma_f32_16x16x32_bf16 v[10:13], v[122:125], v[210:213], v[10:13]
	v_mfma_f32_16x16x32_bf16 v[62:65], v[110:113], v[182:185], v[62:65]
	v_mfma_f32_16x16x32_bf16 v[58:61], v[134:137], v[182:185], v[58:61]
	v_mfma_f32_16x16x32_bf16 v[46:49], v[110:113], v[190:193], v[46:49]
	v_mfma_f32_16x16x32_bf16 v[42:45], v[134:137], v[190:193], v[42:45]
	v_mfma_f32_16x16x32_bf16 v[30:33], v[110:113], v[206:209], v[30:33]
	v_mfma_f32_16x16x32_bf16 v[26:29], v[134:137], v[206:209], v[26:29]
	v_mfma_f32_16x16x32_bf16 v[14:17], v[110:113], v[214:217], v[14:17]
	v_mfma_f32_16x16x32_bf16 v[10:13], v[134:137], v[214:217], v[10:13]
	s_setprio 0
	s_setprio 1
	v_mfma_f32_16x16x32_bf16 v[54:57], v[146:149], v[178:181], v[54:57]
	v_mfma_f32_16x16x32_bf16 v[50:53], v[170:173], v[178:181], v[50:53]
	v_mfma_f32_16x16x32_bf16 v[38:41], v[146:149], v[186:189], v[38:41]
	v_mfma_f32_16x16x32_bf16 v[34:37], v[170:173], v[186:189], v[34:37]
	v_mfma_f32_16x16x32_bf16 v[22:25], v[146:149], v[194:197], v[22:25]
	v_mfma_f32_16x16x32_bf16 v[18:21], v[170:173], v[194:197], v[18:21]
	v_mfma_f32_16x16x32_bf16 v[6:9], v[146:149], v[210:213], v[6:9]
	v_mfma_f32_16x16x32_bf16 v[2:5], v[170:173], v[210:213], v[2:5]
	v_mfma_f32_16x16x32_bf16 v[54:57], v[150:153], v[182:185], v[54:57]
	v_mfma_f32_16x16x32_bf16 v[50:53], v[174:177], v[182:185], v[50:53]
	v_mfma_f32_16x16x32_bf16 v[38:41], v[150:153], v[190:193], v[38:41]
	v_mfma_f32_16x16x32_bf16 v[34:37], v[174:177], v[190:193], v[34:37]
	v_mfma_f32_16x16x32_bf16 v[22:25], v[150:153], v[206:209], v[22:25]
	v_mfma_f32_16x16x32_bf16 v[18:21], v[174:177], v[206:209], v[18:21]
	v_mfma_f32_16x16x32_bf16 v[6:9], v[150:153], v[214:217], v[6:9]
	v_mfma_f32_16x16x32_bf16 v[2:5], v[174:177], v[214:217], v[2:5]
	s_setprio 0
	s_barrier
	ds_read_b128 v[98:101], v202
	ds_read_b128 v[110:113], v202 offset:1024
	ds_read_b128 v[122:125], v202 offset:2048
	ds_read_b128 v[134:137], v202 offset:3072
	ds_read_b128 v[146:149], v203
	ds_read_b128 v[150:153], v203 offset:1024
	ds_read_b128 v[170:173], v203 offset:2048
	ds_read_b128 v[174:177], v203 offset:3072
	s_add_u32 s28, s36, 0xb0000
	s_addc_u32 s29, s37, 0
	s_mov_b32 m0, s48
	v_lshl_add_u64 v[226:227], s[28:29], 0, v[154:155]
	ds_read_b128 v[178:181], v201 offset:32768
	ds_read_b128 v[182:185], v201 offset:33792
	ds_read_b128 v[186:189], v201 offset:34816
	ds_read_b128 v[190:193], v201 offset:35840
	ds_read_b128 v[194:197], v201 offset:36864
	ds_read_b128 v[206:209], v201 offset:37888
	ds_read_b128 v[210:213], v201 offset:38912
	ds_read_b128 v[214:217], v201 offset:39936
	global_load_lds_dwordx4 v[226:227], off
	s_mov_b32 m0, s49
	v_lshl_add_u64 v[226:227], s[28:29], 0, v[158:159]
	global_load_lds_dwordx4 v[226:227], off
	s_waitcnt vmcnt(8) lgkmcnt(0)
	s_barrier
	s_setprio 1
	v_mfma_f32_16x16x32_bf16 v[142:145], v[98:101], v[178:181], v[142:145]
	v_mfma_f32_16x16x32_bf16 v[138:141], v[122:125], v[178:181], v[138:141]
	v_mfma_f32_16x16x32_bf16 v[118:121], v[98:101], v[186:189], v[118:121]
	v_mfma_f32_16x16x32_bf16 v[114:117], v[122:125], v[186:189], v[114:117]
	v_mfma_f32_16x16x32_bf16 v[94:97], v[98:101], v[194:197], v[94:97]
	v_mfma_f32_16x16x32_bf16 v[90:93], v[122:125], v[194:197], v[90:93]
	v_mfma_f32_16x16x32_bf16 v[78:81], v[98:101], v[210:213], v[78:81]
	v_mfma_f32_16x16x32_bf16 v[74:77], v[122:125], v[210:213], v[74:77]
	v_mfma_f32_16x16x32_bf16 v[142:145], v[110:113], v[182:185], v[142:145]
	v_mfma_f32_16x16x32_bf16 v[138:141], v[134:137], v[182:185], v[138:141]
	v_mfma_f32_16x16x32_bf16 v[118:121], v[110:113], v[190:193], v[118:121]
	v_mfma_f32_16x16x32_bf16 v[114:117], v[134:137], v[190:193], v[114:117]
	v_mfma_f32_16x16x32_bf16 v[94:97], v[110:113], v[206:209], v[94:97]
	v_mfma_f32_16x16x32_bf16 v[90:93], v[134:137], v[206:209], v[90:93]
	v_mfma_f32_16x16x32_bf16 v[78:81], v[110:113], v[214:217], v[78:81]
	v_mfma_f32_16x16x32_bf16 v[74:77], v[134:137], v[214:217], v[74:77]
	s_setprio 0
	s_setprio 1
	v_mfma_f32_16x16x32_bf16 v[130:133], v[146:149], v[178:181], v[130:133]
	v_mfma_f32_16x16x32_bf16 v[126:129], v[170:173], v[178:181], v[126:129]
	v_mfma_f32_16x16x32_bf16 v[106:109], v[146:149], v[186:189], v[106:109]
	v_mfma_f32_16x16x32_bf16 v[102:105], v[170:173], v[186:189], v[102:105]
	v_mfma_f32_16x16x32_bf16 v[86:89], v[146:149], v[194:197], v[86:89]
	v_mfma_f32_16x16x32_bf16 v[82:85], v[170:173], v[194:197], v[82:85]
	v_mfma_f32_16x16x32_bf16 v[70:73], v[146:149], v[210:213], v[70:73]
	v_mfma_f32_16x16x32_bf16 v[66:69], v[170:173], v[210:213], v[66:69]
	v_mfma_f32_16x16x32_bf16 v[130:133], v[150:153], v[182:185], v[130:133]
	v_mfma_f32_16x16x32_bf16 v[126:129], v[174:177], v[182:185], v[126:129]
	v_mfma_f32_16x16x32_bf16 v[106:109], v[150:153], v[190:193], v[106:109]
	v_mfma_f32_16x16x32_bf16 v[102:105], v[174:177], v[190:193], v[102:105]
	v_mfma_f32_16x16x32_bf16 v[86:89], v[150:153], v[206:209], v[86:89]
	v_mfma_f32_16x16x32_bf16 v[82:85], v[174:177], v[206:209], v[82:85]
	v_mfma_f32_16x16x32_bf16 v[70:73], v[150:153], v[214:217], v[70:73]
	v_mfma_f32_16x16x32_bf16 v[66:69], v[174:177], v[214:217], v[66:69]
	s_setprio 0
	s_barrier
; #define PG8_STAGE(bufoff, gbase, voff) do { _Pragma("unroll") for (int _i = 0; _i < 2; ++_i) \
;         __builtin_amdgcn_global_load_lds((const unsigned*)((const char*)(gbase) + (voff)[_i]), (PG8_LAS unsigned*)(lds + (bufoff) + ldsw + _i * 8192), 16, 0, 0); } while (0)
; #define PG8_LDA(dst, b, h) do { _Pragma("unroll") for (int m = 0; m < 4; ++m) _Pragma("unroll") for (int k = 0; k < 2; ++k) dst[m][k] = *(const PG8_LAS bf16x8*)(lds + PG8_SA(b, h) + aoff + m * 2048 + k * 1024); } while (0)
; #define PG8_MMA(ai, bj, At, Bt) do { __builtin_amdgcn_s_setprio(1); _Pragma("unroll") for (int m = 0; m < 4; ++m) _Pragma("unroll") for (int n = 0; n < 2; ++n) _Pragma("unroll") for (int k = 0; k < 2; ++k) \
;         acc[ai][bj][m][n] = __builtin_amdgcn_mfma_f32_16x16x32_bf16(Bt[n][k], At[m][k], acc[ai][bj][m][n], 0, 0, 0); __builtin_amdgcn_s_setprio(0); } while (0)
; #define PG8_WAIT_V(n) asm volatile("s_waitcnt vmcnt(" #n ")" ::: "memory")
; #define PG8_WAIT_L(n) do { asm volatile("s_waitcnt lgkmcnt(" #n ")" ::: "memory"); __builtin_amdgcn_s_waitcnt(0xC07F); } while (0)
; #define PG8_BAR __builtin_amdgcn_s_barrier()
; #define PG8_SCHED __builtin_amdgcn_sched_barrier(0)
; template <class Epi, class Sched, bool SEG3 = false>
; __device__ __forceinline__ void gemm_phase(PG8_LAS unsigned char* lds, const Gemm g, const Sched& S, const Epi& E) {
;     ...
;             PG8_LDA(At, 1, 1); PG8_STAGE(PG8_SB(1, 0), b3, voffB); PG8_STAGE(PG8_SB(1, 1), b3 + hsB, voffB); PG8_STAGE(PG8_SA(1, 0), a3, voffA);
;             PG8_WAIT_V(8); PG8_WAIT_L(0); PG8_BAR; if (cur.half != 0) { PG8_MMA(1, 0, At, B0); PG8_MMA(1, 1, At, B1); } PG8_BAR; PG8_SCHED;
;         }
	s_mov_b32 m0, s52
	v_lshl_add_u64 v[218:219], v[218:219], 0, s[20:21]
	s_add_u32 s28, s34, 0xb0080
	ds_read_b128 v[178:181], v201 offset:49152
	ds_read_b128 v[182:185], v201 offset:50176
	ds_read_b128 v[186:189], v201 offset:51200
	ds_read_b128 v[190:193], v201 offset:52224
	ds_read_b128 v[194:197], v201 offset:53248
	ds_read_b128 v[206:209], v201 offset:54272
	ds_read_b128 v[210:213], v201 offset:55296
	ds_read_b128 v[214:217], v201 offset:56320
	global_load_lds_dwordx4 v[218:219], off
	v_lshl_add_u64 v[218:219], v[220:221], 0, s[20:21]
	s_mov_b32 m0, s53
	s_addc_u32 s29, s35, 0
	global_load_lds_dwordx4 v[218:219], off
	s_mov_b32 m0, s56
	v_lshl_add_u64 v[218:219], s[28:29], 0, v[156:157]
	global_load_lds_dwordx4 v[218:219], off
	s_mov_b32 m0, s57
	v_lshl_add_u64 v[218:219], s[28:29], 0, v[160:161]
	global_load_lds_dwordx4 v[218:219], off
	s_mov_b32 m0, s54
	v_lshl_add_u64 v[218:219], v[222:223], 0, s[20:21]
	global_load_lds_dwordx4 v[218:219], off
	s_mov_b32 m0, s55
	v_lshl_add_u64 v[218:219], v[224:225], 0, s[20:21]
	global_load_lds_dwordx4 v[218:219], off
	s_waitcnt vmcnt(8) lgkmcnt(0)
	s_barrier
	s_setprio 1
	v_mfma_f32_16x16x32_bf16 v[62:65], v[98:101], v[178:181], v[62:65]
	v_mfma_f32_16x16x32_bf16 v[58:61], v[122:125], v[178:181], v[58:61]
	v_mfma_f32_16x16x32_bf16 v[46:49], v[98:101], v[186:189], v[46:49]
	v_mfma_f32_16x16x32_bf16 v[42:45], v[122:125], v[186:189], v[42:45]
	v_mfma_f32_16x16x32_bf16 v[30:33], v[98:101], v[194:197], v[30:33]
	v_mfma_f32_16x16x32_bf16 v[26:29], v[122:125], v[194:197], v[26:29]
	v_mfma_f32_16x16x32_bf16 v[14:17], v[98:101], v[210:213], v[14:17]
	v_mfma_f32_16x16x32_bf16 v[10:13], v[122:125], v[210:213], v[10:13]
	v_mfma_f32_16x16x32_bf16 v[62:65], v[110:113], v[182:185], v[62:65]
	v_mfma_f32_16x16x32_bf16 v[58:61], v[134:137], v[182:185], v[58:61]
	v_mfma_f32_16x16x32_bf16 v[46:49], v[110:113], v[190:193], v[46:49]
	v_mfma_f32_16x16x32_bf16 v[42:45], v[134:137], v[190:193], v[42:45]
	v_mfma_f32_16x16x32_bf16 v[30:33], v[110:113], v[206:209], v[30:33]
	v_mfma_f32_16x16x32_bf16 v[26:29], v[134:137], v[206:209], v[26:29]
	v_mfma_f32_16x16x32_bf16 v[14:17], v[110:113], v[214:217], v[14:17]
	v_mfma_f32_16x16x32_bf16 v[10:13], v[134:137], v[214:217], v[10:13]
	s_setprio 0
	s_setprio 1
	v_mfma_f32_16x16x32_bf16 v[54:57], v[146:149], v[178:181], v[54:57]
	v_mfma_f32_16x16x32_bf16 v[50:53], v[170:173], v[178:181], v[50:53]
	v_mfma_f32_16x16x32_bf16 v[38:41], v[146:149], v[186:189], v[38:41]
	v_mfma_f32_16x16x32_bf16 v[34:37], v[170:173], v[186:189], v[34:37]
	v_mfma_f32_16x16x32_bf16 v[22:25], v[146:149], v[194:197], v[22:25]
	v_mfma_f32_16x16x32_bf16 v[18:21], v[170:173], v[194:197], v[18:21]
	v_mfma_f32_16x16x32_bf16 v[6:9], v[146:149], v[210:213], v[6:9]
	v_mfma_f32_16x16x32_bf16 v[2:5], v[170:173], v[210:213], v[2:5]
	v_mfma_f32_16x16x32_bf16 v[54:57], v[150:153], v[182:185], v[54:57]
	v_mfma_f32_16x16x32_bf16 v[50:53], v[174:177], v[182:185], v[50:53]
	v_mfma_f32_16x16x32_bf16 v[38:41], v[150:153], v[190:193], v[38:41]
	v_mfma_f32_16x16x32_bf16 v[34:37], v[174:177], v[190:193], v[34:37]
	v_mfma_f32_16x16x32_bf16 v[22:25], v[150:153], v[206:209], v[22:25]
	v_mfma_f32_16x16x32_bf16 v[18:21], v[174:177], v[206:209], v[18:21]
	v_mfma_f32_16x16x32_bf16 v[6:9], v[150:153], v[214:217], v[6:9]
	v_mfma_f32_16x16x32_bf16 v[2:5], v[174:177], v[214:217], v[2:5]
	s_setprio 0
	s_barrier
	s_add_u32 s66, s66, 0x100
	s_addc_u32 s67, s67, 0
	s_cmp_lt_i32 s68, s51
	s_mov_b64 s[28:29], s[30:31]
	s_mov_b32 s34, s68
	s_cbranch_scc1 .LBB0_2579
	s_andn2_b64 vcc, exec, s[24:25]
	s_cbranch_vccnz .LBB0_2582

; #define PG8_STAGE(bufoff, gbase, voff) do { _Pragma("unroll") for (int _i = 0; _i < 2; ++_i) \
;         __builtin_amdgcn_global_load_lds((const unsigned*)((const char*)(gbase) + (voff)[_i]), (PG8_LAS unsigned*)(lds + (bufoff) + ldsw + _i * 8192), 16, 0, 0); } while (0)
; #define PG8_LDA(dst, b, h) do { _Pragma("unroll") for (int m = 0; m < 4; ++m) _Pragma("unroll") for (int k = 0; k < 2; ++k) dst[m][k] = *(const PG8_LAS bf16x8*)(lds + PG8_SA(b, h) + aoff + m * 2048 + k * 1024); } while (0)
; #define PG8_LDB(dst, b, h) do { _Pragma("unroll") for (int n = 0; n < 2; ++n) _Pragma("unroll") for (int k = 0; k < 2; ++k) dst[n][k] = *(const PG8_LAS bf16x8*)(lds + PG8_SB(b, h) + boff + n * 2048 + k * 1024); } while (0)
; #define PG8_MMA(ai, bj, At, Bt) do { __builtin_amdgcn_s_setprio(1); _Pragma("unroll") for (int m = 0; m < 4; ++m) _Pragma("unroll") for (int n = 0; n < 2; ++n) _Pragma("unroll") for (int k = 0; k < 2; ++k) \
;         acc[ai][bj][m][n] = __builtin_amdgcn_mfma_f32_16x16x32_bf16(Bt[n][k], At[m][k], acc[ai][bj][m][n], 0, 0, 0); __builtin_amdgcn_s_setprio(0); } while (0)
; #define PG8_WAIT_V(n) asm volatile("s_waitcnt vmcnt(" #n ")" ::: "memory")
; #define PG8_WAIT_L(n) do { asm volatile("s_waitcnt lgkmcnt(" #n ")" ::: "memory"); __builtin_amdgcn_s_waitcnt(0xC07F); } while (0)
; #define PG8_BAR __builtin_amdgcn_s_barrier()
; template <class Epi, class Sched, bool SEG3 = false>
; __device__ __forceinline__ void gemm_phase(PG8_LAS unsigned char* lds, const Gemm g, const Sched& S, const Epi& E) {
;     ...
;             const bool last = (t == ntc - 2);
;             const char* a1 = cA + (size_t)(t + 1) * kstep;
;             const char* a2 = last ? nA : cA + (size_t)(t + 2) * kstep; const char* b2 = last ? nB : cB + (size_t)(t + 2) * kstep;
;             const char* a3 = a2 + kstep; const char* b3 = b2 + kstep;
;             PG8_LDB(B0, 0, 0); PG8_LDB(B1, 0, 1); PG8_SCHED; PG8_LDA(At, 0, 0); PG8_STAGE(PG8_SA(1, 1), a1 + hsA, voffA);
;             PG8_WAIT_V(8); PG8_WAIT_L(0); PG8_BAR; if (cur.half != 1) { PG8_MMA(0, 0, At, B0); PG8_MMA(0, 1, At, B1); } PG8_BAR; PG8_SCHED;
;             PG8_LDA(At, 0, 1); PG8_STAGE(PG8_SB(0, 0), b2, voffB); PG8_STAGE(PG8_SB(0, 1), b2 + hsB, voffB); PG8_STAGE(PG8_SA(0, 0), a2, voffA);
;             PG8_WAIT_V(8); PG8_WAIT_L(0); PG8_BAR; if (cur.half != 0) { PG8_MMA(1, 0, At, B0); PG8_MMA(1, 1, At, B1); } PG8_BAR; PG8_SCHED;
.LBB0_2680:
	ds_read_b128 v[10:13], v185
	ds_read_b128 v[14:17], v185 offset:1024
	ds_read_b128 v[34:37], v185 offset:2048
	ds_read_b128 v[38:41], v185 offset:3072
	ds_read_b128 v[146:149], v186
	ds_read_b128 v[174:177], v186 offset:1024
	ds_read_b128 v[178:181], v186 offset:2048
	ds_read_b128 v[210:213], v186 offset:3072
	s_add_i32 s20, s10, 2
	s_add_u32 s11, s8, 0xfffc0080
	s_addc_u32 s12, s9, -1
	s_cmp_eq_u32 s84, s10
	s_cselect_b32 s10, s16, s17
	s_cselect_b32 s13, s7, s12
	s_cselect_b32 s12, s14, s11
	s_cselect_b32 s11, s15, s19
	v_lshl_add_u64 v[182:183], s[8:9], 0, v[168:169]
	s_add_i32 m0, s71, 0xc000
	ds_read_b128 v[214:217], v187
	ds_read_b128 v[218:221], v187 offset:1024
	ds_read_b128 v[222:225], v187 offset:2048
	ds_read_b128 v[226:229], v187 offset:3072
	ds_read_b128 v[230:233], v187 offset:4096
	ds_read_b128 v[234:237], v187 offset:5120
	ds_read_b128 v[238:241], v187 offset:6144
	ds_read_b128 v[242:245], v187 offset:7168
	global_load_lds_dwordx4 v[182:183], off
	s_add_i32 m0, s71, 0xe000
	v_lshl_add_u64 v[182:183], s[8:9], 0, v[170:171]
	global_load_lds_dwordx4 v[182:183], off
	s_waitcnt vmcnt(8) lgkmcnt(0)
	s_barrier
	s_setprio 1
	v_mfma_f32_16x16x32_bf16 v[142:145], v[10:13], v[214:217], v[142:145]
	v_mfma_f32_16x16x32_bf16 v[138:141], v[34:37], v[214:217], v[138:141]
	v_mfma_f32_16x16x32_bf16 v[126:129], v[10:13], v[222:225], v[126:129]
	v_mfma_f32_16x16x32_bf16 v[122:125], v[34:37], v[222:225], v[122:125]
	v_mfma_f32_16x16x32_bf16 v[110:113], v[10:13], v[230:233], v[110:113]
	v_mfma_f32_16x16x32_bf16 v[106:109], v[34:37], v[230:233], v[106:109]
	v_mfma_f32_16x16x32_bf16 v[94:97], v[10:13], v[238:241], v[94:97]
	v_mfma_f32_16x16x32_bf16 v[90:93], v[34:37], v[238:241], v[90:93]
	v_mfma_f32_16x16x32_bf16 v[142:145], v[14:17], v[218:221], v[142:145]
	v_mfma_f32_16x16x32_bf16 v[138:141], v[38:41], v[218:221], v[138:141]
	v_mfma_f32_16x16x32_bf16 v[126:129], v[14:17], v[226:229], v[126:129]
	v_mfma_f32_16x16x32_bf16 v[122:125], v[38:41], v[226:229], v[122:125]
	v_mfma_f32_16x16x32_bf16 v[110:113], v[14:17], v[234:237], v[110:113]
	v_mfma_f32_16x16x32_bf16 v[106:109], v[38:41], v[234:237], v[106:109]
	v_mfma_f32_16x16x32_bf16 v[94:97], v[14:17], v[242:245], v[94:97]
	v_mfma_f32_16x16x32_bf16 v[90:93], v[38:41], v[242:245], v[90:93]
	s_setprio 0
	s_setprio 1
	v_mfma_f32_16x16x32_bf16 v[134:137], v[146:149], v[214:217], v[134:137]
	v_mfma_f32_16x16x32_bf16 v[130:133], v[178:181], v[214:217], v[130:133]
	v_mfma_f32_16x16x32_bf16 v[118:121], v[146:149], v[222:225], v[118:121]
	v_mfma_f32_16x16x32_bf16 v[114:117], v[178:181], v[222:225], v[114:117]
	v_mfma_f32_16x16x32_bf16 v[102:105], v[146:149], v[230:233], v[102:105]
	v_mfma_f32_16x16x32_bf16 v[98:101], v[178:181], v[230:233], v[98:101]
	v_mfma_f32_16x16x32_bf16 v[86:89], v[146:149], v[238:241], v[86:89]
	v_mfma_f32_16x16x32_bf16 v[82:85], v[178:181], v[238:241], v[82:85]
	v_mfma_f32_16x16x32_bf16 v[134:137], v[174:177], v[218:221], v[134:137]
	v_mfma_f32_16x16x32_bf16 v[130:133], v[210:213], v[218:221], v[130:133]
	v_mfma_f32_16x16x32_bf16 v[118:121], v[174:177], v[226:229], v[118:121]
	v_mfma_f32_16x16x32_bf16 v[114:117], v[210:213], v[226:229], v[114:117]
	v_mfma_f32_16x16x32_bf16 v[102:105], v[174:177], v[234:237], v[102:105]
	v_mfma_f32_16x16x32_bf16 v[98:101], v[210:213], v[234:237], v[98:101]
	v_mfma_f32_16x16x32_bf16 v[86:89], v[174:177], v[242:245], v[86:89]
	v_mfma_f32_16x16x32_bf16 v[82:85], v[210:213], v[242:245], v[82:85]
	s_setprio 0
	s_barrier
	s_mov_b32 m0, s67
	v_lshl_add_u64 v[182:183], s[10:11], 0, v[152:153]
	s_add_u32 s54, s10, 0x40000
	ds_read_b128 v[214:217], v187 offset:16384
	ds_read_b128 v[218:221], v187 offset:17408
	ds_read_b128 v[222:225], v187 offset:18432
	ds_read_b128 v[226:229], v187 offset:19456
	ds_read_b128 v[230:233], v187 offset:20480
	ds_read_b128 v[234:237], v187 offset:21504
	ds_read_b128 v[238:241], v187 offset:22528
	ds_read_b128 v[242:245], v187 offset:23552
	global_load_lds_dwordx4 v[182:183], off
	v_lshl_add_u64 v[246:247], s[10:11], 0, v[156:157]
	s_mov_b32 m0, s68
	s_addc_u32 s55, s11, 0
	global_load_lds_dwordx4 v[246:247], off
	v_lshl_add_u64 v[248:249], s[54:55], 0, v[152:153]
	s_mov_b32 m0, s69
	v_lshl_add_u64 v[250:251], s[12:13], 0, v[154:155]
	global_load_lds_dwordx4 v[248:249], off
	s_mov_b32 m0, s70
	v_lshl_add_u64 v[248:249], s[54:55], 0, v[156:157]
	global_load_lds_dwordx4 v[248:249], off
	s_mov_b32 m0, s71
	v_lshl_add_u64 v[248:249], s[12:13], 0, v[150:151]
	global_load_lds_dwordx4 v[248:249], off
	s_mov_b32 m0, s72
	s_nop 0
	global_load_lds_dwordx4 v[250:251], off
	s_waitcnt vmcnt(8) lgkmcnt(0)
	s_barrier
; #define PG8_STAGE(bufoff, gbase, voff) do { _Pragma("unroll") for (int _i = 0; _i < 2; ++_i) \
;         __builtin_amdgcn_global_load_lds((const unsigned*)((const char*)(gbase) + (voff)[_i]), (PG8_LAS unsigned*)(lds + (bufoff) + ldsw + _i * 8192), 16, 0, 0); } while (0)
; #define PG8_LDA(dst, b, h) do { _Pragma("unroll") for (int m = 0; m < 4; ++m) _Pragma("unroll") for (int k = 0; k < 2; ++k) dst[m][k] = *(const PG8_LAS bf16x8*)(lds + PG8_SA(b, h) + aoff + m * 2048 + k * 1024); } while (0)
; #define PG8_LDB(dst, b, h) do { _Pragma("unroll") for (int n = 0; n < 2; ++n) _Pragma("unroll") for (int k = 0; k < 2; ++k) dst[n][k] = *(const PG8_LAS bf16x8*)(lds + PG8_SB(b, h) + boff + n * 2048 + k * 1024); } while (0)
; #define PG8_MMA(ai, bj, At, Bt) do { __builtin_amdgcn_s_setprio(1); _Pragma("unroll") for (int m = 0; m < 4; ++m) _Pragma("unroll") for (int n = 0; n < 2; ++n) _Pragma("unroll") for (int k = 0; k < 2; ++k) \
;         acc[ai][bj][m][n] = __builtin_amdgcn_mfma_f32_16x16x32_bf16(Bt[n][k], At[m][k], acc[ai][bj][m][n], 0, 0, 0); __builtin_amdgcn_s_setprio(0); } while (0)
; #define PG8_WAIT_V(n) asm volatile("s_waitcnt vmcnt(" #n ")" ::: "memory")
; #define PG8_WAIT_L(n) do { asm volatile("s_waitcnt lgkmcnt(" #n ")" ::: "memory"); __builtin_amdgcn_s_waitcnt(0xC07F); } while (0)
; #define PG8_BAR __builtin_amdgcn_s_barrier()
; #define PG8_SCHED __builtin_amdgcn_sched_barrier(0)
; template <class Epi, class Sched, bool SEG3 = false>
; __device__ __forceinline__ void gemm_phase(PG8_LAS unsigned char* lds, const Gemm g, const Sched& S, const Epi& E) {
;     ...
;             PG8_WAIT_V(8); PG8_WAIT_L(0); PG8_BAR; if (cur.half != 0) { PG8_MMA(1, 0, At, B0); PG8_MMA(1, 1, At, B1); } PG8_BAR; PG8_SCHED;
;             PG8_LDB(B0, 1, 0); PG8_LDB(B1, 1, 1); PG8_SCHED; PG8_LDA(At, 1, 0); PG8_STAGE(PG8_SA(0, 1), a2 + hsA, voffA);
;             PG8_WAIT_V(8); PG8_WAIT_L(0); PG8_BAR; if (cur.half != 1) { PG8_MMA(0, 0, At, B0); PG8_MMA(0, 1, At, B1); } PG8_BAR; PG8_SCHED;
	s_setprio 1
	v_mfma_f32_16x16x32_bf16 v[78:81], v[10:13], v[214:217], v[78:81]
	v_mfma_f32_16x16x32_bf16 v[74:77], v[34:37], v[214:217], v[74:77]
	v_mfma_f32_16x16x32_bf16 v[62:65], v[10:13], v[222:225], v[62:65]
	v_mfma_f32_16x16x32_bf16 v[58:61], v[34:37], v[222:225], v[58:61]
	v_mfma_f32_16x16x32_bf16 v[46:49], v[10:13], v[230:233], v[46:49]
	v_mfma_f32_16x16x32_bf16 v[42:45], v[34:37], v[230:233], v[42:45]
	v_mfma_f32_16x16x32_bf16 v[10:13], v[10:13], v[238:241], v[22:25]
	v_mfma_f32_16x16x32_bf16 v[78:81], v[14:17], v[218:221], v[78:81]
	v_mfma_f32_16x16x32_bf16 v[74:77], v[38:41], v[218:221], v[74:77]
	v_mfma_f32_16x16x32_bf16 v[62:65], v[14:17], v[226:229], v[62:65]
	v_mfma_f32_16x16x32_bf16 v[58:61], v[38:41], v[226:229], v[58:61]
	v_mfma_f32_16x16x32_bf16 v[46:49], v[14:17], v[234:237], v[46:49]
	v_mfma_f32_16x16x32_bf16 v[42:45], v[38:41], v[234:237], v[42:45]
	v_mfma_f32_16x16x32_bf16 v[10:13], v[14:17], v[242:245], v[10:13]
	v_mfma_f32_16x16x32_bf16 v[14:17], v[34:37], v[238:241], v[18:21]
	v_mfma_f32_16x16x32_bf16 v[14:17], v[38:41], v[242:245], v[14:17]
	s_setprio 0
	s_setprio 1
	v_mfma_f32_16x16x32_bf16 v[18:21], v[146:149], v[214:217], v[70:73]
	v_mfma_f32_16x16x32_bf16 v[34:37], v[174:177], v[218:221], v[18:21]
	v_mfma_f32_16x16x32_bf16 v[18:21], v[178:181], v[214:217], v[66:69]
	v_mfma_f32_16x16x32_bf16 v[38:41], v[210:213], v[218:221], v[18:21]
	v_mfma_f32_16x16x32_bf16 v[18:21], v[146:149], v[222:225], v[54:57]
	v_mfma_f32_16x16x32_bf16 v[54:57], v[174:177], v[226:229], v[18:21]
	v_mfma_f32_16x16x32_bf16 v[18:21], v[178:181], v[222:225], v[50:53]
	v_mfma_f32_16x16x32_bf16 v[50:53], v[210:213], v[226:229], v[18:21]
	v_mfma_f32_16x16x32_bf16 v[18:21], v[146:149], v[230:233], v[30:33]
	v_mfma_f32_16x16x32_bf16 v[30:33], v[174:177], v[234:237], v[18:21]
	v_mfma_f32_16x16x32_bf16 v[18:21], v[178:181], v[230:233], v[26:29]
	v_mfma_f32_16x16x32_bf16 v[6:9], v[146:149], v[238:241], v[6:9]
	v_mfma_f32_16x16x32_bf16 v[2:5], v[178:181], v[238:241], v[2:5]
	v_mfma_f32_16x16x32_bf16 v[26:29], v[210:213], v[234:237], v[18:21]
	v_mfma_f32_16x16x32_bf16 v[6:9], v[174:177], v[242:245], v[6:9]
	v_mfma_f32_16x16x32_bf16 v[2:5], v[210:213], v[242:245], v[2:5]
	s_setprio 0
	s_barrier
	s_nop 0
	ds_read_b128 v[18:21], v188
	ds_read_b128 v[22:25], v188 offset:1024
	ds_read_b128 v[66:69], v188 offset:2048
	ds_read_b128 v[70:73], v188 offset:3072
	ds_read_b128 v[146:149], v189
	ds_read_b128 v[174:177], v189 offset:1024
	ds_read_b128 v[178:181], v189 offset:2048
	ds_read_b128 v[210:213], v189 offset:3072
	s_add_u32 s12, s12, 0x40000
	s_addc_u32 s13, s13, 0
	s_mov_b32 m0, s73
	v_lshl_add_u64 v[252:253], s[12:13], 0, v[150:151]
	ds_read_b128 v[214:217], v187 offset:32768
	ds_read_b128 v[218:221], v187 offset:33792
	ds_read_b128 v[222:225], v187 offset:34816
	ds_read_b128 v[226:229], v187 offset:35840
	ds_read_b128 v[230:233], v187 offset:36864
	ds_read_b128 v[234:237], v187 offset:37888
	ds_read_b128 v[238:241], v187 offset:38912
	ds_read_b128 v[242:245], v187 offset:39936
	global_load_lds_dwordx4 v[252:253], off
	s_mov_b32 m0, s74
	v_lshl_add_u64 v[252:253], s[12:13], 0, v[154:155]
	global_load_lds_dwordx4 v[252:253], off
	s_waitcnt vmcnt(8) lgkmcnt(0)
	s_barrier
	s_setprio 1
	v_mfma_f32_16x16x32_bf16 v[142:145], v[18:21], v[214:217], v[142:145]
	v_mfma_f32_16x16x32_bf16 v[138:141], v[66:69], v[214:217], v[138:141]
	v_mfma_f32_16x16x32_bf16 v[126:129], v[18:21], v[222:225], v[126:129]
	v_mfma_f32_16x16x32_bf16 v[122:125], v[66:69], v[222:225], v[122:125]
	v_mfma_f32_16x16x32_bf16 v[110:113], v[18:21], v[230:233], v[110:113]
	v_mfma_f32_16x16x32_bf16 v[106:109], v[66:69], v[230:233], v[106:109]
	v_mfma_f32_16x16x32_bf16 v[94:97], v[18:21], v[238:241], v[94:97]
	v_mfma_f32_16x16x32_bf16 v[90:93], v[66:69], v[238:241], v[90:93]
	v_mfma_f32_16x16x32_bf16 v[142:145], v[22:25], v[218:221], v[142:145]
	v_mfma_f32_16x16x32_bf16 v[138:141], v[70:73], v[218:221], v[138:141]
	v_mfma_f32_16x16x32_bf16 v[126:129], v[22:25], v[226:229], v[126:129]
	v_mfma_f32_16x16x32_bf16 v[122:125], v[70:73], v[226:229], v[122:125]
	v_mfma_f32_16x16x32_bf16 v[110:113], v[22:25], v[234:237], v[110:113]
	v_mfma_f32_16x16x32_bf16 v[106:109], v[70:73], v[234:237], v[106:109]
	v_mfma_f32_16x16x32_bf16 v[94:97], v[22:25], v[242:245], v[94:97]
	v_mfma_f32_16x16x32_bf16 v[90:93], v[70:73], v[242:245], v[90:93]
	s_setprio 0
	s_setprio 1
	v_mfma_f32_16x16x32_bf16 v[134:137], v[146:149], v[214:217], v[134:137]
	v_mfma_f32_16x16x32_bf16 v[130:133], v[178:181], v[214:217], v[130:133]
	v_mfma_f32_16x16x32_bf16 v[118:121], v[146:149], v[222:225], v[118:121]
	v_mfma_f32_16x16x32_bf16 v[114:117], v[178:181], v[222:225], v[114:117]
	v_mfma_f32_16x16x32_bf16 v[102:105], v[146:149], v[230:233], v[102:105]
	v_mfma_f32_16x16x32_bf16 v[98:101], v[178:181], v[230:233], v[98:101]
	v_mfma_f32_16x16x32_bf16 v[86:89], v[146:149], v[238:241], v[86:89]
	v_mfma_f32_16x16x32_bf16 v[82:85], v[178:181], v[238:241], v[82:85]
	v_mfma_f32_16x16x32_bf16 v[134:137], v[174:177], v[218:221], v[134:137]
	v_mfma_f32_16x16x32_bf16 v[130:133], v[210:213], v[218:221], v[130:133]
	v_mfma_f32_16x16x32_bf16 v[118:121], v[174:177], v[226:229], v[118:121]
	v_mfma_f32_16x16x32_bf16 v[114:117], v[210:213], v[226:229], v[114:117]
	v_mfma_f32_16x16x32_bf16 v[102:105], v[174:177], v[234:237], v[102:105]
	v_mfma_f32_16x16x32_bf16 v[98:101], v[210:213], v[234:237], v[98:101]
	v_mfma_f32_16x16x32_bf16 v[86:89], v[174:177], v[242:245], v[86:89]
	v_mfma_f32_16x16x32_bf16 v[82:85], v[210:213], v[242:245], v[82:85]
	s_setprio 0
	s_barrier
; #define PG8_STAGE(bufoff, gbase, voff) do { _Pragma("unroll") for (int _i = 0; _i < 2; ++_i) \
;         __builtin_amdgcn_global_load_lds((const unsigned*)((const char*)(gbase) + (voff)[_i]), (PG8_LAS unsigned*)(lds + (bufoff) + ldsw + _i * 8192), 16, 0, 0); } while (0)
; #define PG8_LDA(dst, b, h) do { _Pragma("unroll") for (int m = 0; m < 4; ++m) _Pragma("unroll") for (int k = 0; k < 2; ++k) dst[m][k] = *(const PG8_LAS bf16x8*)(lds + PG8_SA(b, h) + aoff + m * 2048 + k * 1024); } while (0)
; #define PG8_MMA(ai, bj, At, Bt) do { __builtin_amdgcn_s_setprio(1); _Pragma("unroll") for (int m = 0; m < 4; ++m) _Pragma("unroll") for (int n = 0; n < 2; ++n) _Pragma("unroll") for (int k = 0; k < 2; ++k) \
;         acc[ai][bj][m][n] = __builtin_amdgcn_mfma_f32_16x16x32_bf16(Bt[n][k], At[m][k], acc[ai][bj][m][n], 0, 0, 0); __builtin_amdgcn_s_setprio(0); } while (0)
; #define PG8_WAIT_V(n) asm volatile("s_waitcnt vmcnt(" #n ")" ::: "memory")
; #define PG8_WAIT_L(n) do { asm volatile("s_waitcnt lgkmcnt(" #n ")" ::: "memory"); __builtin_amdgcn_s_waitcnt(0xC07F); } while (0)
; #define PG8_BAR __builtin_amdgcn_s_barrier()
; #define PG8_SCHED __builtin_amdgcn_sched_barrier(0)
; template <class Epi, class Sched, bool SEG3 = false>
; __device__ __forceinline__ void gemm_phase(PG8_LAS unsigned char* lds, const Gemm g, const Sched& S, const Epi& E) {
;     ...
;             PG8_LDA(At, 1, 1); PG8_STAGE(PG8_SB(1, 0), b3, voffB); PG8_STAGE(PG8_SB(1, 1), b3 + hsB, voffB); PG8_STAGE(PG8_SA(1, 0), a3, voffA);
;             PG8_WAIT_V(8); PG8_WAIT_L(0); PG8_BAR; if (cur.half != 0) { PG8_MMA(1, 0, At, B0); PG8_MMA(1, 1, At, B1); } PG8_BAR; PG8_SCHED;
;         }
	s_mov_b32 m0, s77
	v_lshl_add_u64 v[182:183], v[182:183], 0, s[30:31]
	s_add_u32 s10, s10, 0x40080
	ds_read_b128 v[214:217], v187 offset:49152
	ds_read_b128 v[218:221], v187 offset:50176
	ds_read_b128 v[222:225], v187 offset:51200
	ds_read_b128 v[226:229], v187 offset:52224
	ds_read_b128 v[230:233], v187 offset:53248
	ds_read_b128 v[234:237], v187 offset:54272
	ds_read_b128 v[238:241], v187 offset:55296
	ds_read_b128 v[242:245], v187 offset:56320
	global_load_lds_dwordx4 v[182:183], off
	v_lshl_add_u64 v[182:183], v[246:247], 0, s[30:31]
	s_mov_b32 m0, s78
	s_addc_u32 s11, s11, 0
	global_load_lds_dwordx4 v[182:183], off
	s_mov_b32 m0, s82
	v_lshl_add_u64 v[182:183], s[10:11], 0, v[152:153]
	global_load_lds_dwordx4 v[182:183], off
	s_mov_b32 m0, s83
	v_lshl_add_u64 v[182:183], s[10:11], 0, v[156:157]
	global_load_lds_dwordx4 v[182:183], off
	s_mov_b32 m0, s80
	v_lshl_add_u64 v[182:183], v[248:249], 0, s[30:31]
	global_load_lds_dwordx4 v[182:183], off
	s_mov_b32 m0, s81
	v_lshl_add_u64 v[182:183], v[250:251], 0, s[30:31]
	global_load_lds_dwordx4 v[182:183], off
	s_waitcnt vmcnt(8) lgkmcnt(0)
	s_barrier
	s_setprio 1
	v_mfma_f32_16x16x32_bf16 v[78:81], v[18:21], v[214:217], v[78:81]
	v_mfma_f32_16x16x32_bf16 v[62:65], v[18:21], v[222:225], v[62:65]
	v_mfma_f32_16x16x32_bf16 v[46:49], v[18:21], v[230:233], v[46:49]
	v_mfma_f32_16x16x32_bf16 v[10:13], v[18:21], v[238:241], v[10:13]
	v_mfma_f32_16x16x32_bf16 v[78:81], v[22:25], v[218:221], v[78:81]
	v_mfma_f32_16x16x32_bf16 v[74:77], v[66:69], v[214:217], v[74:77]
	v_mfma_f32_16x16x32_bf16 v[62:65], v[22:25], v[226:229], v[62:65]
	v_mfma_f32_16x16x32_bf16 v[58:61], v[66:69], v[222:225], v[58:61]
	v_mfma_f32_16x16x32_bf16 v[46:49], v[22:25], v[234:237], v[46:49]
	v_mfma_f32_16x16x32_bf16 v[42:45], v[66:69], v[230:233], v[42:45]
	v_mfma_f32_16x16x32_bf16 v[22:25], v[22:25], v[242:245], v[10:13]
	v_mfma_f32_16x16x32_bf16 v[10:13], v[66:69], v[238:241], v[14:17]
	v_mfma_f32_16x16x32_bf16 v[74:77], v[70:73], v[218:221], v[74:77]
	v_mfma_f32_16x16x32_bf16 v[58:61], v[70:73], v[226:229], v[58:61]
	v_mfma_f32_16x16x32_bf16 v[42:45], v[70:73], v[234:237], v[42:45]
	v_mfma_f32_16x16x32_bf16 v[18:21], v[70:73], v[242:245], v[10:13]
	s_setprio 0
	s_setprio 1
	v_mfma_f32_16x16x32_bf16 v[10:13], v[146:149], v[214:217], v[34:37]
	v_mfma_f32_16x16x32_bf16 v[70:73], v[174:177], v[218:221], v[10:13]
	v_mfma_f32_16x16x32_bf16 v[10:13], v[178:181], v[214:217], v[38:41]
	v_mfma_f32_16x16x32_bf16 v[66:69], v[210:213], v[218:221], v[10:13]
	v_mfma_f32_16x16x32_bf16 v[10:13], v[146:149], v[222:225], v[54:57]
	v_mfma_f32_16x16x32_bf16 v[54:57], v[174:177], v[226:229], v[10:13]
	v_mfma_f32_16x16x32_bf16 v[10:13], v[178:181], v[222:225], v[50:53]
	v_mfma_f32_16x16x32_bf16 v[50:53], v[210:213], v[226:229], v[10:13]
	v_mfma_f32_16x16x32_bf16 v[10:13], v[146:149], v[230:233], v[30:33]
	v_mfma_f32_16x16x32_bf16 v[30:33], v[174:177], v[234:237], v[10:13]
	v_mfma_f32_16x16x32_bf16 v[10:13], v[178:181], v[230:233], v[26:29]
	v_mfma_f32_16x16x32_bf16 v[6:9], v[146:149], v[238:241], v[6:9]
	v_mfma_f32_16x16x32_bf16 v[2:5], v[178:181], v[238:241], v[2:5]
	v_mfma_f32_16x16x32_bf16 v[26:29], v[210:213], v[234:237], v[10:13]
	v_mfma_f32_16x16x32_bf16 v[6:9], v[174:177], v[242:245], v[6:9]
	v_mfma_f32_16x16x32_bf16 v[2:5], v[210:213], v[242:245], v[2:5]
	s_setprio 0
	s_barrier
	s_add_u32 s8, s8, 0x100
	s_addc_u32 s9, s9, 0
	s_add_u32 s17, s17, 0x100
	s_addc_u32 s19, s19, 0
	s_cmp_lt_i32 s20, s75
	s_mov_b32 s10, s20
	s_cbranch_scc1 .LBB0_2680
	s_andn2_b64 vcc, exec, s[36:37]
	s_cbranch_vccnz .LBB0_2683

; #define PG8_STAGE(bufoff, gbase, voff) do { _Pragma("unroll") for (int _i = 0; _i < 2; ++_i) \
;         __builtin_amdgcn_global_load_lds((const unsigned*)((const char*)(gbase) + (voff)[_i]), (PG8_LAS unsigned*)(lds + (bufoff) + ldsw + _i * 8192), 16, 0, 0); } while (0)
; #define PG8_LDA(dst, b, h) do { _Pragma("unroll") for (int m = 0; m < 4; ++m) _Pragma("unroll") for (int k = 0; k < 2; ++k) dst[m][k] = *(const PG8_LAS bf16x8*)(lds + PG8_SA(b, h) + aoff + m * 2048 + k * 1024); } while (0)
; #define PG8_LDB(dst, b, h) do { _Pragma("unroll") for (int n = 0; n < 2; ++n) _Pragma("unroll") for (int k = 0; k < 2; ++k) dst[n][k] = *(const PG8_LAS bf16x8*)(lds + PG8_SB(b, h) + boff + n * 2048 + k * 1024); } while (0)
; #define PG8_MMA(ai, bj, At, Bt) do { __builtin_amdgcn_s_setprio(1); _Pragma("unroll") for (int m = 0; m < 4; ++m) _Pragma("unroll") for (int n = 0; n < 2; ++n) _Pragma("unroll") for (int k = 0; k < 2; ++k) \
;         acc[ai][bj][m][n] = __builtin_amdgcn_mfma_f32_16x16x32_bf16(Bt[n][k], At[m][k], acc[ai][bj][m][n], 0, 0, 0); __builtin_amdgcn_s_setprio(0); } while (0)
; #define PG8_WAIT_V(n) asm volatile("s_waitcnt vmcnt(" #n ")" ::: "memory")
; #define PG8_WAIT_L(n) do { asm volatile("s_waitcnt lgkmcnt(" #n ")" ::: "memory"); __builtin_amdgcn_s_waitcnt(0xC07F); } while (0)
; #define PG8_BAR __builtin_amdgcn_s_barrier()
; template <class Epi, class Sched, bool SEG3 = false>
; __device__ __forceinline__ void gemm_phase(PG8_LAS unsigned char* lds, const Gemm g, const Sched& S, const Epi& E) {
;     ...
;             const bool last = (t == ntc - 2);
;             const char* a1 = cA + (size_t)(t + 1) * kstep;
;             const char* a2 = last ? nA : cA + (size_t)(t + 2) * kstep; const char* b2 = last ? nB : cB + (size_t)(t + 2) * kstep;
;             const char* a3 = a2 + kstep; const char* b3 = b2 + kstep;
;             PG8_LDB(B0, 0, 0); PG8_LDB(B1, 0, 1); PG8_SCHED; PG8_LDA(At, 0, 0); PG8_STAGE(PG8_SA(1, 1), a1 + hsA, voffA);
;             PG8_WAIT_V(8); PG8_WAIT_L(0); PG8_BAR; if (cur.half != 1) { PG8_MMA(0, 0, At, B0); PG8_MMA(0, 1, At, B1); } PG8_BAR; PG8_SCHED;
;             PG8_LDA(At, 0, 1); PG8_STAGE(PG8_SB(0, 0), b2, voffB); PG8_STAGE(PG8_SB(0, 1), b2 + hsB, voffB); PG8_STAGE(PG8_SA(0, 0), a2, voffA);
;             PG8_WAIT_V(8); PG8_WAIT_L(0); PG8_BAR; if (cur.half != 0) { PG8_MMA(1, 0, At, B0); PG8_MMA(1, 1, At, B1); } PG8_BAR; PG8_SCHED;
.LBB0_4031:
	ds_read_b128 v[124:127], v231
	ds_read_b128 v[132:135], v231 offset:1024
	ds_read_b128 v[140:143], v231 offset:2048
	ds_read_b128 v[144:147], v231 offset:3072
	ds_read_b128 v[148:151], v232
	ds_read_b128 v[152:155], v232 offset:1024
	ds_read_b128 v[156:159], v232 offset:2048
	ds_read_b128 v[160:163], v232 offset:3072
	s_add_i32 s65, s28, 2
	s_add_u32 s29, s6, 0xfffc0080
	s_addc_u32 s30, s7, -1
	s_cmp_eq_u32 s17, s28
	s_cselect_b32 s28, s22, s19
	s_cselect_b32 s31, s21, s30
	s_cselect_b32 s30, s20, s29
	s_cselect_b32 s29, s23, s27
	v_lshl_add_u64 v[98:99], s[6:7], 0, v[206:207]
	s_add_i32 m0, s50, 0xc000
	ds_read_b128 v[164:167], v233
	ds_read_b128 v[168:171], v233 offset:1024
	ds_read_b128 v[172:175], v233 offset:2048
	ds_read_b128 v[176:179], v233 offset:3072
	ds_read_b128 v[180:183], v233 offset:4096
	ds_read_b128 v[184:187], v233 offset:5120
	ds_read_b128 v[188:191], v233 offset:6144
	ds_read_b128 v[192:195], v233 offset:7168
	global_load_lds_dwordx4 v[98:99], off
	s_add_i32 m0, s50, 0xe000
	v_lshl_add_u64 v[98:99], s[6:7], 0, v[208:209]
	global_load_lds_dwordx4 v[98:99], off
	s_waitcnt vmcnt(8) lgkmcnt(0)
	s_barrier
	s_setprio 1
	v_mfma_f32_16x16x32_bf16 v[136:139], v[124:127], v[164:167], v[136:139]
	v_mfma_f32_16x16x32_bf16 v[128:131], v[140:143], v[164:167], v[128:131]
	v_mfma_f32_16x16x32_bf16 v[112:115], v[124:127], v[172:175], v[112:115]
	v_mfma_f32_16x16x32_bf16 v[108:111], v[140:143], v[172:175], v[108:111]
	v_mfma_f32_16x16x32_bf16 v[94:97], v[124:127], v[180:183], v[94:97]
	v_mfma_f32_16x16x32_bf16 v[90:93], v[140:143], v[180:183], v[90:93]
	v_mfma_f32_16x16x32_bf16 v[78:81], v[124:127], v[188:191], v[78:81]
	v_mfma_f32_16x16x32_bf16 v[74:77], v[140:143], v[188:191], v[74:77]
	v_mfma_f32_16x16x32_bf16 v[136:139], v[132:135], v[168:171], v[136:139]
	v_mfma_f32_16x16x32_bf16 v[128:131], v[144:147], v[168:171], v[128:131]
	v_mfma_f32_16x16x32_bf16 v[112:115], v[132:135], v[176:179], v[112:115]
	v_mfma_f32_16x16x32_bf16 v[108:111], v[144:147], v[176:179], v[108:111]
	v_mfma_f32_16x16x32_bf16 v[94:97], v[132:135], v[184:187], v[94:97]
	v_mfma_f32_16x16x32_bf16 v[90:93], v[144:147], v[184:187], v[90:93]
	v_mfma_f32_16x16x32_bf16 v[78:81], v[132:135], v[192:195], v[78:81]
	v_mfma_f32_16x16x32_bf16 v[74:77], v[144:147], v[192:195], v[74:77]
	s_setprio 0
	s_setprio 1
	v_mfma_f32_16x16x32_bf16 v[120:123], v[148:151], v[164:167], v[120:123]
	v_mfma_f32_16x16x32_bf16 v[116:119], v[156:159], v[164:167], v[116:119]
	v_mfma_f32_16x16x32_bf16 v[104:107], v[148:151], v[172:175], v[104:107]
	v_mfma_f32_16x16x32_bf16 v[98:101], v[156:159], v[172:175], v[100:103]
	v_mfma_f32_16x16x32_bf16 v[86:89], v[148:151], v[180:183], v[86:89]
	v_mfma_f32_16x16x32_bf16 v[82:85], v[156:159], v[180:183], v[82:85]
	v_mfma_f32_16x16x32_bf16 v[70:73], v[148:151], v[188:191], v[70:73]
	v_mfma_f32_16x16x32_bf16 v[66:69], v[156:159], v[188:191], v[66:69]
	v_mfma_f32_16x16x32_bf16 v[120:123], v[152:155], v[168:171], v[120:123]
	v_mfma_f32_16x16x32_bf16 v[116:119], v[160:163], v[168:171], v[116:119]
	v_mfma_f32_16x16x32_bf16 v[104:107], v[152:155], v[176:179], v[104:107]
	v_mfma_f32_16x16x32_bf16 v[98:101], v[160:163], v[176:179], v[98:101]
	v_mfma_f32_16x16x32_bf16 v[86:89], v[152:155], v[184:187], v[86:89]
	v_mfma_f32_16x16x32_bf16 v[82:85], v[160:163], v[184:187], v[82:85]
	v_mfma_f32_16x16x32_bf16 v[70:73], v[152:155], v[192:195], v[70:73]
	v_mfma_f32_16x16x32_bf16 v[66:69], v[160:163], v[192:195], v[66:69]
	s_setprio 0
	s_barrier
	s_mov_b32 m0, s46
	v_lshl_add_u64 v[214:215], s[28:29], 0, v[198:199]
	s_add_u32 s66, s28, 0x40000
	ds_read_b128 v[164:167], v233 offset:16384
	ds_read_b128 v[168:171], v233 offset:17408
	ds_read_b128 v[172:175], v233 offset:18432
	ds_read_b128 v[176:179], v233 offset:19456
	ds_read_b128 v[180:183], v233 offset:20480
	ds_read_b128 v[184:187], v233 offset:21504
	ds_read_b128 v[188:191], v233 offset:22528
	ds_read_b128 v[192:195], v233 offset:23552
	global_load_lds_dwordx4 v[214:215], off
	v_lshl_add_u64 v[216:217], s[28:29], 0, v[202:203]
	s_mov_b32 m0, s47
	s_addc_u32 s67, s29, 0
	global_load_lds_dwordx4 v[216:217], off
	v_lshl_add_u64 v[102:103], s[66:67], 0, v[198:199]
	s_mov_b32 m0, s48
	v_lshl_add_u64 v[218:219], s[30:31], 0, v[196:197]
	global_load_lds_dwordx4 v[102:103], off
	v_lshl_add_u64 v[102:103], s[66:67], 0, v[202:203]
	s_mov_b32 m0, s49
	v_lshl_add_u64 v[220:221], s[30:31], 0, v[200:201]
	global_load_lds_dwordx4 v[102:103], off
	s_mov_b32 m0, s50
	s_nop 0
	global_load_lds_dwordx4 v[218:219], off
	s_mov_b32 m0, s51
	s_nop 0
	global_load_lds_dwordx4 v[220:221], off
	s_waitcnt vmcnt(8) lgkmcnt(0)
	s_barrier
; #define PG8_STAGE(bufoff, gbase, voff) do { _Pragma("unroll") for (int _i = 0; _i < 2; ++_i) \
;         __builtin_amdgcn_global_load_lds((const unsigned*)((const char*)(gbase) + (voff)[_i]), (PG8_LAS unsigned*)(lds + (bufoff) + ldsw + _i * 8192), 16, 0, 0); } while (0)
; #define PG8_LDA(dst, b, h) do { _Pragma("unroll") for (int m = 0; m < 4; ++m) _Pragma("unroll") for (int k = 0; k < 2; ++k) dst[m][k] = *(const PG8_LAS bf16x8*)(lds + PG8_SA(b, h) + aoff + m * 2048 + k * 1024); } while (0)
; #define PG8_LDB(dst, b, h) do { _Pragma("unroll") for (int n = 0; n < 2; ++n) _Pragma("unroll") for (int k = 0; k < 2; ++k) dst[n][k] = *(const PG8_LAS bf16x8*)(lds + PG8_SB(b, h) + boff + n * 2048 + k * 1024); } while (0)
; #define PG8_MMA(ai, bj, At, Bt) do { __builtin_amdgcn_s_setprio(1); _Pragma("unroll") for (int m = 0; m < 4; ++m) _Pragma("unroll") for (int n = 0; n < 2; ++n) _Pragma("unroll") for (int k = 0; k < 2; ++k) \
;         acc[ai][bj][m][n] = __builtin_amdgcn_mfma_f32_16x16x32_bf16(Bt[n][k], At[m][k], acc[ai][bj][m][n], 0, 0, 0); __builtin_amdgcn_s_setprio(0); } while (0)
; #define PG8_WAIT_V(n) asm volatile("s_waitcnt vmcnt(" #n ")" ::: "memory")
; #define PG8_WAIT_L(n) do { asm volatile("s_waitcnt lgkmcnt(" #n ")" ::: "memory"); __builtin_amdgcn_s_waitcnt(0xC07F); } while (0)
; #define PG8_BAR __builtin_amdgcn_s_barrier()
; #define PG8_SCHED __builtin_amdgcn_sched_barrier(0)
; template <class Epi, class Sched, bool SEG3 = false>
; __device__ __forceinline__ void gemm_phase(PG8_LAS unsigned char* lds, const Gemm g, const Sched& S, const Epi& E) {
;     ...
;             PG8_WAIT_V(8); PG8_WAIT_L(0); PG8_BAR; if (cur.half != 0) { PG8_MMA(1, 0, At, B0); PG8_MMA(1, 1, At, B1); } PG8_BAR; PG8_SCHED;
;             PG8_LDB(B0, 1, 0); PG8_LDB(B1, 1, 1); PG8_SCHED; PG8_LDA(At, 1, 0); PG8_STAGE(PG8_SA(0, 1), a2 + hsA, voffA);
;             PG8_WAIT_V(8); PG8_WAIT_L(0); PG8_BAR; if (cur.half != 1) { PG8_MMA(0, 0, At, B0); PG8_MMA(0, 1, At, B1); } PG8_BAR; PG8_SCHED;
	s_setprio 1
	v_mfma_f32_16x16x32_bf16 v[62:65], v[124:127], v[164:167], v[62:65]
	v_mfma_f32_16x16x32_bf16 v[58:61], v[140:143], v[164:167], v[58:61]
	v_mfma_f32_16x16x32_bf16 v[46:49], v[124:127], v[172:175], v[46:49]
	v_mfma_f32_16x16x32_bf16 v[42:45], v[140:143], v[172:175], v[42:45]
	v_mfma_f32_16x16x32_bf16 v[30:33], v[124:127], v[180:183], v[30:33]
	v_mfma_f32_16x16x32_bf16 v[26:29], v[140:143], v[180:183], v[26:29]
	v_mfma_f32_16x16x32_bf16 v[14:17], v[124:127], v[188:191], v[14:17]
	v_mfma_f32_16x16x32_bf16 v[10:13], v[140:143], v[188:191], v[10:13]
	v_mfma_f32_16x16x32_bf16 v[62:65], v[132:135], v[168:171], v[62:65]
	v_mfma_f32_16x16x32_bf16 v[58:61], v[144:147], v[168:171], v[58:61]
	v_mfma_f32_16x16x32_bf16 v[46:49], v[132:135], v[176:179], v[46:49]
	v_mfma_f32_16x16x32_bf16 v[42:45], v[144:147], v[176:179], v[42:45]
	v_mfma_f32_16x16x32_bf16 v[30:33], v[132:135], v[184:187], v[30:33]
	v_mfma_f32_16x16x32_bf16 v[26:29], v[144:147], v[184:187], v[26:29]
	v_mfma_f32_16x16x32_bf16 v[14:17], v[132:135], v[192:195], v[14:17]
	v_mfma_f32_16x16x32_bf16 v[10:13], v[144:147], v[192:195], v[10:13]
	s_setprio 0
	s_setprio 1
	v_mfma_f32_16x16x32_bf16 v[54:57], v[148:151], v[164:167], v[54:57]
	v_mfma_f32_16x16x32_bf16 v[50:53], v[156:159], v[164:167], v[50:53]
	v_mfma_f32_16x16x32_bf16 v[38:41], v[148:151], v[172:175], v[38:41]
	v_mfma_f32_16x16x32_bf16 v[34:37], v[156:159], v[172:175], v[34:37]
	v_mfma_f32_16x16x32_bf16 v[22:25], v[148:151], v[180:183], v[22:25]
	v_mfma_f32_16x16x32_bf16 v[18:21], v[156:159], v[180:183], v[18:21]
	v_mfma_f32_16x16x32_bf16 v[6:9], v[148:151], v[188:191], v[6:9]
	v_mfma_f32_16x16x32_bf16 v[2:5], v[156:159], v[188:191], v[2:5]
	v_mfma_f32_16x16x32_bf16 v[54:57], v[152:155], v[168:171], v[54:57]
	v_mfma_f32_16x16x32_bf16 v[50:53], v[160:163], v[168:171], v[50:53]
	v_mfma_f32_16x16x32_bf16 v[38:41], v[152:155], v[176:179], v[38:41]
	v_mfma_f32_16x16x32_bf16 v[34:37], v[160:163], v[176:179], v[34:37]
	v_mfma_f32_16x16x32_bf16 v[22:25], v[152:155], v[184:187], v[22:25]
	v_mfma_f32_16x16x32_bf16 v[18:21], v[160:163], v[184:187], v[18:21]
	v_mfma_f32_16x16x32_bf16 v[6:9], v[152:155], v[192:195], v[6:9]
	v_mfma_f32_16x16x32_bf16 v[2:5], v[160:163], v[192:195], v[2:5]
	s_setprio 0
	s_barrier
	ds_read_b128 v[124:127], v234
	ds_read_b128 v[132:135], v234 offset:1024
	ds_read_b128 v[140:143], v234 offset:2048
	ds_read_b128 v[144:147], v234 offset:3072
	ds_read_b128 v[148:151], v235
	ds_read_b128 v[152:155], v235 offset:1024
	ds_read_b128 v[156:159], v235 offset:2048
	ds_read_b128 v[160:163], v235 offset:3072
	s_add_u32 s30, s30, 0x40000
	s_addc_u32 s31, s31, 0
	s_mov_b32 m0, s52
	v_lshl_add_u64 v[102:103], s[30:31], 0, v[196:197]
	ds_read_b128 v[164:167], v233 offset:32768
	ds_read_b128 v[168:171], v233 offset:33792
	ds_read_b128 v[172:175], v233 offset:34816
	ds_read_b128 v[176:179], v233 offset:35840
	ds_read_b128 v[180:183], v233 offset:36864
	ds_read_b128 v[184:187], v233 offset:37888
	ds_read_b128 v[188:191], v233 offset:38912
	ds_read_b128 v[192:195], v233 offset:39936
	global_load_lds_dwordx4 v[102:103], off
	s_mov_b32 m0, s53
	v_lshl_add_u64 v[102:103], s[30:31], 0, v[200:201]
	global_load_lds_dwordx4 v[102:103], off
	s_waitcnt vmcnt(8) lgkmcnt(0)
	s_barrier
	s_setprio 1
	v_mfma_f32_16x16x32_bf16 v[136:139], v[124:127], v[164:167], v[136:139]
	v_mfma_f32_16x16x32_bf16 v[128:131], v[140:143], v[164:167], v[128:131]
	v_mfma_f32_16x16x32_bf16 v[112:115], v[124:127], v[172:175], v[112:115]
	v_mfma_f32_16x16x32_bf16 v[108:111], v[140:143], v[172:175], v[108:111]
	v_mfma_f32_16x16x32_bf16 v[94:97], v[124:127], v[180:183], v[94:97]
	v_mfma_f32_16x16x32_bf16 v[90:93], v[140:143], v[180:183], v[90:93]
	v_mfma_f32_16x16x32_bf16 v[78:81], v[124:127], v[188:191], v[78:81]
	v_mfma_f32_16x16x32_bf16 v[74:77], v[140:143], v[188:191], v[74:77]
	v_mfma_f32_16x16x32_bf16 v[136:139], v[132:135], v[168:171], v[136:139]
	v_mfma_f32_16x16x32_bf16 v[128:131], v[144:147], v[168:171], v[128:131]
	v_mfma_f32_16x16x32_bf16 v[112:115], v[132:135], v[176:179], v[112:115]
	v_mfma_f32_16x16x32_bf16 v[108:111], v[144:147], v[176:179], v[108:111]
	v_mfma_f32_16x16x32_bf16 v[94:97], v[132:135], v[184:187], v[94:97]
	v_mfma_f32_16x16x32_bf16 v[90:93], v[144:147], v[184:187], v[90:93]
	v_mfma_f32_16x16x32_bf16 v[78:81], v[132:135], v[192:195], v[78:81]
	v_mfma_f32_16x16x32_bf16 v[74:77], v[144:147], v[192:195], v[74:77]
	s_setprio 0
	s_setprio 1
	v_mfma_f32_16x16x32_bf16 v[120:123], v[148:151], v[164:167], v[120:123]
	v_mfma_f32_16x16x32_bf16 v[116:119], v[156:159], v[164:167], v[116:119]
	v_mfma_f32_16x16x32_bf16 v[102:105], v[148:151], v[172:175], v[104:107]
	v_mfma_f32_16x16x32_bf16 v[98:101], v[156:159], v[172:175], v[98:101]
	v_mfma_f32_16x16x32_bf16 v[86:89], v[148:151], v[180:183], v[86:89]
	v_mfma_f32_16x16x32_bf16 v[82:85], v[156:159], v[180:183], v[82:85]
	v_mfma_f32_16x16x32_bf16 v[70:73], v[148:151], v[188:191], v[70:73]
	v_mfma_f32_16x16x32_bf16 v[66:69], v[156:159], v[188:191], v[66:69]
	v_mfma_f32_16x16x32_bf16 v[120:123], v[152:155], v[168:171], v[120:123]
	v_mfma_f32_16x16x32_bf16 v[116:119], v[160:163], v[168:171], v[116:119]
	v_mfma_f32_16x16x32_bf16 v[104:107], v[152:155], v[176:179], v[102:105]
	v_mfma_f32_16x16x32_bf16 v[100:103], v[160:163], v[176:179], v[98:101]
	v_mfma_f32_16x16x32_bf16 v[86:89], v[152:155], v[184:187], v[86:89]
	v_mfma_f32_16x16x32_bf16 v[82:85], v[160:163], v[184:187], v[82:85]
	v_mfma_f32_16x16x32_bf16 v[70:73], v[152:155], v[192:195], v[70:73]
	v_mfma_f32_16x16x32_bf16 v[66:69], v[160:163], v[192:195], v[66:69]
	s_setprio 0
	s_barrier
; #define PG8_STAGE(bufoff, gbase, voff) do { _Pragma("unroll") for (int _i = 0; _i < 2; ++_i) \
;         __builtin_amdgcn_global_load_lds((const unsigned*)((const char*)(gbase) + (voff)[_i]), (PG8_LAS unsigned*)(lds + (bufoff) + ldsw + _i * 8192), 16, 0, 0); } while (0)
; #define PG8_LDA(dst, b, h) do { _Pragma("unroll") for (int m = 0; m < 4; ++m) _Pragma("unroll") for (int k = 0; k < 2; ++k) dst[m][k] = *(const PG8_LAS bf16x8*)(lds + PG8_SA(b, h) + aoff + m * 2048 + k * 1024); } while (0)
; #define PG8_MMA(ai, bj, At, Bt) do { __builtin_amdgcn_s_setprio(1); _Pragma("unroll") for (int m = 0; m < 4; ++m) _Pragma("unroll") for (int n = 0; n < 2; ++n) _Pragma("unroll") for (int k = 0; k < 2; ++k) \
;         acc[ai][bj][m][n] = __builtin_amdgcn_mfma_f32_16x16x32_bf16(Bt[n][k], At[m][k], acc[ai][bj][m][n], 0, 0, 0); __builtin_amdgcn_s_setprio(0); } while (0)
; #define PG8_WAIT_V(n) asm volatile("s_waitcnt vmcnt(" #n ")" ::: "memory")
; #define PG8_WAIT_L(n) do { asm volatile("s_waitcnt lgkmcnt(" #n ")" ::: "memory"); __builtin_amdgcn_s_waitcnt(0xC07F); } while (0)
; #define PG8_BAR __builtin_amdgcn_s_barrier()
; #define PG8_SCHED __builtin_amdgcn_sched_barrier(0)
; template <class Epi, class Sched, bool SEG3 = false>
; __device__ __forceinline__ void gemm_phase(PG8_LAS unsigned char* lds, const Gemm g, const Sched& S, const Epi& E) {
;     ...
;             PG8_LDA(At, 1, 1); PG8_STAGE(PG8_SB(1, 0), b3, voffB); PG8_STAGE(PG8_SB(1, 1), b3 + hsB, voffB); PG8_STAGE(PG8_SA(1, 0), a3, voffA);
;             PG8_WAIT_V(8); PG8_WAIT_L(0); PG8_BAR; if (cur.half != 0) { PG8_MMA(1, 0, At, B0); PG8_MMA(1, 1, At, B1); } PG8_BAR; PG8_SCHED;
;         }
	s_mov_b32 m0, s55
	v_lshl_add_u64 v[98:99], v[214:215], 0, s[12:13]
	s_add_u32 s28, s28, 0x40080
	ds_read_b128 v[164:167], v233 offset:49152
	ds_read_b128 v[168:171], v233 offset:50176
	ds_read_b128 v[172:175], v233 offset:51200
	ds_read_b128 v[176:179], v233 offset:52224
	ds_read_b128 v[180:183], v233 offset:53248
	ds_read_b128 v[184:187], v233 offset:54272
	ds_read_b128 v[188:191], v233 offset:55296
	ds_read_b128 v[192:195], v233 offset:56320
	global_load_lds_dwordx4 v[98:99], off
	v_lshl_add_u64 v[98:99], v[216:217], 0, s[12:13]
	s_mov_b32 m0, s56
	s_addc_u32 s29, s29, 0
	global_load_lds_dwordx4 v[98:99], off
	s_mov_b32 m0, s59
	v_lshl_add_u64 v[98:99], s[28:29], 0, v[198:199]
	global_load_lds_dwordx4 v[98:99], off
	s_mov_b32 m0, s60
	v_lshl_add_u64 v[98:99], s[28:29], 0, v[202:203]
	global_load_lds_dwordx4 v[98:99], off
	s_mov_b32 m0, s57
	v_lshl_add_u64 v[98:99], v[218:219], 0, s[12:13]
	global_load_lds_dwordx4 v[98:99], off
	s_mov_b32 m0, s58
	v_lshl_add_u64 v[98:99], v[220:221], 0, s[12:13]
	global_load_lds_dwordx4 v[98:99], off
	s_waitcnt vmcnt(8) lgkmcnt(0)
	s_barrier
	s_setprio 1
	v_mfma_f32_16x16x32_bf16 v[62:65], v[124:127], v[164:167], v[62:65]
	v_mfma_f32_16x16x32_bf16 v[58:61], v[140:143], v[164:167], v[58:61]
	v_mfma_f32_16x16x32_bf16 v[46:49], v[124:127], v[172:175], v[46:49]
	v_mfma_f32_16x16x32_bf16 v[42:45], v[140:143], v[172:175], v[42:45]
	v_mfma_f32_16x16x32_bf16 v[30:33], v[124:127], v[180:183], v[30:33]
	v_mfma_f32_16x16x32_bf16 v[26:29], v[140:143], v[180:183], v[26:29]
	v_mfma_f32_16x16x32_bf16 v[14:17], v[124:127], v[188:191], v[14:17]
	v_mfma_f32_16x16x32_bf16 v[10:13], v[140:143], v[188:191], v[10:13]
	v_mfma_f32_16x16x32_bf16 v[62:65], v[132:135], v[168:171], v[62:65]
	v_mfma_f32_16x16x32_bf16 v[58:61], v[144:147], v[168:171], v[58:61]
	v_mfma_f32_16x16x32_bf16 v[46:49], v[132:135], v[176:179], v[46:49]
	v_mfma_f32_16x16x32_bf16 v[42:45], v[144:147], v[176:179], v[42:45]
	v_mfma_f32_16x16x32_bf16 v[30:33], v[132:135], v[184:187], v[30:33]
	v_mfma_f32_16x16x32_bf16 v[26:29], v[144:147], v[184:187], v[26:29]
	v_mfma_f32_16x16x32_bf16 v[14:17], v[132:135], v[192:195], v[14:17]
	v_mfma_f32_16x16x32_bf16 v[10:13], v[144:147], v[192:195], v[10:13]
	s_setprio 0
	s_setprio 1
	v_mfma_f32_16x16x32_bf16 v[54:57], v[148:151], v[164:167], v[54:57]
	v_mfma_f32_16x16x32_bf16 v[50:53], v[156:159], v[164:167], v[50:53]
	v_mfma_f32_16x16x32_bf16 v[38:41], v[148:151], v[172:175], v[38:41]
	v_mfma_f32_16x16x32_bf16 v[34:37], v[156:159], v[172:175], v[34:37]
	v_mfma_f32_16x16x32_bf16 v[22:25], v[148:151], v[180:183], v[22:25]
	v_mfma_f32_16x16x32_bf16 v[18:21], v[156:159], v[180:183], v[18:21]
	v_mfma_f32_16x16x32_bf16 v[6:9], v[148:151], v[188:191], v[6:9]
	v_mfma_f32_16x16x32_bf16 v[2:5], v[156:159], v[188:191], v[2:5]
	v_mfma_f32_16x16x32_bf16 v[54:57], v[152:155], v[168:171], v[54:57]
	v_mfma_f32_16x16x32_bf16 v[50:53], v[160:163], v[168:171], v[50:53]
	v_mfma_f32_16x16x32_bf16 v[38:41], v[152:155], v[176:179], v[38:41]
	v_mfma_f32_16x16x32_bf16 v[34:37], v[160:163], v[176:179], v[34:37]
	v_mfma_f32_16x16x32_bf16 v[22:25], v[152:155], v[184:187], v[22:25]
	v_mfma_f32_16x16x32_bf16 v[18:21], v[160:163], v[184:187], v[18:21]
	v_mfma_f32_16x16x32_bf16 v[6:9], v[152:155], v[192:195], v[6:9]
	v_mfma_f32_16x16x32_bf16 v[2:5], v[160:163], v[192:195], v[2:5]
	s_setprio 0
	s_barrier
	s_add_u32 s6, s6, 0x100
	s_addc_u32 s7, s7, 0
	s_add_u32 s19, s19, 0x100
	s_addc_u32 s27, s27, 0
	s_cmp_lt_i32 s65, s25
	s_mov_b32 s28, s65
	s_cbranch_scc1 .LBB0_4031
	s_andn2_b64 vcc, exec, s[14:15]
	s_cbranch_vccnz .LBB0_4034

; #define PG8_STAGE(bufoff, gbase, voff) do { _Pragma("unroll") for (int _i = 0; _i < 2; ++_i) \
;         __builtin_amdgcn_global_load_lds((const unsigned*)((const char*)(gbase) + (voff)[_i]), (PG8_LAS unsigned*)(lds + (bufoff) + ldsw + _i * 8192), 16, 0, 0); } while (0)
; #define PG8_LDA(dst, b, h) do { _Pragma("unroll") for (int m = 0; m < 4; ++m) _Pragma("unroll") for (int k = 0; k < 2; ++k) dst[m][k] = *(const PG8_LAS bf16x8*)(lds + PG8_SA(b, h) + aoff + m * 2048 + k * 1024); } while (0)
; #define PG8_LDB(dst, b, h) do { _Pragma("unroll") for (int n = 0; n < 2; ++n) _Pragma("unroll") for (int k = 0; k < 2; ++k) dst[n][k] = *(const PG8_LAS bf16x8*)(lds + PG8_SB(b, h) + boff + n * 2048 + k * 1024); } while (0)
; #define PG8_MMA(ai, bj, At, Bt) do { __builtin_amdgcn_s_setprio(1); _Pragma("unroll") for (int m = 0; m < 4; ++m) _Pragma("unroll") for (int n = 0; n < 2; ++n) _Pragma("unroll") for (int k = 0; k < 2; ++k) \
;         acc[ai][bj][m][n] = __builtin_amdgcn_mfma_f32_16x16x32_bf16(Bt[n][k], At[m][k], acc[ai][bj][m][n], 0, 0, 0); __builtin_amdgcn_s_setprio(0); } while (0)
; #define PG8_WAIT_V(n) asm volatile("s_waitcnt vmcnt(" #n ")" ::: "memory")
; #define PG8_WAIT_L(n) do { asm volatile("s_waitcnt lgkmcnt(" #n ")" ::: "memory"); __builtin_amdgcn_s_waitcnt(0xC07F); } while (0)
; #define PG8_BAR __builtin_amdgcn_s_barrier()
; template <class Epi, class Sched, bool SEG3 = false>
; __device__ __forceinline__ void gemm_phase(PG8_LAS unsigned char* lds, const Gemm g, const Sched& S, const Epi& E) {
;     ...
;             const bool last = (t == ntc - 2);
;             const char* a1 = cA + (size_t)(t + 1) * kstep;
;             const char* a2 = last ? nA : cA + (size_t)(t + 2) * kstep; const char* b2 = last ? nB : cB + (size_t)(t + 2) * kstep;
;             const char* a3 = a2 + kstep; const char* b3 = b2 + kstep;
;             PG8_LDB(B0, 0, 0); PG8_LDB(B1, 0, 1); PG8_SCHED; PG8_LDA(At, 0, 0); PG8_STAGE(PG8_SA(1, 1), a1 + hsA, voffA);
;             PG8_WAIT_V(8); PG8_WAIT_L(0); PG8_BAR; if (cur.half != 1) { PG8_MMA(0, 0, At, B0); PG8_MMA(0, 1, At, B1); } PG8_BAR; PG8_SCHED;
;             PG8_LDA(At, 0, 1); PG8_STAGE(PG8_SB(0, 0), b2, voffB); PG8_STAGE(PG8_SB(0, 1), b2 + hsB, voffB); PG8_STAGE(PG8_SA(0, 0), a2, voffA);
;             PG8_WAIT_V(8); PG8_WAIT_L(0); PG8_BAR; if (cur.half != 0) { PG8_MMA(1, 0, At, B0); PG8_MMA(1, 1, At, B1); } PG8_BAR; PG8_SCHED;
.LBB0_4157:
	ds_read_b128 v[34:37], v207
	ds_read_b128 v[38:41], v207 offset:1024
	ds_read_b128 v[42:45], v207 offset:2048
	ds_read_b128 v[46:49], v207 offset:3072
	ds_read_b128 v[114:117], v208
	ds_read_b128 v[126:129], v208 offset:1024
	ds_read_b128 v[138:141], v208 offset:2048
	ds_read_b128 v[150:153], v208 offset:3072
	s_add_i32 s70, s40, 2
	s_add_u32 s41, s38, 0xfffc0080
	s_addc_u32 s42, s39, -1
	s_cmp_eq_u32 s64, s40
	s_cselect_b32 s40, s37, s68
	s_cselect_b32 s43, s25, s42
	s_cselect_b32 s42, s27, s41
	s_cselect_b32 s41, s35, s69
	v_lshl_add_u64 v[218:219], s[38:39], 0, v[178:179]
	s_add_i32 m0, s52, 0xc000
	ds_read_b128 v[162:165], v209
	ds_read_b128 v[166:169], v209 offset:1024
	ds_read_b128 v[186:189], v209 offset:2048
	ds_read_b128 v[190:193], v209 offset:3072
	ds_read_b128 v[194:197], v209 offset:4096
	ds_read_b128 v[198:201], v209 offset:5120
	ds_read_b128 v[202:205], v209 offset:6144
	ds_read_b128 v[214:217], v209 offset:7168
	global_load_lds_dwordx4 v[218:219], off
	s_add_i32 m0, s52, 0xe000
	v_lshl_add_u64 v[218:219], s[38:39], 0, v[180:181]
	global_load_lds_dwordx4 v[218:219], off
	s_waitcnt vmcnt(8) lgkmcnt(0)
	s_barrier
	s_setprio 1
	v_mfma_f32_16x16x32_bf16 v[158:161], v[34:37], v[162:165], v[158:161]
	v_mfma_f32_16x16x32_bf16 v[154:157], v[42:45], v[162:165], v[154:157]
	v_mfma_f32_16x16x32_bf16 v[134:137], v[34:37], v[186:189], v[134:137]
	v_mfma_f32_16x16x32_bf16 v[130:133], v[42:45], v[186:189], v[130:133]
	v_mfma_f32_16x16x32_bf16 v[110:113], v[34:37], v[194:197], v[110:113]
	v_mfma_f32_16x16x32_bf16 v[106:109], v[42:45], v[194:197], v[106:109]
	v_mfma_f32_16x16x32_bf16 v[94:97], v[34:37], v[202:205], v[94:97]
	v_mfma_f32_16x16x32_bf16 v[90:93], v[42:45], v[202:205], v[90:93]
	v_mfma_f32_16x16x32_bf16 v[158:161], v[38:41], v[166:169], v[158:161]
	v_mfma_f32_16x16x32_bf16 v[154:157], v[46:49], v[166:169], v[154:157]
	v_mfma_f32_16x16x32_bf16 v[134:137], v[38:41], v[190:193], v[134:137]
	v_mfma_f32_16x16x32_bf16 v[130:133], v[46:49], v[190:193], v[130:133]
	v_mfma_f32_16x16x32_bf16 v[110:113], v[38:41], v[198:201], v[110:113]
	v_mfma_f32_16x16x32_bf16 v[106:109], v[46:49], v[198:201], v[106:109]
	v_mfma_f32_16x16x32_bf16 v[94:97], v[38:41], v[214:217], v[94:97]
	v_mfma_f32_16x16x32_bf16 v[90:93], v[46:49], v[214:217], v[90:93]
	s_setprio 0
	s_setprio 1
	v_mfma_f32_16x16x32_bf16 v[146:149], v[114:117], v[162:165], v[146:149]
	v_mfma_f32_16x16x32_bf16 v[142:145], v[138:141], v[162:165], v[142:145]
	v_mfma_f32_16x16x32_bf16 v[122:125], v[114:117], v[186:189], v[122:125]
	v_mfma_f32_16x16x32_bf16 v[118:121], v[138:141], v[186:189], v[118:121]
	v_mfma_f32_16x16x32_bf16 v[102:105], v[114:117], v[194:197], v[102:105]
	v_mfma_f32_16x16x32_bf16 v[98:101], v[138:141], v[194:197], v[98:101]
	v_mfma_f32_16x16x32_bf16 v[86:89], v[114:117], v[202:205], v[86:89]
	v_mfma_f32_16x16x32_bf16 v[82:85], v[138:141], v[202:205], v[82:85]
	v_mfma_f32_16x16x32_bf16 v[146:149], v[126:129], v[166:169], v[146:149]
	v_mfma_f32_16x16x32_bf16 v[142:145], v[150:153], v[166:169], v[142:145]
	v_mfma_f32_16x16x32_bf16 v[122:125], v[126:129], v[190:193], v[122:125]
	v_mfma_f32_16x16x32_bf16 v[118:121], v[150:153], v[190:193], v[118:121]
	v_mfma_f32_16x16x32_bf16 v[102:105], v[126:129], v[198:201], v[102:105]
	v_mfma_f32_16x16x32_bf16 v[98:101], v[150:153], v[198:201], v[98:101]
	v_mfma_f32_16x16x32_bf16 v[86:89], v[126:129], v[214:217], v[86:89]
	v_mfma_f32_16x16x32_bf16 v[82:85], v[150:153], v[214:217], v[82:85]
	s_setprio 0
	s_barrier
	s_mov_b32 m0, s48
	v_lshl_add_u64 v[218:219], s[40:41], 0, v[172:173]
	s_add_u32 s72, s40, 0x40000
	ds_read_b128 v[162:165], v209 offset:16384
	ds_read_b128 v[166:169], v209 offset:17408
	ds_read_b128 v[186:189], v209 offset:18432
	ds_read_b128 v[190:193], v209 offset:19456
	ds_read_b128 v[194:197], v209 offset:20480
	ds_read_b128 v[198:201], v209 offset:21504
	ds_read_b128 v[202:205], v209 offset:22528
	ds_read_b128 v[214:217], v209 offset:23552
	global_load_lds_dwordx4 v[218:219], off
	v_lshl_add_u64 v[220:221], s[40:41], 0, v[176:177]
	s_mov_b32 m0, s49
	s_addc_u32 s73, s41, 0
	global_load_lds_dwordx4 v[220:221], off
	v_lshl_add_u64 v[222:223], s[72:73], 0, v[172:173]
	s_mov_b32 m0, s50
	v_lshl_add_u64 v[224:225], s[42:43], 0, v[174:175]
	global_load_lds_dwordx4 v[222:223], off
	s_mov_b32 m0, s51
	v_lshl_add_u64 v[222:223], s[72:73], 0, v[176:177]
	global_load_lds_dwordx4 v[222:223], off
	s_mov_b32 m0, s52
	v_lshl_add_u64 v[222:223], s[42:43], 0, v[170:171]
	global_load_lds_dwordx4 v[222:223], off
	s_mov_b32 m0, s53
	s_nop 0
	global_load_lds_dwordx4 v[224:225], off
	s_waitcnt vmcnt(8) lgkmcnt(0)
	s_barrier
; #define PG8_STAGE(bufoff, gbase, voff) do { _Pragma("unroll") for (int _i = 0; _i < 2; ++_i) \
;         __builtin_amdgcn_global_load_lds((const unsigned*)((const char*)(gbase) + (voff)[_i]), (PG8_LAS unsigned*)(lds + (bufoff) + ldsw + _i * 8192), 16, 0, 0); } while (0)
; #define PG8_LDA(dst, b, h) do { _Pragma("unroll") for (int m = 0; m < 4; ++m) _Pragma("unroll") for (int k = 0; k < 2; ++k) dst[m][k] = *(const PG8_LAS bf16x8*)(lds + PG8_SA(b, h) + aoff + m * 2048 + k * 1024); } while (0)
; #define PG8_LDB(dst, b, h) do { _Pragma("unroll") for (int n = 0; n < 2; ++n) _Pragma("unroll") for (int k = 0; k < 2; ++k) dst[n][k] = *(const PG8_LAS bf16x8*)(lds + PG8_SB(b, h) + boff + n * 2048 + k * 1024); } while (0)
; #define PG8_MMA(ai, bj, At, Bt) do { __builtin_amdgcn_s_setprio(1); _Pragma("unroll") for (int m = 0; m < 4; ++m) _Pragma("unroll") for (int n = 0; n < 2; ++n) _Pragma("unroll") for (int k = 0; k < 2; ++k) \
;         acc[ai][bj][m][n] = __builtin_amdgcn_mfma_f32_16x16x32_bf16(Bt[n][k], At[m][k], acc[ai][bj][m][n], 0, 0, 0); __builtin_amdgcn_s_setprio(0); } while (0)
; #define PG8_WAIT_V(n) asm volatile("s_waitcnt vmcnt(" #n ")" ::: "memory")
; #define PG8_WAIT_L(n) do { asm volatile("s_waitcnt lgkmcnt(" #n ")" ::: "memory"); __builtin_amdgcn_s_waitcnt(0xC07F); } while (0)
; #define PG8_BAR __builtin_amdgcn_s_barrier()
; #define PG8_SCHED __builtin_amdgcn_sched_barrier(0)
; template <class Epi, class Sched, bool SEG3 = false>
; __device__ __forceinline__ void gemm_phase(PG8_LAS unsigned char* lds, const Gemm g, const Sched& S, const Epi& E) {
;     ...
;             PG8_WAIT_V(8); PG8_WAIT_L(0); PG8_BAR; if (cur.half != 0) { PG8_MMA(1, 0, At, B0); PG8_MMA(1, 1, At, B1); } PG8_BAR; PG8_SCHED;
;             PG8_LDB(B0, 1, 0); PG8_LDB(B1, 1, 1); PG8_SCHED; PG8_LDA(At, 1, 0); PG8_STAGE(PG8_SA(0, 1), a2 + hsA, voffA);
;             PG8_WAIT_V(8); PG8_WAIT_L(0); PG8_BAR; if (cur.half != 1) { PG8_MMA(0, 0, At, B0); PG8_MMA(0, 1, At, B1); } PG8_BAR; PG8_SCHED;
	s_setprio 1
	v_mfma_f32_16x16x32_bf16 v[78:81], v[34:37], v[162:165], v[78:81]
	v_mfma_f32_16x16x32_bf16 v[74:77], v[42:45], v[162:165], v[74:77]
	v_mfma_f32_16x16x32_bf16 v[62:65], v[34:37], v[186:189], v[62:65]
	v_mfma_f32_16x16x32_bf16 v[58:61], v[42:45], v[186:189], v[58:61]
	v_mfma_f32_16x16x32_bf16 v[30:33], v[34:37], v[194:197], v[30:33]
	v_mfma_f32_16x16x32_bf16 v[26:29], v[42:45], v[194:197], v[26:29]
	v_mfma_f32_16x16x32_bf16 v[14:17], v[34:37], v[202:205], v[14:17]
	v_mfma_f32_16x16x32_bf16 v[10:13], v[42:45], v[202:205], v[10:13]
	v_mfma_f32_16x16x32_bf16 v[78:81], v[38:41], v[166:169], v[78:81]
	v_mfma_f32_16x16x32_bf16 v[74:77], v[46:49], v[166:169], v[74:77]
	v_mfma_f32_16x16x32_bf16 v[62:65], v[38:41], v[190:193], v[62:65]
	v_mfma_f32_16x16x32_bf16 v[58:61], v[46:49], v[190:193], v[58:61]
	v_mfma_f32_16x16x32_bf16 v[30:33], v[38:41], v[198:201], v[30:33]
	v_mfma_f32_16x16x32_bf16 v[26:29], v[46:49], v[198:201], v[26:29]
	v_mfma_f32_16x16x32_bf16 v[14:17], v[38:41], v[214:217], v[14:17]
	v_mfma_f32_16x16x32_bf16 v[10:13], v[46:49], v[214:217], v[10:13]
	s_setprio 0
	s_setprio 1
	v_mfma_f32_16x16x32_bf16 v[22:25], v[114:117], v[194:197], v[22:25]
	v_mfma_f32_16x16x32_bf16 v[18:21], v[138:141], v[194:197], v[18:21]
	v_mfma_f32_16x16x32_bf16 v[6:9], v[114:117], v[202:205], v[6:9]
	v_mfma_f32_16x16x32_bf16 v[2:5], v[138:141], v[202:205], v[2:5]
	v_mfma_f32_16x16x32_bf16 v[34:37], v[114:117], v[162:165], v[70:73]
	v_mfma_f32_16x16x32_bf16 v[38:41], v[138:141], v[162:165], v[66:69]
	v_mfma_f32_16x16x32_bf16 v[42:45], v[114:117], v[186:189], v[54:57]
	v_mfma_f32_16x16x32_bf16 v[46:49], v[138:141], v[186:189], v[50:53]
	v_mfma_f32_16x16x32_bf16 v[22:25], v[126:129], v[198:201], v[22:25]
	v_mfma_f32_16x16x32_bf16 v[18:21], v[150:153], v[198:201], v[18:21]
	v_mfma_f32_16x16x32_bf16 v[6:9], v[126:129], v[214:217], v[6:9]
	v_mfma_f32_16x16x32_bf16 v[2:5], v[150:153], v[214:217], v[2:5]
	v_mfma_f32_16x16x32_bf16 v[34:37], v[126:129], v[166:169], v[34:37]
	v_mfma_f32_16x16x32_bf16 v[38:41], v[150:153], v[166:169], v[38:41]
	v_mfma_f32_16x16x32_bf16 v[42:45], v[126:129], v[190:193], v[42:45]
	v_mfma_f32_16x16x32_bf16 v[46:49], v[150:153], v[190:193], v[46:49]
	s_setprio 0
	s_barrier
	ds_read_b128 v[50:53], v210
	ds_read_b128 v[54:57], v210 offset:1024
	ds_read_b128 v[66:69], v210 offset:2048
	ds_read_b128 v[70:73], v210 offset:3072
	ds_read_b128 v[114:117], v211
	ds_read_b128 v[126:129], v211 offset:1024
	ds_read_b128 v[138:141], v211 offset:2048
	ds_read_b128 v[150:153], v211 offset:3072
	s_add_u32 s42, s42, 0x40000
	s_addc_u32 s43, s43, 0
	s_mov_b32 m0, s54
	v_lshl_add_u64 v[226:227], s[42:43], 0, v[170:171]
	ds_read_b128 v[162:165], v209 offset:32768
	ds_read_b128 v[166:169], v209 offset:33792
	ds_read_b128 v[186:189], v209 offset:34816
	ds_read_b128 v[190:193], v209 offset:35840
	ds_read_b128 v[194:197], v209 offset:36864
	ds_read_b128 v[198:201], v209 offset:37888
	ds_read_b128 v[202:205], v209 offset:38912
	ds_read_b128 v[214:217], v209 offset:39936
	global_load_lds_dwordx4 v[226:227], off
	s_mov_b32 m0, s55
	v_lshl_add_u64 v[226:227], s[42:43], 0, v[174:175]
	global_load_lds_dwordx4 v[226:227], off
	s_waitcnt vmcnt(8) lgkmcnt(0)
	s_barrier
	s_setprio 1
	v_mfma_f32_16x16x32_bf16 v[158:161], v[50:53], v[162:165], v[158:161]
	v_mfma_f32_16x16x32_bf16 v[154:157], v[66:69], v[162:165], v[154:157]
	v_mfma_f32_16x16x32_bf16 v[134:137], v[50:53], v[186:189], v[134:137]
	v_mfma_f32_16x16x32_bf16 v[130:133], v[66:69], v[186:189], v[130:133]
	v_mfma_f32_16x16x32_bf16 v[110:113], v[50:53], v[194:197], v[110:113]
	v_mfma_f32_16x16x32_bf16 v[106:109], v[66:69], v[194:197], v[106:109]
	v_mfma_f32_16x16x32_bf16 v[94:97], v[50:53], v[202:205], v[94:97]
	v_mfma_f32_16x16x32_bf16 v[90:93], v[66:69], v[202:205], v[90:93]
	v_mfma_f32_16x16x32_bf16 v[158:161], v[54:57], v[166:169], v[158:161]
	v_mfma_f32_16x16x32_bf16 v[154:157], v[70:73], v[166:169], v[154:157]
	v_mfma_f32_16x16x32_bf16 v[134:137], v[54:57], v[190:193], v[134:137]
	v_mfma_f32_16x16x32_bf16 v[130:133], v[70:73], v[190:193], v[130:133]
	v_mfma_f32_16x16x32_bf16 v[110:113], v[54:57], v[198:201], v[110:113]
	v_mfma_f32_16x16x32_bf16 v[106:109], v[70:73], v[198:201], v[106:109]
	v_mfma_f32_16x16x32_bf16 v[94:97], v[54:57], v[214:217], v[94:97]
	v_mfma_f32_16x16x32_bf16 v[90:93], v[70:73], v[214:217], v[90:93]
	s_setprio 0
	s_setprio 1
	v_mfma_f32_16x16x32_bf16 v[146:149], v[114:117], v[162:165], v[146:149]
	v_mfma_f32_16x16x32_bf16 v[142:145], v[138:141], v[162:165], v[142:145]
	v_mfma_f32_16x16x32_bf16 v[122:125], v[114:117], v[186:189], v[122:125]
	v_mfma_f32_16x16x32_bf16 v[118:121], v[138:141], v[186:189], v[118:121]
	v_mfma_f32_16x16x32_bf16 v[102:105], v[114:117], v[194:197], v[102:105]
	v_mfma_f32_16x16x32_bf16 v[98:101], v[138:141], v[194:197], v[98:101]
	v_mfma_f32_16x16x32_bf16 v[86:89], v[114:117], v[202:205], v[86:89]
	v_mfma_f32_16x16x32_bf16 v[82:85], v[138:141], v[202:205], v[82:85]
	v_mfma_f32_16x16x32_bf16 v[146:149], v[126:129], v[166:169], v[146:149]
	v_mfma_f32_16x16x32_bf16 v[142:145], v[150:153], v[166:169], v[142:145]
	v_mfma_f32_16x16x32_bf16 v[122:125], v[126:129], v[190:193], v[122:125]
	v_mfma_f32_16x16x32_bf16 v[118:121], v[150:153], v[190:193], v[118:121]
	v_mfma_f32_16x16x32_bf16 v[102:105], v[126:129], v[198:201], v[102:105]
	v_mfma_f32_16x16x32_bf16 v[98:101], v[150:153], v[198:201], v[98:101]
	v_mfma_f32_16x16x32_bf16 v[86:89], v[126:129], v[214:217], v[86:89]
	v_mfma_f32_16x16x32_bf16 v[82:85], v[150:153], v[214:217], v[82:85]
	s_setprio 0
	s_barrier
; #define PG8_STAGE(bufoff, gbase, voff) do { _Pragma("unroll") for (int _i = 0; _i < 2; ++_i) \
;         __builtin_amdgcn_global_load_lds((const unsigned*)((const char*)(gbase) + (voff)[_i]), (PG8_LAS unsigned*)(lds + (bufoff) + ldsw + _i * 8192), 16, 0, 0); } while (0)
; #define PG8_LDA(dst, b, h) do { _Pragma("unroll") for (int m = 0; m < 4; ++m) _Pragma("unroll") for (int k = 0; k < 2; ++k) dst[m][k] = *(const PG8_LAS bf16x8*)(lds + PG8_SA(b, h) + aoff + m * 2048 + k * 1024); } while (0)
; #define PG8_MMA(ai, bj, At, Bt) do { __builtin_amdgcn_s_setprio(1); _Pragma("unroll") for (int m = 0; m < 4; ++m) _Pragma("unroll") for (int n = 0; n < 2; ++n) _Pragma("unroll") for (int k = 0; k < 2; ++k) \
;         acc[ai][bj][m][n] = __builtin_amdgcn_mfma_f32_16x16x32_bf16(Bt[n][k], At[m][k], acc[ai][bj][m][n], 0, 0, 0); __builtin_amdgcn_s_setprio(0); } while (0)
; #define PG8_WAIT_V(n) asm volatile("s_waitcnt vmcnt(" #n ")" ::: "memory")
; #define PG8_WAIT_L(n) do { asm volatile("s_waitcnt lgkmcnt(" #n ")" ::: "memory"); __builtin_amdgcn_s_waitcnt(0xC07F); } while (0)
; #define PG8_BAR __builtin_amdgcn_s_barrier()
; #define PG8_SCHED __builtin_amdgcn_sched_barrier(0)
; template <class Epi, class Sched, bool SEG3 = false>
; __device__ __forceinline__ void gemm_phase(PG8_LAS unsigned char* lds, const Gemm g, const Sched& S, const Epi& E) {
;     ...
;             PG8_LDA(At, 1, 1); PG8_STAGE(PG8_SB(1, 0), b3, voffB); PG8_STAGE(PG8_SB(1, 1), b3 + hsB, voffB); PG8_STAGE(PG8_SA(1, 0), a3, voffA);
;             PG8_WAIT_V(8); PG8_WAIT_L(0); PG8_BAR; if (cur.half != 0) { PG8_MMA(1, 0, At, B0); PG8_MMA(1, 1, At, B1); } PG8_BAR; PG8_SCHED;
;         }
	s_mov_b32 m0, s58
	v_lshl_add_u64 v[218:219], v[218:219], 0, s[18:19]
	s_add_u32 s40, s40, 0x40080
	ds_read_b128 v[162:165], v209 offset:49152
	ds_read_b128 v[166:169], v209 offset:50176
	ds_read_b128 v[186:189], v209 offset:51200
	ds_read_b128 v[190:193], v209 offset:52224
	ds_read_b128 v[194:197], v209 offset:53248
	ds_read_b128 v[198:201], v209 offset:54272
	ds_read_b128 v[202:205], v209 offset:55296
	ds_read_b128 v[214:217], v209 offset:56320
	global_load_lds_dwordx4 v[218:219], off
	v_lshl_add_u64 v[218:219], v[220:221], 0, s[18:19]
	s_mov_b32 m0, s59
	s_addc_u32 s41, s41, 0
	global_load_lds_dwordx4 v[218:219], off
	s_mov_b32 m0, s62
	v_lshl_add_u64 v[218:219], s[40:41], 0, v[172:173]
	global_load_lds_dwordx4 v[218:219], off
	s_mov_b32 m0, s63
	v_lshl_add_u64 v[218:219], s[40:41], 0, v[176:177]
	global_load_lds_dwordx4 v[218:219], off
	s_mov_b32 m0, s60
	v_lshl_add_u64 v[218:219], v[222:223], 0, s[18:19]
	global_load_lds_dwordx4 v[218:219], off
	s_mov_b32 m0, s61
	v_lshl_add_u64 v[218:219], v[224:225], 0, s[18:19]
	global_load_lds_dwordx4 v[218:219], off
	s_waitcnt vmcnt(8) lgkmcnt(0)
	s_barrier
	s_setprio 1
	v_mfma_f32_16x16x32_bf16 v[78:81], v[50:53], v[162:165], v[78:81]
	v_mfma_f32_16x16x32_bf16 v[74:77], v[66:69], v[162:165], v[74:77]
	v_mfma_f32_16x16x32_bf16 v[62:65], v[50:53], v[186:189], v[62:65]
	v_mfma_f32_16x16x32_bf16 v[58:61], v[66:69], v[186:189], v[58:61]
	v_mfma_f32_16x16x32_bf16 v[30:33], v[50:53], v[194:197], v[30:33]
	v_mfma_f32_16x16x32_bf16 v[26:29], v[66:69], v[194:197], v[26:29]
	v_mfma_f32_16x16x32_bf16 v[14:17], v[50:53], v[202:205], v[14:17]
	v_mfma_f32_16x16x32_bf16 v[10:13], v[66:69], v[202:205], v[10:13]
	v_mfma_f32_16x16x32_bf16 v[78:81], v[54:57], v[166:169], v[78:81]
	v_mfma_f32_16x16x32_bf16 v[74:77], v[70:73], v[166:169], v[74:77]
	v_mfma_f32_16x16x32_bf16 v[62:65], v[54:57], v[190:193], v[62:65]
	v_mfma_f32_16x16x32_bf16 v[58:61], v[70:73], v[190:193], v[58:61]
	v_mfma_f32_16x16x32_bf16 v[30:33], v[54:57], v[198:201], v[30:33]
	v_mfma_f32_16x16x32_bf16 v[26:29], v[70:73], v[198:201], v[26:29]
	v_mfma_f32_16x16x32_bf16 v[14:17], v[54:57], v[214:217], v[14:17]
	v_mfma_f32_16x16x32_bf16 v[10:13], v[70:73], v[214:217], v[10:13]
	s_setprio 0
	s_setprio 1
	v_mfma_f32_16x16x32_bf16 v[34:37], v[114:117], v[162:165], v[34:37]
	v_mfma_f32_16x16x32_bf16 v[70:73], v[126:129], v[166:169], v[34:37]
	v_mfma_f32_16x16x32_bf16 v[34:37], v[138:141], v[162:165], v[38:41]
	v_mfma_f32_16x16x32_bf16 v[66:69], v[150:153], v[166:169], v[34:37]
	v_mfma_f32_16x16x32_bf16 v[34:37], v[114:117], v[186:189], v[42:45]
	v_mfma_f32_16x16x32_bf16 v[54:57], v[126:129], v[190:193], v[34:37]
	v_mfma_f32_16x16x32_bf16 v[34:37], v[138:141], v[186:189], v[46:49]
	v_mfma_f32_16x16x32_bf16 v[22:25], v[114:117], v[194:197], v[22:25]
	v_mfma_f32_16x16x32_bf16 v[18:21], v[138:141], v[194:197], v[18:21]
	v_mfma_f32_16x16x32_bf16 v[6:9], v[114:117], v[202:205], v[6:9]
	v_mfma_f32_16x16x32_bf16 v[2:5], v[138:141], v[202:205], v[2:5]
	v_mfma_f32_16x16x32_bf16 v[50:53], v[150:153], v[190:193], v[34:37]
	v_mfma_f32_16x16x32_bf16 v[22:25], v[126:129], v[198:201], v[22:25]
	v_mfma_f32_16x16x32_bf16 v[18:21], v[150:153], v[198:201], v[18:21]
	v_mfma_f32_16x16x32_bf16 v[6:9], v[126:129], v[214:217], v[6:9]
	v_mfma_f32_16x16x32_bf16 v[2:5], v[150:153], v[214:217], v[2:5]
	s_setprio 0
	s_barrier
	s_add_u32 s38, s38, 0x100
	s_addc_u32 s39, s39, 0
	s_add_u32 s68, s68, 0x100
	s_addc_u32 s69, s69, 0
	s_cmp_lt_i32 s70, s57
	s_mov_b32 s40, s70
	s_cbranch_scc1 .LBB0_4157
	s_andn2_b64 vcc, exec, s[22:23]
	s_cbranch_vccnz .LBB0_4160
